# K-loops of in-proj/up-proj/out-proj hand-pipelined; out-proj epilogue rewritten (loads ahead of stores, 16B xb stores); in-proj: next tile K-tile-1 DMA issued before epilogue stores with counted vmcnt
# speedup vs baseline: 1.0326x; 1.0326x over previous
; DI int my_tid() { int t = threadIdx.x; asm volatile("" : "+v"(t)); return t; }
;     ...
;     if (my_tid() < 256) {
;       const float* pp = p.part() + ((long)mt * 256 + my_tid()) * 16;
;       const f32x4 v0 = *(const f32x4*)pp, v1 = *(const f32x4*)(pp + 4);
;       const float s = ((v0[0] + v0[1]) + (v0[2] + v0[3])) + ((v1[0] + v1[1]) + (v1[2] + v1[3]));
;       rs_s[my_tid()] = rsqrtf(s * (1.f / 1024.f) + NORM_EPS);
;     } else if (my_tid() < 448) {
;       const int k = my_tid() - 256;
;       rs_s[256 + k] = k < 64 ? p.qng()[layer * 64 + k] : p.kng()[(layer * 3 + 1) * 64 + (k - 64)];
;     }
.LBB0_253:
	s_or_b64 exec, exec, s[8:9]
	s_mov_b64 s[8:9], -1
	s_and_saveexec_b64 s[74:75], vcc
	s_cbranch_execz .LBB0_250
	v_readfirstlane_b32 s36, v162
	s_cmp_eq_u32 s27, 0
	s_cbranch_scc1 .Lmy_rs_do
	s_cmp_eq_u32 s36, s86
	s_cbranch_scc0 .Lmy_rs_do
	v_ashrrev_i32_e32 v163, 31, v162
	s_branch .Lmy_rs_skip
.Lmy_rs_do:
	s_mov_b32 s86, s36
	v_mov_b32_e32 v0, v210
	s_movk_i32 s8, 0xff
	s_nop 0
	v_cmp_lt_i32_e32 vcc, s8, v0
	s_mov_b64 s[8:9], 0
	s_and_saveexec_b64 s[10:11], vcc
	s_xor_b64 s[10:11], exec, s[10:11]
	s_cbranch_execz .LBB0_268
	v_mov_b32_e32 v0, v210
	s_movk_i32 s8, 0x1c0
	s_nop 0
	v_cmp_gt_i32_e32 vcc, s8, v0
	s_mov_b64 s[8:9], 0
	s_and_saveexec_b64 s[12:13], vcc
	s_xor_b64 s[12:13], exec, s[12:13]
	s_cbranch_execz .LBB0_257
	v_mov_b32_e32 v3, v210
	s_movk_i32 s28, 0x140
	v_mov_b32_e32 v0, s0
	v_mov_b32_e32 v4, s1
	v_cmp_gt_i32_e32 vcc, s28, v3
	s_movk_i32 s28, 0xff00
	s_mov_b64 s[8:9], exec
	v_cndmask_b32_e32 v6, v0, v4, vcc
	v_mov_b32_e32 v0, 0x1f670400
	v_mov_b32_e32 v4, 0x1f670000
	v_cndmask_b32_e32 v0, v0, v4, vcc
	v_add3_u32 v6, v3, v6, s28
	v_lshl_add_u64 v[4:5], s[14:15], 0, v[0:1]
	v_ashrrev_i32_e32 v7, 31, v6
	v_lshl_add_u64 v[4:5], v[6:7], 2, v[4:5]
	global_load_dword v0, v[4:5], off

; DI bool tile_order(const Slot sl, int it, int nN, int& mt, int& nt) {
;   const int xcd = sl.xcd, slot = sl.slot, SL = gridDim.x >> 3;
;   const int q = slot + it * SL, per = 8 * nN;
;   if (q >= 2 * per) return false;
;   const int mg = q / per, e = q - mg * per;
;   nt = e >> 3; mt = xcd * 16 + mg * 8 + (e & 7);
;   return true;
; }
;     ...
;     int mt2, nt2;
;     const bool more = !fake && tile_order(sl, it + 1, NT_IN, mt2, nt2);
;     const bf16_t* Xn = more ? p.xb() + (long)mt2 * 256 * LDX : Xg; const bf16_t* Wn = more ? Wt + (long)nt2 * 256 * LDX : Wg;
.Lmy_rs_skip:
	v_add_u32_e32 v0, v2, v211
	s_movk_i32 s8, 0x180
	v_cmp_gt_i32_e32 vcc, s8, v0
	s_and_saveexec_b64 s[8:9], vcc
	s_cbranch_execz .LBB0_262
	s_mov_b32 s10, 0x2aaaaaab
	v_mul_hi_i32 v2, v0, s10
	v_lshrrev_b32_e32 v3, 31, v2
	v_ashrrev_i32_e32 v2, 5, v2
	v_add_u32_e32 v4, v2, v3
	s_movk_i32 s10, 0xff40
	v_mad_u64_u32 v[2:3], s[10:11], v4, s10, v[0:1]
	v_ashrrev_i32_e32 v203, 3, v2
	v_lshl_add_u32 v2, v4, 3, v213
	v_and_or_b32 v204, v0, 7, v2

; DI int my_tid() { int t = threadIdx.x; asm volatile("" : "+v"(t)); return t; }
;     ...
;   const int tid = my_tid(), lane = tid & 63, w = __builtin_amdgcn_readfirstlane(tid >> 6), wa = w >> 2, wb = w & 3, qi = lane & 15, quad = lane >> 4;
;   const bf16_t* base = w >= 4 ? Bg : Ag; const int ld = (int)(w >= 4 ? ldb : lda);
;   const bf16_t* nbase = nAg ? (w >= 4 ? nBg : nAg) : base;
;   unsigned off[8];
; #pragma unroll
;   for (int u = 0; u < 8; ++u) {
;     const int blk = (w & 3) * 8 + u, rg = blk >> 1, kh = blk & 1;
;     int R = rg * 16 + (lane >> 2);
;     if (perm) { const int rho = R & 31; R = (R & ~31) + ((rho >> 2) & 3) * 8 + (rho >> 4) * 4 + (rho & 3); }
;     off[u] = (unsigned)(R * ld + kh * 32 + (lane & 3) * 8);
;   }
;   const int ra = (wa * 8) * 2 * 1024 + (qi * 4 + quad) * 16, rb = (wb * 4) * 2 * 1024 + (qi * 4 + quad) * 16;
;   unsigned char* buf0 = lds; unsigned char* buf1 = lds + STAGE_B;
;   const int KT = K >> 6;
;   if (!pre) {
;     g_dma(base, off, 0, buf0, w);
;     asm volatile("s_waitcnt vmcnt(0)" ::: "memory");
;     __syncthreads();
;   }
;     ...
;     const bf16_t* Xg = p.xb() + (long)mtl * 256 * LDX; const bf16_t* Wg = Wt + (long)ntl * 256 * LDX;
;     f32x4 acc[8][4]; zero_acc(acc);
;     const int kstep = (fake == 1 || fake == 2) ? 0 : 64;
;     int mt2, nt2;
;     const bool more = !fake && tile_order(sl, it + 1, NT_IN, mt2, nt2);
;     const bf16_t* Xn = more ? p.xb() + (long)mt2 * 256 * LDX : Xg; const bf16_t* Wn = more ? Wt + (long)nt2 * 256 * LDX : Wg;
;     const bool vn = more ? nt2 >= 21 : nt >= 21;
;     gemm_core(nt >= 21 ? Xg : Wg, LDX, nt >= 21 ? Wg : Xg, LDX, D_MODEL, gl, acc, kstep, !fake && it > 0, vn ? Xn : Wn, vn ? Wn : Xn, true);
.LBB0_273:
	v_cmp_lt_i32_e32 vcc, 20, v13
	s_nop 1
	v_cndmask_b32_e32 v7, v5, v3, vcc
	v_cndmask_b32_e32 v6, v4, v2, vcc
	v_cndmask_b32_e32 v0, v2, v4, vcc
	v_cndmask_b32_e32 v2, v3, v5, vcc
	v_and_b32_e32 v3, 48, v12
	v_cndmask_b32_e64 v135, v7, v2, s[12:13]
	v_cndmask_b32_e64 v134, v6, v0, s[12:13]
	s_lshl_b32 s12, s30, 6
	v_lshlrev_b32_e32 v0, 6, v12
	s_movk_i32 s13, 0x3c0
	s_and_b32 s12, s12, 0xffffc000
	v_and_or_b32 v0, v0, s13, v3
	v_mov_b32_e32 v2, 0
	v_cmp_eq_u64_e64 s[10:11], 0, v[6:7]
	v_or_b32_e32 v144, s12, v0
	v_lshl_or_b32 v145, s29, 13, v0
	s_mov_b32 s29, 0
	s_mov_b32 s12, 0
	v_mov_b32_e32 v3, v2
	v_mov_b32_e32 v4, v2
	v_mov_b32_e32 v5, v2
	v_mov_b32_e32 v6, v2
	v_mov_b32_e32 v7, v2
	v_mov_b32_e32 v8, v2
	v_mov_b32_e32 v9, v2
	v_mov_b32_e32 v18, v2
	v_mov_b32_e32 v19, v2
	v_mov_b32_e32 v20, v2
	v_mov_b32_e32 v21, v2
	v_mov_b32_e32 v26, v2
	v_mov_b32_e32 v27, v2
	v_mov_b32_e32 v28, v2
	v_mov_b32_e32 v29, v2
	v_mov_b32_e32 v10, v2
	v_mov_b32_e32 v11, v2
	v_mov_b32_e32 v12, v2
	v_mov_b32_e32 v13, v2
	v_mov_b32_e32 v14, v2
	v_mov_b32_e32 v15, v2
	v_mov_b32_e32 v16, v2
	v_mov_b32_e32 v17, v2
	v_mov_b32_e32 v22, v2
	v_mov_b32_e32 v23, v2
	v_mov_b32_e32 v24, v2
	v_mov_b32_e32 v25, v2
	v_mov_b32_e32 v30, v2
	v_mov_b32_e32 v31, v2
	v_mov_b32_e32 v32, v2
	v_mov_b32_e32 v33, v2
	v_mov_b32_e32 v34, v2
	v_mov_b32_e32 v35, v2
	v_mov_b32_e32 v36, v2
	v_mov_b32_e32 v37, v2
	v_mov_b32_e32 v42, v2
	v_mov_b32_e32 v43, v2
	v_mov_b32_e32 v44, v2
	v_mov_b32_e32 v45, v2
	v_mov_b32_e32 v50, v2
	v_mov_b32_e32 v51, v2
	v_mov_b32_e32 v52, v2
	v_mov_b32_e32 v53, v2
	v_mov_b32_e32 v58, v2
	v_mov_b32_e32 v59, v2
	v_mov_b32_e32 v60, v2
	v_mov_b32_e32 v61, v2
	v_mov_b32_e32 v38, v2
	v_mov_b32_e32 v39, v2
	v_mov_b32_e32 v40, v2
	v_mov_b32_e32 v41, v2
	v_mov_b32_e32 v46, v2
	v_mov_b32_e32 v47, v2
	v_mov_b32_e32 v48, v2
	v_mov_b32_e32 v49, v2
	v_mov_b32_e32 v54, v2
	v_mov_b32_e32 v55, v2
	v_mov_b32_e32 v56, v2
	v_mov_b32_e32 v57, v2
	v_mov_b32_e32 v62, v2
	v_mov_b32_e32 v63, v2
	v_mov_b32_e32 v64, v2
	v_mov_b32_e32 v65, v2
	v_mov_b32_e32 v66, v2
	v_mov_b32_e32 v67, v2
	v_mov_b32_e32 v68, v2
	v_mov_b32_e32 v69, v2
	v_mov_b32_e32 v74, v2
	v_mov_b32_e32 v75, v2
	v_mov_b32_e32 v76, v2
	v_mov_b32_e32 v77, v2
	v_mov_b32_e32 v82, v2
	v_mov_b32_e32 v83, v2
	v_mov_b32_e32 v84, v2
	v_mov_b32_e32 v85, v2
	v_mov_b32_e32 v90, v2
	v_mov_b32_e32 v91, v2
	v_mov_b32_e32 v92, v2
	v_mov_b32_e32 v93, v2
	v_mov_b32_e32 v70, v2
	v_mov_b32_e32 v71, v2
	v_mov_b32_e32 v72, v2
	v_mov_b32_e32 v73, v2
	v_mov_b32_e32 v78, v2
	v_mov_b32_e32 v79, v2
	v_mov_b32_e32 v80, v2
	v_mov_b32_e32 v81, v2
	v_mov_b32_e32 v86, v2
	v_mov_b32_e32 v87, v2
	v_mov_b32_e32 v88, v2
	v_mov_b32_e32 v89, v2
	v_mov_b32_e32 v94, v2
	v_mov_b32_e32 v95, v2
	v_mov_b32_e32 v96, v2
	v_mov_b32_e32 v97, v2
	v_mov_b32_e32 v98, v2
	v_mov_b32_e32 v99, v2
	v_mov_b32_e32 v100, v2
	v_mov_b32_e32 v101, v2
	v_mov_b32_e32 v106, v2
	v_mov_b32_e32 v107, v2
	v_mov_b32_e32 v108, v2
	v_mov_b32_e32 v109, v2
	v_mov_b32_e32 v114, v2
	v_mov_b32_e32 v115, v2
	v_mov_b32_e32 v116, v2
	v_mov_b32_e32 v117, v2
	v_mov_b32_e32 v122, v2
	v_mov_b32_e32 v123, v2
	v_mov_b32_e32 v124, v2
	v_mov_b32_e32 v125, v2
	v_mov_b32_e32 v102, v2
	v_mov_b32_e32 v103, v2
	v_mov_b32_e32 v104, v2
	v_mov_b32_e32 v105, v2
	v_mov_b32_e32 v110, v2
	v_mov_b32_e32 v111, v2
	v_mov_b32_e32 v112, v2
	v_mov_b32_e32 v113, v2
	v_mov_b32_e32 v118, v2
	v_mov_b32_e32 v119, v2
	v_mov_b32_e32 v120, v2
	v_mov_b32_e32 v121, v2
	v_mov_b32_e32 v126, v2
	v_mov_b32_e32 v127, v2
	v_mov_b32_e32 v128, v2
	v_mov_b32_e32 v129, v2
	v_lshlrev_b32_e32 v244, 1, v143
	v_add_u32_e32 v196, 32, v144
	v_add_u32_e32 v197, 0x10020, v144
	v_add_u32_e32 v198, 0x8020, v145
	v_add_u32_e32 v199, 0x18020, v145
	v_readfirstlane_b32 s40, v130
	v_readfirstlane_b32 s41, v131
	v_readfirstlane_b32 s42, v134
	v_readfirstlane_b32 s43, v135
	v_add_u32_e32 v245, 0x40, v244
	v_add_u32_e32 v246, 0x2200, v244
	v_add_u32_e32 v247, 0x2240, v244
	v_add_u32_e32 v248, 0x11000, v244
	v_add_u32_e32 v249, 0x11040, v244
	v_add_u32_e32 v250, 0x13200, v244
	v_add_u32_e32 v251, 0x13240, v244
	s_add_i32 s44, s28, 32
	s_add_i32 s45, s28, s35
	s_cmp_lg_u64 s[10:11], 0
	s_cselect_b64 s[42:43], s[40:41], s[42:43]
	s_add_u32 s40, s40, 0x80
	s_addc_u32 s41, s41, 0
	s_mov_b32 s47, 0
	s_cmp_eq_u32 s27, 0
	s_cbranch_scc1 .LgA_k1issue
	s_mov_b32 s47, s87
	s_branch .LgA_k1done
.LgA_k1issue:
	s_add_i32 m0, s45, 0x0
	s_nop 0
	global_load_lds_dwordx4 v244, s[40:41]
	s_add_i32 m0, s45, 0x400
	s_nop 0
	global_load_lds_dwordx4 v245, s[40:41]
	s_add_i32 m0, s45, 0x800
	s_nop 0
	global_load_lds_dwordx4 v246, s[40:41]
	s_add_i32 m0, s45, 0xc00
	s_nop 0
	global_load_lds_dwordx4 v247, s[40:41]
	s_add_i32 m0, s45, 0x1000
	s_nop 0
	global_load_lds_dwordx4 v248, s[40:41]
	s_add_i32 m0, s45, 0x1400
	s_nop 0
	global_load_lds_dwordx4 v249, s[40:41]
	s_add_i32 m0, s45, 0x1800
	s_nop 0
	global_load_lds_dwordx4 v250, s[40:41]
	s_add_i32 m0, s45, 0x1c00
	s_nop 0
	global_load_lds_dwordx4 v251, s[40:41]
; #define G_LDA(dst, ih, ks) _Pragma("unroll") for (int i = 0; i < 4; ++i) dst[i] = mk8(*(const u32x4*)(stage + ra + (((ih) * 4 + i) * 2 + (ks)) * 1024))
; #define G_LDB(dst, ks) _Pragma("unroll") for (int j = 0; j < 4; ++j) dst[j] = mk8(*(const u32x4*)(stage + TILE_B + rb + (j * 2 + (ks)) * 1024))
; #define G_MMA(ih, A, B) do { _Pragma("unroll") for (int i = 0; i < 4; ++i) _Pragma("unroll") for (int j = 0; j < 4; ++j) acc[(ih) * 4 + i][j] = MFMA16(A[i], B[j], acc[(ih) * 4 + i][j]); } while (0)
; DI void g_compute(const unsigned char* stage, int ra, int rb, f32x4 (&acc)[8][4]) {
;   bf16x8 b0[4], b1[4], a0[4], a1[4];
;   G_LDB(b0, 0); G_LDA(a0, 0, 0);
;   __builtin_amdgcn_sched_barrier(0);
;   G_LDA(a1, 1, 0);
;   G_MMA(0, a0, b0);
;   __builtin_amdgcn_sched_barrier(0);
;   G_LDB(b1, 1); G_LDA(a0, 0, 1);
;   G_MMA(1, a1, b0);
;   __builtin_amdgcn_sched_barrier(0);
;   G_LDA(a1, 1, 1);
;   G_MMA(0, a0, b1);
;   __builtin_amdgcn_sched_barrier(0);
;   G_MMA(1, a1, b1);
;   __builtin_amdgcn_sched_barrier(0);
; }
;     ...
;   for (int kt = 0; kt < KT; kt += 2) {
;     g_dma(base, off, (kt + 1) * kstep, buf1, w);
;     g_compute(buf0, ra, rb, acc);
.LgA_k1done:
	s_add_u32 s40, s40, 0x80
	s_addc_u32 s41, s41, 0
	ds_read_b128 v[146:149], v198
	ds_read_b128 v[150:153], v198 offset:2048
	ds_read_b128 v[154:157], v198 offset:4096
	ds_read_b128 v[158:161], v198 offset:6144
	ds_read_b128 v[164:167], v196
	ds_read_b128 v[168:171], v196 offset:2048
	ds_read_b128 v[172:175], v196 offset:4096
	ds_read_b128 v[176:179], v196 offset:6144
	s_mov_b32 s46, 0
.LgA_loop:
	s_waitcnt lgkmcnt(0)
	v_mfma_f32_16x16x32_bf16 v[126:129], v[164:167], v[146:149], v[126:129]
	v_mfma_f32_16x16x32_bf16 v[118:121], v[164:167], v[150:153], v[118:121]
	ds_read_b128 v[180:183], v196 offset:8192
	v_mfma_f32_16x16x32_bf16 v[110:113], v[164:167], v[154:157], v[110:113]
	v_mfma_f32_16x16x32_bf16 v[102:105], v[164:167], v[158:161], v[102:105]
	v_mfma_f32_16x16x32_bf16 v[122:125], v[168:171], v[146:149], v[122:125]
	ds_read_b128 v[184:187], v196 offset:10240
	v_mfma_f32_16x16x32_bf16 v[114:117], v[168:171], v[150:153], v[114:117]
	v_mfma_f32_16x16x32_bf16 v[106:109], v[168:171], v[154:157], v[106:109]
	v_mfma_f32_16x16x32_bf16 v[98:101], v[168:171], v[158:161], v[98:101]
	ds_read_b128 v[188:191], v196 offset:12288
	v_mfma_f32_16x16x32_bf16 v[94:97], v[172:175], v[146:149], v[94:97]
	v_mfma_f32_16x16x32_bf16 v[86:89], v[172:175], v[150:153], v[86:89]
	v_mfma_f32_16x16x32_bf16 v[78:81], v[172:175], v[154:157], v[78:81]
	ds_read_b128 v[192:195], v196 offset:14336
	v_mfma_f32_16x16x32_bf16 v[70:73], v[172:175], v[158:161], v[70:73]
	v_mfma_f32_16x16x32_bf16 v[90:93], v[176:179], v[146:149], v[90:93]
	v_mfma_f32_16x16x32_bf16 v[82:85], v[176:179], v[150:153], v[82:85]
	v_mfma_f32_16x16x32_bf16 v[74:77], v[176:179], v[154:157], v[74:77]
	v_mfma_f32_16x16x32_bf16 v[66:69], v[176:179], v[158:161], v[66:69]
	s_waitcnt lgkmcnt(0)
	v_mfma_f32_16x16x32_bf16 v[62:65], v[180:183], v[146:149], v[62:65]
	ds_read_b128 v[216:219], v198 offset:1024
	v_mfma_f32_16x16x32_bf16 v[54:57], v[180:183], v[150:153], v[54:57]
	v_mfma_f32_16x16x32_bf16 v[46:49], v[180:183], v[154:157], v[46:49]
	ds_read_b128 v[220:223], v198 offset:3072
	v_mfma_f32_16x16x32_bf16 v[38:41], v[180:183], v[158:161], v[38:41]
	v_mfma_f32_16x16x32_bf16 v[58:61], v[184:187], v[146:149], v[58:61]
	ds_read_b128 v[224:227], v198 offset:5120
	v_mfma_f32_16x16x32_bf16 v[50:53], v[184:187], v[150:153], v[50:53]
	v_mfma_f32_16x16x32_bf16 v[42:45], v[184:187], v[154:157], v[42:45]
	ds_read_b128 v[240:243], v198 offset:7168
	v_mfma_f32_16x16x32_bf16 v[34:37], v[184:187], v[158:161], v[34:37]
	v_mfma_f32_16x16x32_bf16 v[30:33], v[188:191], v[146:149], v[30:33]
	ds_read_b128 v[164:167], v196 offset:1024
	v_mfma_f32_16x16x32_bf16 v[22:25], v[188:191], v[150:153], v[22:25]
	ds_read_b128 v[168:171], v196 offset:3072
	v_mfma_f32_16x16x32_bf16 v[14:17], v[188:191], v[154:157], v[14:17]
	ds_read_b128 v[172:175], v196 offset:5120
	v_mfma_f32_16x16x32_bf16 v[10:13], v[188:191], v[158:161], v[10:13]
	ds_read_b128 v[176:179], v196 offset:7168
	v_mfma_f32_16x16x32_bf16 v[26:29], v[192:195], v[146:149], v[26:29]
	v_mfma_f32_16x16x32_bf16 v[18:21], v[192:195], v[150:153], v[18:21]
	v_mfma_f32_16x16x32_bf16 v[6:9], v[192:195], v[154:157], v[6:9]
	v_mfma_f32_16x16x32_bf16 v[2:5], v[192:195], v[158:161], v[2:5]
	s_waitcnt lgkmcnt(0)
	v_mfma_f32_16x16x32_bf16 v[126:129], v[164:167], v[216:219], v[126:129]
	v_mfma_f32_16x16x32_bf16 v[118:121], v[164:167], v[220:223], v[118:121]
	ds_read_b128 v[180:183], v196 offset:9216
	v_mfma_f32_16x16x32_bf16 v[110:113], v[164:167], v[224:227], v[110:113]
	v_mfma_f32_16x16x32_bf16 v[102:105], v[164:167], v[240:243], v[102:105]
	v_mfma_f32_16x16x32_bf16 v[122:125], v[168:171], v[216:219], v[122:125]
	ds_read_b128 v[184:187], v196 offset:11264
	v_mfma_f32_16x16x32_bf16 v[114:117], v[168:171], v[220:223], v[114:117]
	v_mfma_f32_16x16x32_bf16 v[106:109], v[168:171], v[224:227], v[106:109]
	v_mfma_f32_16x16x32_bf16 v[98:101], v[168:171], v[240:243], v[98:101]
	ds_read_b128 v[188:191], v196 offset:13312
	v_mfma_f32_16x16x32_bf16 v[94:97], v[172:175], v[216:219], v[94:97]
	v_mfma_f32_16x16x32_bf16 v[86:89], v[172:175], v[220:223], v[86:89]
	v_mfma_f32_16x16x32_bf16 v[78:81], v[172:175], v[224:227], v[78:81]
	ds_read_b128 v[192:195], v196 offset:15360
	v_mfma_f32_16x16x32_bf16 v[70:73], v[172:175], v[240:243], v[70:73]
	v_mfma_f32_16x16x32_bf16 v[90:93], v[176:179], v[216:219], v[90:93]
	v_mfma_f32_16x16x32_bf16 v[82:85], v[176:179], v[220:223], v[82:85]
	v_mfma_f32_16x16x32_bf16 v[74:77], v[176:179], v[224:227], v[74:77]
	v_mfma_f32_16x16x32_bf16 v[66:69], v[176:179], v[240:243], v[66:69]
	s_waitcnt lgkmcnt(0)
	s_cmp_eq_u32 s47, 0
	s_cbranch_scc1 .LgA_w0
	s_mov_b32 s47, 0
	s_waitcnt vmcnt(16)
	s_branch .LgA_w1

;     ...
;   for (int kt = 0; kt < KT; kt += 2) {
;     g_dma(base, off, (kt + 1) * kstep, buf1, w);
;     g_compute(buf0, ra, rb, acc);
;     asm volatile("s_waitcnt vmcnt(0)" ::: "memory");
;     __syncthreads();
;     const bool last = kt + 2 >= KT;
;     g_dma(last ? nbase : base, off, last ? 0 : (kt + 2) * kstep, buf0, w);
;     g_compute(buf1, ra, rb, acc);
;     asm volatile("s_waitcnt vmcnt(0)" ::: "memory");
;     __syncthreads();
.LgA_w1:
	s_barrier
	s_add_i32 m0, s44, 0x0
	v_mfma_f32_16x16x32_bf16 v[62:65], v[180:183], v[216:219], v[62:65]
	global_load_lds_dwordx4 v244, s[40:41]
	ds_read_b128 v[146:149], v199
	v_mfma_f32_16x16x32_bf16 v[54:57], v[180:183], v[220:223], v[54:57]
	ds_read_b128 v[150:153], v199 offset:2048
	s_add_i32 m0, s44, 0x400
	v_mfma_f32_16x16x32_bf16 v[46:49], v[180:183], v[224:227], v[46:49]
	global_load_lds_dwordx4 v245, s[40:41]
	ds_read_b128 v[154:157], v199 offset:4096
	v_mfma_f32_16x16x32_bf16 v[38:41], v[180:183], v[240:243], v[38:41]
	ds_read_b128 v[158:161], v199 offset:6144
	s_add_i32 m0, s44, 0x800
	v_mfma_f32_16x16x32_bf16 v[58:61], v[184:187], v[216:219], v[58:61]
	global_load_lds_dwordx4 v246, s[40:41]
	ds_read_b128 v[164:167], v197
	v_mfma_f32_16x16x32_bf16 v[50:53], v[184:187], v[220:223], v[50:53]
	ds_read_b128 v[168:171], v197 offset:2048
	s_add_i32 m0, s44, 0xc00
	v_mfma_f32_16x16x32_bf16 v[42:45], v[184:187], v[224:227], v[42:45]
	global_load_lds_dwordx4 v247, s[40:41]
	ds_read_b128 v[172:175], v197 offset:4096
	v_mfma_f32_16x16x32_bf16 v[34:37], v[184:187], v[240:243], v[34:37]
	ds_read_b128 v[176:179], v197 offset:6144
	s_add_i32 m0, s44, 0x1000
	v_mfma_f32_16x16x32_bf16 v[30:33], v[188:191], v[216:219], v[30:33]
	global_load_lds_dwordx4 v248, s[40:41]
	v_mfma_f32_16x16x32_bf16 v[22:25], v[188:191], v[220:223], v[22:25]
	s_add_i32 m0, s44, 0x1400
	v_mfma_f32_16x16x32_bf16 v[14:17], v[188:191], v[224:227], v[14:17]
	global_load_lds_dwordx4 v249, s[40:41]
	v_mfma_f32_16x16x32_bf16 v[10:13], v[188:191], v[240:243], v[10:13]
	s_add_i32 m0, s44, 0x1800
	v_mfma_f32_16x16x32_bf16 v[26:29], v[192:195], v[216:219], v[26:29]
	global_load_lds_dwordx4 v250, s[40:41]
	v_mfma_f32_16x16x32_bf16 v[18:21], v[192:195], v[220:223], v[18:21]
	s_add_i32 m0, s44, 0x1c00
	v_mfma_f32_16x16x32_bf16 v[6:9], v[192:195], v[224:227], v[6:9]
	global_load_lds_dwordx4 v251, s[40:41]
	v_mfma_f32_16x16x32_bf16 v[2:5], v[192:195], v[240:243], v[2:5]
	s_add_u32 s40, s40, 0x80
	s_addc_u32 s41, s41, 0
	s_waitcnt lgkmcnt(0)
	v_mfma_f32_16x16x32_bf16 v[126:129], v[164:167], v[146:149], v[126:129]
	v_mfma_f32_16x16x32_bf16 v[118:121], v[164:167], v[150:153], v[118:121]
	ds_read_b128 v[180:183], v197 offset:8192
	v_mfma_f32_16x16x32_bf16 v[110:113], v[164:167], v[154:157], v[110:113]
	v_mfma_f32_16x16x32_bf16 v[102:105], v[164:167], v[158:161], v[102:105]
	v_mfma_f32_16x16x32_bf16 v[122:125], v[168:171], v[146:149], v[122:125]
	ds_read_b128 v[184:187], v197 offset:10240
	v_mfma_f32_16x16x32_bf16 v[114:117], v[168:171], v[150:153], v[114:117]
	v_mfma_f32_16x16x32_bf16 v[106:109], v[168:171], v[154:157], v[106:109]
	v_mfma_f32_16x16x32_bf16 v[98:101], v[168:171], v[158:161], v[98:101]
	ds_read_b128 v[188:191], v197 offset:12288
	v_mfma_f32_16x16x32_bf16 v[94:97], v[172:175], v[146:149], v[94:97]
	v_mfma_f32_16x16x32_bf16 v[86:89], v[172:175], v[150:153], v[86:89]
	v_mfma_f32_16x16x32_bf16 v[78:81], v[172:175], v[154:157], v[78:81]
	ds_read_b128 v[192:195], v197 offset:14336
	v_mfma_f32_16x16x32_bf16 v[70:73], v[172:175], v[158:161], v[70:73]
	v_mfma_f32_16x16x32_bf16 v[90:93], v[176:179], v[146:149], v[90:93]
	v_mfma_f32_16x16x32_bf16 v[82:85], v[176:179], v[150:153], v[82:85]
	v_mfma_f32_16x16x32_bf16 v[74:77], v[176:179], v[154:157], v[74:77]
	v_mfma_f32_16x16x32_bf16 v[66:69], v[176:179], v[158:161], v[66:69]
	s_waitcnt lgkmcnt(0)
	v_mfma_f32_16x16x32_bf16 v[62:65], v[180:183], v[146:149], v[62:65]
	ds_read_b128 v[216:219], v199 offset:1024
	v_mfma_f32_16x16x32_bf16 v[54:57], v[180:183], v[150:153], v[54:57]
	v_mfma_f32_16x16x32_bf16 v[46:49], v[180:183], v[154:157], v[46:49]
	ds_read_b128 v[220:223], v199 offset:3072
	v_mfma_f32_16x16x32_bf16 v[38:41], v[180:183], v[158:161], v[38:41]
	v_mfma_f32_16x16x32_bf16 v[58:61], v[184:187], v[146:149], v[58:61]
	ds_read_b128 v[224:227], v199 offset:5120
	v_mfma_f32_16x16x32_bf16 v[50:53], v[184:187], v[150:153], v[50:53]
	v_mfma_f32_16x16x32_bf16 v[42:45], v[184:187], v[154:157], v[42:45]
	ds_read_b128 v[240:243], v199 offset:7168
	v_mfma_f32_16x16x32_bf16 v[34:37], v[184:187], v[158:161], v[34:37]
	v_mfma_f32_16x16x32_bf16 v[30:33], v[188:191], v[146:149], v[30:33]
	ds_read_b128 v[164:167], v197 offset:1024
	v_mfma_f32_16x16x32_bf16 v[22:25], v[188:191], v[150:153], v[22:25]
	ds_read_b128 v[168:171], v197 offset:3072
	v_mfma_f32_16x16x32_bf16 v[14:17], v[188:191], v[154:157], v[14:17]
	ds_read_b128 v[172:175], v197 offset:5120
	v_mfma_f32_16x16x32_bf16 v[10:13], v[188:191], v[158:161], v[10:13]
	ds_read_b128 v[176:179], v197 offset:7168
	v_mfma_f32_16x16x32_bf16 v[26:29], v[192:195], v[146:149], v[26:29]
	v_mfma_f32_16x16x32_bf16 v[18:21], v[192:195], v[150:153], v[18:21]
	v_mfma_f32_16x16x32_bf16 v[6:9], v[192:195], v[154:157], v[6:9]
	v_mfma_f32_16x16x32_bf16 v[2:5], v[192:195], v[158:161], v[2:5]
	s_waitcnt lgkmcnt(0)
	v_mfma_f32_16x16x32_bf16 v[126:129], v[164:167], v[216:219], v[126:129]
	v_mfma_f32_16x16x32_bf16 v[118:121], v[164:167], v[220:223], v[118:121]
	ds_read_b128 v[180:183], v197 offset:9216
	v_mfma_f32_16x16x32_bf16 v[110:113], v[164:167], v[224:227], v[110:113]
	v_mfma_f32_16x16x32_bf16 v[102:105], v[164:167], v[240:243], v[102:105]
	v_mfma_f32_16x16x32_bf16 v[122:125], v[168:171], v[216:219], v[122:125]
	ds_read_b128 v[184:187], v197 offset:11264
	v_mfma_f32_16x16x32_bf16 v[114:117], v[168:171], v[220:223], v[114:117]
	v_mfma_f32_16x16x32_bf16 v[106:109], v[168:171], v[224:227], v[106:109]
	v_mfma_f32_16x16x32_bf16 v[98:101], v[168:171], v[240:243], v[98:101]
	ds_read_b128 v[188:191], v197 offset:13312
	v_mfma_f32_16x16x32_bf16 v[94:97], v[172:175], v[216:219], v[94:97]
	v_mfma_f32_16x16x32_bf16 v[86:89], v[172:175], v[220:223], v[86:89]
	v_mfma_f32_16x16x32_bf16 v[78:81], v[172:175], v[224:227], v[78:81]
	ds_read_b128 v[192:195], v197 offset:15360
	v_mfma_f32_16x16x32_bf16 v[70:73], v[172:175], v[240:243], v[70:73]
	v_mfma_f32_16x16x32_bf16 v[90:93], v[176:179], v[216:219], v[90:93]
	v_mfma_f32_16x16x32_bf16 v[82:85], v[176:179], v[220:223], v[82:85]
	v_mfma_f32_16x16x32_bf16 v[74:77], v[176:179], v[224:227], v[74:77]
	v_mfma_f32_16x16x32_bf16 v[66:69], v[176:179], v[240:243], v[66:69]
	s_waitcnt lgkmcnt(0)
	s_waitcnt vmcnt(0)
	s_barrier
;     ...
;   for (int kt = 0; kt < KT; kt += 2) {
;     g_dma(base, off, (kt + 1) * kstep, buf1, w);
;     g_compute(buf0, ra, rb, acc);
;     asm volatile("s_waitcnt vmcnt(0)" ::: "memory");
;     __syncthreads();
;     const bool last = kt + 2 >= KT;
;     g_dma(last ? nbase : base, off, last ? 0 : (kt + 2) * kstep, buf0, w);
;     g_compute(buf1, ra, rb, acc);
;     asm volatile("s_waitcnt vmcnt(0)" ::: "memory");
;     __syncthreads();
	s_add_i32 m0, s45, 0x0
	v_mfma_f32_16x16x32_bf16 v[62:65], v[180:183], v[216:219], v[62:65]
	global_load_lds_dwordx4 v244, s[40:41]
	ds_read_b128 v[146:149], v198
	v_mfma_f32_16x16x32_bf16 v[54:57], v[180:183], v[220:223], v[54:57]
	ds_read_b128 v[150:153], v198 offset:2048
	s_add_i32 m0, s45, 0x400
	v_mfma_f32_16x16x32_bf16 v[46:49], v[180:183], v[224:227], v[46:49]
	global_load_lds_dwordx4 v245, s[40:41]
	ds_read_b128 v[154:157], v198 offset:4096
	v_mfma_f32_16x16x32_bf16 v[38:41], v[180:183], v[240:243], v[38:41]
	ds_read_b128 v[158:161], v198 offset:6144
	s_add_i32 m0, s45, 0x800
	v_mfma_f32_16x16x32_bf16 v[58:61], v[184:187], v[216:219], v[58:61]
	global_load_lds_dwordx4 v246, s[40:41]
	ds_read_b128 v[164:167], v196
	v_mfma_f32_16x16x32_bf16 v[50:53], v[184:187], v[220:223], v[50:53]
	ds_read_b128 v[168:171], v196 offset:2048
	s_add_i32 m0, s45, 0xc00
	v_mfma_f32_16x16x32_bf16 v[42:45], v[184:187], v[224:227], v[42:45]
	global_load_lds_dwordx4 v247, s[40:41]
	ds_read_b128 v[172:175], v196 offset:4096
	v_mfma_f32_16x16x32_bf16 v[34:37], v[184:187], v[240:243], v[34:37]
	ds_read_b128 v[176:179], v196 offset:6144
	s_add_i32 m0, s45, 0x1000
	v_mfma_f32_16x16x32_bf16 v[30:33], v[188:191], v[216:219], v[30:33]
	global_load_lds_dwordx4 v248, s[40:41]
	v_mfma_f32_16x16x32_bf16 v[22:25], v[188:191], v[220:223], v[22:25]
	s_add_i32 m0, s45, 0x1400
	v_mfma_f32_16x16x32_bf16 v[14:17], v[188:191], v[224:227], v[14:17]
	global_load_lds_dwordx4 v249, s[40:41]
	v_mfma_f32_16x16x32_bf16 v[10:13], v[188:191], v[240:243], v[10:13]
	s_add_i32 m0, s45, 0x1800
	v_mfma_f32_16x16x32_bf16 v[26:29], v[192:195], v[216:219], v[26:29]
	global_load_lds_dwordx4 v250, s[40:41]
	v_mfma_f32_16x16x32_bf16 v[18:21], v[192:195], v[220:223], v[18:21]
	s_add_i32 m0, s45, 0x1c00
	v_mfma_f32_16x16x32_bf16 v[6:9], v[192:195], v[224:227], v[6:9]
	global_load_lds_dwordx4 v251, s[40:41]
	v_mfma_f32_16x16x32_bf16 v[2:5], v[192:195], v[240:243], v[2:5]
	s_add_u32 s40, s40, 0x80
	s_addc_u32 s41, s41, 0
	s_add_i32 s46, s46, 1
	s_cmp_lt_u32 s46, 7
	s_cbranch_scc1 .LgA_loop
	s_waitcnt lgkmcnt(0)
	v_mfma_f32_16x16x32_bf16 v[126:129], v[164:167], v[146:149], v[126:129]
	v_mfma_f32_16x16x32_bf16 v[118:121], v[164:167], v[150:153], v[118:121]
	ds_read_b128 v[180:183], v196 offset:8192
	v_mfma_f32_16x16x32_bf16 v[110:113], v[164:167], v[154:157], v[110:113]
	v_mfma_f32_16x16x32_bf16 v[102:105], v[164:167], v[158:161], v[102:105]
	v_mfma_f32_16x16x32_bf16 v[122:125], v[168:171], v[146:149], v[122:125]
	ds_read_b128 v[184:187], v196 offset:10240
	v_mfma_f32_16x16x32_bf16 v[114:117], v[168:171], v[150:153], v[114:117]
	v_mfma_f32_16x16x32_bf16 v[106:109], v[168:171], v[154:157], v[106:109]
	v_mfma_f32_16x16x32_bf16 v[98:101], v[168:171], v[158:161], v[98:101]
	ds_read_b128 v[188:191], v196 offset:12288
	v_mfma_f32_16x16x32_bf16 v[94:97], v[172:175], v[146:149], v[94:97]
	v_mfma_f32_16x16x32_bf16 v[86:89], v[172:175], v[150:153], v[86:89]
	v_mfma_f32_16x16x32_bf16 v[78:81], v[172:175], v[154:157], v[78:81]
	ds_read_b128 v[192:195], v196 offset:14336
	v_mfma_f32_16x16x32_bf16 v[70:73], v[172:175], v[158:161], v[70:73]
	v_mfma_f32_16x16x32_bf16 v[90:93], v[176:179], v[146:149], v[90:93]
	v_mfma_f32_16x16x32_bf16 v[82:85], v[176:179], v[150:153], v[82:85]
	v_mfma_f32_16x16x32_bf16 v[74:77], v[176:179], v[154:157], v[74:77]
	v_mfma_f32_16x16x32_bf16 v[66:69], v[176:179], v[158:161], v[66:69]
	s_waitcnt lgkmcnt(0)
	v_mfma_f32_16x16x32_bf16 v[62:65], v[180:183], v[146:149], v[62:65]
	ds_read_b128 v[216:219], v198 offset:1024
	v_mfma_f32_16x16x32_bf16 v[54:57], v[180:183], v[150:153], v[54:57]
	v_mfma_f32_16x16x32_bf16 v[46:49], v[180:183], v[154:157], v[46:49]
	ds_read_b128 v[220:223], v198 offset:3072
	v_mfma_f32_16x16x32_bf16 v[38:41], v[180:183], v[158:161], v[38:41]
	v_mfma_f32_16x16x32_bf16 v[58:61], v[184:187], v[146:149], v[58:61]
	ds_read_b128 v[224:227], v198 offset:5120
	v_mfma_f32_16x16x32_bf16 v[50:53], v[184:187], v[150:153], v[50:53]
	v_mfma_f32_16x16x32_bf16 v[42:45], v[184:187], v[154:157], v[42:45]
	ds_read_b128 v[240:243], v198 offset:7168
	v_mfma_f32_16x16x32_bf16 v[34:37], v[184:187], v[158:161], v[34:37]
	v_mfma_f32_16x16x32_bf16 v[30:33], v[188:191], v[146:149], v[30:33]
	ds_read_b128 v[164:167], v196 offset:1024
	v_mfma_f32_16x16x32_bf16 v[22:25], v[188:191], v[150:153], v[22:25]
	ds_read_b128 v[168:171], v196 offset:3072
	v_mfma_f32_16x16x32_bf16 v[14:17], v[188:191], v[154:157], v[14:17]
	ds_read_b128 v[172:175], v196 offset:5120
	v_mfma_f32_16x16x32_bf16 v[10:13], v[188:191], v[158:161], v[10:13]
	ds_read_b128 v[176:179], v196 offset:7168
	v_mfma_f32_16x16x32_bf16 v[26:29], v[192:195], v[146:149], v[26:29]
	v_mfma_f32_16x16x32_bf16 v[18:21], v[192:195], v[150:153], v[18:21]
	v_mfma_f32_16x16x32_bf16 v[6:9], v[192:195], v[154:157], v[6:9]
	v_mfma_f32_16x16x32_bf16 v[2:5], v[192:195], v[158:161], v[2:5]
	s_waitcnt lgkmcnt(0)
	v_mfma_f32_16x16x32_bf16 v[126:129], v[164:167], v[216:219], v[126:129]
	v_mfma_f32_16x16x32_bf16 v[118:121], v[164:167], v[220:223], v[118:121]
	ds_read_b128 v[180:183], v196 offset:9216
	v_mfma_f32_16x16x32_bf16 v[110:113], v[164:167], v[224:227], v[110:113]
	v_mfma_f32_16x16x32_bf16 v[102:105], v[164:167], v[240:243], v[102:105]
	v_mfma_f32_16x16x32_bf16 v[122:125], v[168:171], v[216:219], v[122:125]
	ds_read_b128 v[184:187], v196 offset:11264
	v_mfma_f32_16x16x32_bf16 v[114:117], v[168:171], v[220:223], v[114:117]
	v_mfma_f32_16x16x32_bf16 v[106:109], v[168:171], v[224:227], v[106:109]
	v_mfma_f32_16x16x32_bf16 v[98:101], v[168:171], v[240:243], v[98:101]
	ds_read_b128 v[188:191], v196 offset:13312
	v_mfma_f32_16x16x32_bf16 v[94:97], v[172:175], v[216:219], v[94:97]
	v_mfma_f32_16x16x32_bf16 v[86:89], v[172:175], v[220:223], v[86:89]
	v_mfma_f32_16x16x32_bf16 v[78:81], v[172:175], v[224:227], v[78:81]
	ds_read_b128 v[192:195], v196 offset:15360
	v_mfma_f32_16x16x32_bf16 v[70:73], v[172:175], v[240:243], v[70:73]
	v_mfma_f32_16x16x32_bf16 v[90:93], v[176:179], v[216:219], v[90:93]
	v_mfma_f32_16x16x32_bf16 v[82:85], v[176:179], v[220:223], v[82:85]
	v_mfma_f32_16x16x32_bf16 v[74:77], v[176:179], v[224:227], v[74:77]
	v_mfma_f32_16x16x32_bf16 v[66:69], v[176:179], v[240:243], v[66:69]
	s_waitcnt lgkmcnt(0)
	s_waitcnt vmcnt(0)
	s_barrier
;     ...
;     const bool last = kt + 2 >= KT;
;     g_dma(last ? nbase : base, off, last ? 0 : (kt + 2) * kstep, buf0, w);
;     g_compute(buf1, ra, rb, acc);
;     asm volatile("s_waitcnt vmcnt(0)" ::: "memory");
;     __syncthreads();
	s_add_i32 m0, s44, 0x0
	v_mfma_f32_16x16x32_bf16 v[62:65], v[180:183], v[216:219], v[62:65]
	global_load_lds_dwordx4 v244, s[42:43]
	ds_read_b128 v[146:149], v199
	v_mfma_f32_16x16x32_bf16 v[54:57], v[180:183], v[220:223], v[54:57]
	ds_read_b128 v[150:153], v199 offset:2048
	s_add_i32 m0, s44, 0x400
	v_mfma_f32_16x16x32_bf16 v[46:49], v[180:183], v[224:227], v[46:49]
	global_load_lds_dwordx4 v245, s[42:43]
	ds_read_b128 v[154:157], v199 offset:4096
	v_mfma_f32_16x16x32_bf16 v[38:41], v[180:183], v[240:243], v[38:41]
	ds_read_b128 v[158:161], v199 offset:6144
	s_add_i32 m0, s44, 0x800
	v_mfma_f32_16x16x32_bf16 v[58:61], v[184:187], v[216:219], v[58:61]
	global_load_lds_dwordx4 v246, s[42:43]
	ds_read_b128 v[164:167], v197
	v_mfma_f32_16x16x32_bf16 v[50:53], v[184:187], v[220:223], v[50:53]
	ds_read_b128 v[168:171], v197 offset:2048
	s_add_i32 m0, s44, 0xc00
	v_mfma_f32_16x16x32_bf16 v[42:45], v[184:187], v[224:227], v[42:45]
	global_load_lds_dwordx4 v247, s[42:43]
	ds_read_b128 v[172:175], v197 offset:4096
	v_mfma_f32_16x16x32_bf16 v[34:37], v[184:187], v[240:243], v[34:37]
	ds_read_b128 v[176:179], v197 offset:6144
	s_add_i32 m0, s44, 0x1000
	v_mfma_f32_16x16x32_bf16 v[30:33], v[188:191], v[216:219], v[30:33]
	global_load_lds_dwordx4 v248, s[42:43]
	v_mfma_f32_16x16x32_bf16 v[22:25], v[188:191], v[220:223], v[22:25]
	s_add_i32 m0, s44, 0x1400
	v_mfma_f32_16x16x32_bf16 v[14:17], v[188:191], v[224:227], v[14:17]
	global_load_lds_dwordx4 v249, s[42:43]
	v_mfma_f32_16x16x32_bf16 v[10:13], v[188:191], v[240:243], v[10:13]
	s_add_i32 m0, s44, 0x1800
	v_mfma_f32_16x16x32_bf16 v[26:29], v[192:195], v[216:219], v[26:29]
	global_load_lds_dwordx4 v250, s[42:43]
	v_mfma_f32_16x16x32_bf16 v[18:21], v[192:195], v[220:223], v[18:21]
	s_add_i32 m0, s44, 0x1c00
	v_mfma_f32_16x16x32_bf16 v[6:9], v[192:195], v[224:227], v[6:9]
	global_load_lds_dwordx4 v251, s[42:43]
	v_mfma_f32_16x16x32_bf16 v[2:5], v[192:195], v[240:243], v[2:5]
	s_add_u32 s42, s42, 0x80
	s_addc_u32 s43, s43, 0
	s_waitcnt lgkmcnt(0)
	v_mfma_f32_16x16x32_bf16 v[126:129], v[164:167], v[146:149], v[126:129]
	v_mfma_f32_16x16x32_bf16 v[118:121], v[164:167], v[150:153], v[118:121]
	ds_read_b128 v[180:183], v197 offset:8192
	v_mfma_f32_16x16x32_bf16 v[110:113], v[164:167], v[154:157], v[110:113]
	v_mfma_f32_16x16x32_bf16 v[102:105], v[164:167], v[158:161], v[102:105]
	v_mfma_f32_16x16x32_bf16 v[122:125], v[168:171], v[146:149], v[122:125]
	ds_read_b128 v[184:187], v197 offset:10240
	v_mfma_f32_16x16x32_bf16 v[114:117], v[168:171], v[150:153], v[114:117]
	v_mfma_f32_16x16x32_bf16 v[106:109], v[168:171], v[154:157], v[106:109]
	v_mfma_f32_16x16x32_bf16 v[98:101], v[168:171], v[158:161], v[98:101]
	ds_read_b128 v[188:191], v197 offset:12288
	v_mfma_f32_16x16x32_bf16 v[94:97], v[172:175], v[146:149], v[94:97]
	v_mfma_f32_16x16x32_bf16 v[86:89], v[172:175], v[150:153], v[86:89]
	v_mfma_f32_16x16x32_bf16 v[78:81], v[172:175], v[154:157], v[78:81]
	ds_read_b128 v[192:195], v197 offset:14336
	v_mfma_f32_16x16x32_bf16 v[70:73], v[172:175], v[158:161], v[70:73]
	v_mfma_f32_16x16x32_bf16 v[90:93], v[176:179], v[146:149], v[90:93]
	v_mfma_f32_16x16x32_bf16 v[82:85], v[176:179], v[150:153], v[82:85]
	v_mfma_f32_16x16x32_bf16 v[74:77], v[176:179], v[154:157], v[74:77]
	v_mfma_f32_16x16x32_bf16 v[66:69], v[176:179], v[158:161], v[66:69]
	s_waitcnt lgkmcnt(0)
	v_mfma_f32_16x16x32_bf16 v[62:65], v[180:183], v[146:149], v[62:65]
	ds_read_b128 v[216:219], v199 offset:1024
	v_mfma_f32_16x16x32_bf16 v[54:57], v[180:183], v[150:153], v[54:57]
	v_mfma_f32_16x16x32_bf16 v[46:49], v[180:183], v[154:157], v[46:49]
	ds_read_b128 v[220:223], v199 offset:3072
	v_mfma_f32_16x16x32_bf16 v[38:41], v[180:183], v[158:161], v[38:41]
	v_mfma_f32_16x16x32_bf16 v[58:61], v[184:187], v[146:149], v[58:61]
	ds_read_b128 v[224:227], v199 offset:5120
	v_mfma_f32_16x16x32_bf16 v[50:53], v[184:187], v[150:153], v[50:53]
	v_mfma_f32_16x16x32_bf16 v[42:45], v[184:187], v[154:157], v[42:45]
	ds_read_b128 v[240:243], v199 offset:7168
	v_mfma_f32_16x16x32_bf16 v[34:37], v[184:187], v[158:161], v[34:37]
	v_mfma_f32_16x16x32_bf16 v[30:33], v[188:191], v[146:149], v[30:33]
	ds_read_b128 v[164:167], v197 offset:1024
	v_mfma_f32_16x16x32_bf16 v[22:25], v[188:191], v[150:153], v[22:25]
	ds_read_b128 v[168:171], v197 offset:3072
	v_mfma_f32_16x16x32_bf16 v[14:17], v[188:191], v[154:157], v[14:17]
	ds_read_b128 v[172:175], v197 offset:5120
	v_mfma_f32_16x16x32_bf16 v[10:13], v[188:191], v[158:161], v[10:13]
	ds_read_b128 v[176:179], v197 offset:7168
	v_mfma_f32_16x16x32_bf16 v[26:29], v[192:195], v[146:149], v[26:29]
	v_mfma_f32_16x16x32_bf16 v[18:21], v[192:195], v[150:153], v[18:21]
	v_mfma_f32_16x16x32_bf16 v[6:9], v[192:195], v[154:157], v[6:9]
	v_mfma_f32_16x16x32_bf16 v[2:5], v[192:195], v[158:161], v[2:5]
	s_waitcnt lgkmcnt(0)
	v_mfma_f32_16x16x32_bf16 v[126:129], v[164:167], v[216:219], v[126:129]
	v_mfma_f32_16x16x32_bf16 v[118:121], v[164:167], v[220:223], v[118:121]
	ds_read_b128 v[180:183], v197 offset:9216
	v_mfma_f32_16x16x32_bf16 v[110:113], v[164:167], v[224:227], v[110:113]
	v_mfma_f32_16x16x32_bf16 v[102:105], v[164:167], v[240:243], v[102:105]
	v_mfma_f32_16x16x32_bf16 v[122:125], v[168:171], v[216:219], v[122:125]
	ds_read_b128 v[184:187], v197 offset:11264
	v_mfma_f32_16x16x32_bf16 v[114:117], v[168:171], v[220:223], v[114:117]
	v_mfma_f32_16x16x32_bf16 v[106:109], v[168:171], v[224:227], v[106:109]
	v_mfma_f32_16x16x32_bf16 v[98:101], v[168:171], v[240:243], v[98:101]
	ds_read_b128 v[188:191], v197 offset:13312
	v_mfma_f32_16x16x32_bf16 v[94:97], v[172:175], v[216:219], v[94:97]
	v_mfma_f32_16x16x32_bf16 v[86:89], v[172:175], v[220:223], v[86:89]
	v_mfma_f32_16x16x32_bf16 v[78:81], v[172:175], v[224:227], v[78:81]
	ds_read_b128 v[192:195], v197 offset:15360
	v_mfma_f32_16x16x32_bf16 v[70:73], v[172:175], v[240:243], v[70:73]
	v_mfma_f32_16x16x32_bf16 v[90:93], v[176:179], v[216:219], v[90:93]
	v_mfma_f32_16x16x32_bf16 v[82:85], v[176:179], v[220:223], v[82:85]
	v_mfma_f32_16x16x32_bf16 v[74:77], v[176:179], v[224:227], v[74:77]
	v_mfma_f32_16x16x32_bf16 v[66:69], v[176:179], v[240:243], v[66:69]
	s_waitcnt lgkmcnt(0)
	s_waitcnt vmcnt(0)
	s_barrier
;     ...
;     g_dma(last ? nbase : base, off, last ? 0 : (kt + 2) * kstep, buf0, w);
;     g_compute(buf1, ra, rb, acc);
;     asm volatile("s_waitcnt vmcnt(0)" ::: "memory");
;     __syncthreads();
; DI void phaseA_epilogue(const Params& p, int layer, int mt, int nt, const f32x4 (&acc)[8][4], const float* rs_s) {
;     ...
;   const bool headtype = nt < 4 || (nt >= 6 && nt < 10);
;   const bool rot = nt == 6 || nt == 7 || nt == 9;
;   f32x4 csr[2][2], snr[2][2];
; #pragma unroll
;   for (int j = 0; j < 4; ++j) {
;     if (rot && (j & 1) == 0) {
; #pragma unroll
;       for (int jj = 0; jj < 2; ++jj) {
;         const long tokj = (long)mt * 256 + wb * 64 + (j >> 1) * 32 + (qi >> 2) * 8 + jj * 4 + (qi & 3);
; #pragma unroll
;         for (int i = 0; i < 2; ++i) { csr[jj][i] = *(const f32x4*)(p.cosT() + tokj * 32 + quad * 8 + i * 4); snr[jj][i] = *(const f32x4*)(p.sinT() + tokj * 32 + quad * 8 + i * 4); }
;       }
;     }
;     const int tl = wb * 64 + (j >> 1) * 32 + (qi >> 2) * 8 + (j & 1) * 4 + (qi & 3); const long tok = (long)mt * 256 + tl; const int b = (int)(tok >> 11), sq = (int)(tok & 2047);
	s_add_i32 m0, s45, 0x0
	v_mfma_f32_16x16x32_bf16 v[62:65], v[180:183], v[216:219], v[62:65]
	global_load_lds_dwordx4 v244, s[42:43]
	v_mfma_f32_16x16x32_bf16 v[54:57], v[180:183], v[220:223], v[54:57]
	s_add_i32 m0, s45, 0x400
	v_mfma_f32_16x16x32_bf16 v[46:49], v[180:183], v[224:227], v[46:49]
	global_load_lds_dwordx4 v245, s[42:43]
	v_mfma_f32_16x16x32_bf16 v[38:41], v[180:183], v[240:243], v[38:41]
	s_add_i32 m0, s45, 0x800
	v_mfma_f32_16x16x32_bf16 v[58:61], v[184:187], v[216:219], v[58:61]
	global_load_lds_dwordx4 v246, s[42:43]
	v_mfma_f32_16x16x32_bf16 v[50:53], v[184:187], v[220:223], v[50:53]
	s_add_i32 m0, s45, 0xc00
	v_mfma_f32_16x16x32_bf16 v[42:45], v[184:187], v[224:227], v[42:45]
	global_load_lds_dwordx4 v247, s[42:43]
	v_mfma_f32_16x16x32_bf16 v[34:37], v[184:187], v[240:243], v[34:37]
	s_add_i32 m0, s45, 0x1000
	v_mfma_f32_16x16x32_bf16 v[30:33], v[188:191], v[216:219], v[30:33]
	global_load_lds_dwordx4 v248, s[42:43]
	v_mfma_f32_16x16x32_bf16 v[22:25], v[188:191], v[220:223], v[22:25]
	s_add_i32 m0, s45, 0x1400
	v_mfma_f32_16x16x32_bf16 v[14:17], v[188:191], v[224:227], v[14:17]
	global_load_lds_dwordx4 v249, s[42:43]
	v_mfma_f32_16x16x32_bf16 v[10:13], v[188:191], v[240:243], v[10:13]
	s_add_i32 m0, s45, 0x1800
	v_mfma_f32_16x16x32_bf16 v[26:29], v[192:195], v[216:219], v[26:29]
	global_load_lds_dwordx4 v250, s[42:43]
	v_mfma_f32_16x16x32_bf16 v[18:21], v[192:195], v[220:223], v[18:21]
	s_add_i32 m0, s45, 0x1c00
	v_mfma_f32_16x16x32_bf16 v[6:9], v[192:195], v[224:227], v[6:9]
	global_load_lds_dwordx4 v251, s[42:43]
	v_mfma_f32_16x16x32_bf16 v[2:5], v[192:195], v[240:243], v[2:5]
	s_add_u32 s42, s42, 0x80
	s_addc_u32 s43, s43, 0
	v_readfirstlane_b32 s87, v202
	s_nop 0
	s_cmp_lg_u32 s87, 20
	s_cselect_b32 s87, 1, 0
	s_nop 7
	s_nop 3
	v_mov_b32_e32 v171, v210
	s_nop 0
	v_ashrrev_i32_e32 v169, 8, v171
	v_bfe_u32 v0, v171, 6, 2
	v_and_b32_e32 v131, 15, v171
	v_bfe_u32 v170, v171, 4, 2
	s_and_saveexec_b64 s[10:11], s[8:9]
	s_xor_b64 s[12:13], exec, s[10:11]
	s_cbranch_execz .LBB0_487
	v_cmp_lt_i32_e32 vcc, 8, v202
	s_mov_b64 s[10:11], 0
	v_cmp_eq_u32_e64 s[56:57], 9, v202
	s_and_saveexec_b64 s[8:9], vcc
	s_xor_b64 s[8:9], exec, s[8:9]
	s_and_b64 s[10:11], s[56:57], exec
	s_or_saveexec_b64 s[8:9], s[8:9]
	v_add_u32_e32 v130, -6, v202
	v_cmp_gt_u32_e64 s[58:59], 2, v130
	s_xor_b64 exec, exec, s[8:9]
	s_andn2_b64 s[10:11], s[10:11], exec
	s_and_b64 s[28:29], s[58:59], exec
	s_or_b64 s[10:11], s[10:11], s[28:29]
	s_or_b64 exec, exec, s[8:9]
	v_lshlrev_b32_e32 v130, 1, v131
	v_lshlrev_b32_e32 v0, 6, v0
	v_and_b32_e32 v130, 24, v130
	v_and_b32_e32 v131, 3, v171
	v_lshlrev_b64 v[164:165], 8, v[162:163]
	v_or3_b32 v205, v0, v130, v131
	v_or_b32_e32 v180, v164, v205
	v_mov_b32_e32 v181, v165
	v_lshlrev_b32_e32 v0, 5, v170
	v_lshl_add_u64 v[172:173], s[38:39], 0, v[0:1]
	v_lshl_add_u64 v[174:175], s[60:61], 0, v[0:1]
	v_lshlrev_b64 v[176:177], 7, v[180:181]
	s_and_saveexec_b64 s[8:9], s[10:11]
	s_cbranch_execz .LBB0_282
	v_lshl_add_u64 v[130:131], v[172:173], 0, v[176:177]
	v_lshl_add_u64 v[132:133], v[174:175], 0, v[176:177]
	global_load_dwordx4 v[146:149], v[130:131], off offset:16
	global_load_dwordx4 v[150:153], v[130:131], off
	global_load_dwordx4 v[154:157], v[132:133], off offset:16
	global_load_dwordx4 v[158:161], v[132:133], off
	v_or_b32_e32 v130, 0x200, v176
	v_mov_b32_e32 v131, v177
	v_lshl_add_u64 v[134:135], v[172:173], 0, v[130:131]
	v_lshl_add_u64 v[142:143], v[174:175], 0, v[130:131]
	global_load_dwordx4 v[130:133], v[134:135], off offset:16
	s_nop 0
	global_load_dwordx4 v[134:137], v[134:135], off
	s_nop 0
	global_load_dwordx4 v[138:141], v[142:143], off offset:16
	s_nop 0
	global_load_dwordx4 v[142:145], v[142:143], off

; DI int my_tid() { int t = threadIdx.x; asm volatile("" : "+v"(t)); return t; }
;     ...
;   const int tid = my_tid(), lane = tid & 63, w = __builtin_amdgcn_readfirstlane(tid >> 6), wa = w >> 2, wb = w & 3, qi = lane & 15, quad = lane >> 4;
;   const bf16_t* base = w >= 4 ? Bg : Ag; const int ld = (int)(w >= 4 ? ldb : lda);
;   const bf16_t* nbase = nAg ? (w >= 4 ? nBg : nAg) : base;
;   unsigned off[8];
; #pragma unroll
;   for (int u = 0; u < 8; ++u) {
;     const int blk = (w & 3) * 8 + u, rg = blk >> 1, kh = blk & 1;
;     int R = rg * 16 + (lane >> 2);
;     if (perm) { const int rho = R & 31; R = (R & ~31) + ((rho >> 2) & 3) * 8 + (rho >> 4) * 4 + (rho & 3); }
;     off[u] = (unsigned)(R * ld + kh * 32 + (lane & 3) * 8);
;   }
;   const int ra = (wa * 8) * 2 * 1024 + (qi * 4 + quad) * 16, rb = (wb * 4) * 2 * 1024 + (qi * 4 + quad) * 16;
;   unsigned char* buf0 = lds; unsigned char* buf1 = lds + STAGE_B;
;   const int KT = K >> 6;
;   if (!pre) {
;     g_dma(base, off, 0, buf0, w);
;     asm volatile("s_waitcnt vmcnt(0)" ::: "memory");
;     __syncthreads();
;   }
; DI void phaseD(const Params& p0, const Slot sl, int layer, unsigned char* lds) {
;     ...
;       const bf16_t* Wg = (which ? p.wupb_t() : p.wupa_t()) + ((long)nt * 256) * 512;
;       const bf16_t* Yg = (which ? p.nz() : p.sbz()) + (long)mt * 256 * 512;
;       const bf16_t* Gg = which ? p.gb() : p.ga();
;       int mt2 = mt, nt2 = nt; bool more = true;
;       if (which) more = tile_order(sl, it + 1, 4, mt2, nt2);
;       const bf16_t* Wn = more ? (which ? p.wupa_t() : p.wupb_t()) + ((long)nt2 * 256) * 512 : Wg;
;       const bf16_t* Yn = more ? (which ? p.sbz() : p.nz()) + (long)mt2 * 256 * 512 : Yg;
;       f32x4 acc[8][4]; zero_acc(acc);
;       gemm_core(Wg, 512, Yg, 512, 512, gl, acc, 64, it > 0 || which, Wn, Yn);
.LBB0_838:
	s_or_b64 vcc, s[16:17], s[46:47]
	s_xor_b64 s[0:1], vcc, -1
	s_xor_b64 s[14:15], s[16:17], -1
	s_or_b64 s[0:1], s[16:17], s[0:1]
	s_and_b64 s[40:41], s[16:17], exec
	v_cndmask_b32_e32 v12, v165, v130, vcc
	s_cselect_b32 s36, 0xfd0000, s33
	s_add_u32 s40, s4, s36
	v_ashrrev_i32_e32 v13, 31, v12
	s_addc_u32 s41, s5, 0
	v_lshlrev_b64 v[12:13], 18, v[12:13]
	v_lshl_add_u64 v[12:13], s[40:41], 0, v[12:13]
	s_and_b64 s[40:41], s[16:17], exec
	s_mov_b32 s24, 0xc170000
	v_cndmask_b32_e32 v10, v166, v132, vcc
	s_cselect_b32 s36, 0x13570000, s24
	s_add_u32 s40, s4, s36
	v_ashrrev_i32_e32 v11, 31, v10
	v_cndmask_b32_e64 v0, v4, v12, s[0:1]
	v_cndmask_b32_e64 v9, v5, v13, s[0:1]
	s_addc_u32 s41, s5, 0
	v_lshlrev_b64 v[4:5], 18, v[10:11]
	v_lshl_add_u64 v[4:5], s[40:41], 0, v[4:5]
	v_cndmask_b32_e64 v2, v2, v4, s[0:1]
	v_cndmask_b32_e64 v3, v3, v5, s[0:1]
	v_and_b32_e32 v4, 48, v8
	v_cndmask_b32_e64 v146, v0, v2, s[8:9]
	s_lshl_b32 s0, s38, 6
	v_lshlrev_b32_e32 v0, 6, v8
	s_movk_i32 s1, 0x3c0
	s_and_b32 s0, s0, 0xffffc000
	v_and_or_b32 v0, v0, s1, v4
	v_or_b32_e32 v172, s0, v0
	s_add_i32 s0, s29, 0x6020
	v_lshl_or_b32 v173, s30, 13, v0
	v_add_u32_e32 v0, s0, v7
	v_add_lshl_u32 v0, v0, v6, 1
	s_add_i32 s0, s29, 0x6000
	v_lshl_add_u64 v[148:149], v[0:1], 0, s[6:7]
	v_add_u32_e32 v0, s0, v7
	v_add_lshl_u32 v0, v0, v6, 1
	s_add_i32 s0, s29, 0x4020
	v_lshl_add_u64 v[150:151], v[0:1], 0, s[6:7]
	v_add_u32_e32 v0, s0, v7
	v_add_lshl_u32 v0, v0, v6, 1
	s_add_i32 s0, s29, 0x4000
	v_lshl_add_u64 v[152:153], v[0:1], 0, s[6:7]
	v_add_u32_e32 v0, s0, v7
	v_add_lshl_u32 v0, v0, v6, 1
	s_add_i32 s0, s29, 0x2020
	v_lshl_add_u64 v[154:155], v[0:1], 0, s[6:7]
	v_add_u32_e32 v0, s0, v7
	v_add_lshl_u32 v0, v0, v6, 1
	s_add_i32 s0, s29, 0x2000
	v_lshl_add_u64 v[156:157], v[0:1], 0, s[6:7]
	v_add_u32_e32 v0, s0, v7
	v_add_lshl_u32 v0, v0, v6, 1
	v_lshl_add_u64 v[158:159], v[0:1], 0, s[6:7]
	v_add3_u32 v0, s29, 32, v7
	v_add_lshl_u32 v0, v0, v6, 1
	v_lshl_add_u64 v[160:161], v[0:1], 0, s[6:7]
	v_add_u32_e32 v0, s29, v7
	v_add_lshl_u32 v0, v0, v6, 1
	v_mov_b32_e32 v2, 0
	s_mov_b32 s28, 0
	v_cndmask_b32_e64 v131, v9, v3, s[8:9]
	v_lshl_add_u64 v[162:163], v[0:1], 0, s[6:7]
	s_movk_i32 s0, 0x80
	v_mov_b32_e32 v3, v2
	v_mov_b32_e32 v4, v2
	v_mov_b32_e32 v5, v2
	v_mov_b32_e32 v34, v2
	v_mov_b32_e32 v35, v2
	v_mov_b32_e32 v36, v2
	v_mov_b32_e32 v37, v2
	v_mov_b32_e32 v62, v2
	v_mov_b32_e32 v63, v2
	v_mov_b32_e32 v64, v2
	v_mov_b32_e32 v65, v2
	v_mov_b32_e32 v98, v2
	v_mov_b32_e32 v99, v2
	v_mov_b32_e32 v100, v2
	v_mov_b32_e32 v101, v2
	v_mov_b32_e32 v6, v2
	v_mov_b32_e32 v7, v2
	v_mov_b32_e32 v8, v2
	v_mov_b32_e32 v9, v2
	v_mov_b32_e32 v38, v2
	v_mov_b32_e32 v39, v2
	v_mov_b32_e32 v40, v2
	v_mov_b32_e32 v41, v2
	v_mov_b32_e32 v70, v2
	v_mov_b32_e32 v71, v2
	v_mov_b32_e32 v72, v2
	v_mov_b32_e32 v73, v2
	v_mov_b32_e32 v102, v2
	v_mov_b32_e32 v103, v2
	v_mov_b32_e32 v104, v2
	v_mov_b32_e32 v105, v2
	v_mov_b32_e32 v10, v2
	v_mov_b32_e32 v11, v2
	v_mov_b32_e32 v12, v2
	v_mov_b32_e32 v13, v2
	v_mov_b32_e32 v42, v2
	v_mov_b32_e32 v43, v2
	v_mov_b32_e32 v44, v2
	v_mov_b32_e32 v45, v2
	v_mov_b32_e32 v74, v2
	v_mov_b32_e32 v75, v2
	v_mov_b32_e32 v76, v2
	v_mov_b32_e32 v77, v2
	v_mov_b32_e32 v106, v2
	v_mov_b32_e32 v107, v2
	v_mov_b32_e32 v108, v2
	v_mov_b32_e32 v109, v2
	v_mov_b32_e32 v14, v2
	v_mov_b32_e32 v15, v2
	v_mov_b32_e32 v16, v2
	v_mov_b32_e32 v17, v2
	v_mov_b32_e32 v46, v2
	v_mov_b32_e32 v47, v2
	v_mov_b32_e32 v48, v2
	v_mov_b32_e32 v49, v2
	v_mov_b32_e32 v78, v2
	v_mov_b32_e32 v79, v2
	v_mov_b32_e32 v80, v2
	v_mov_b32_e32 v81, v2
	v_mov_b32_e32 v110, v2
	v_mov_b32_e32 v111, v2
	v_mov_b32_e32 v112, v2
	v_mov_b32_e32 v113, v2
	v_mov_b32_e32 v18, v2
	v_mov_b32_e32 v19, v2
	v_mov_b32_e32 v20, v2
	v_mov_b32_e32 v21, v2
	v_mov_b32_e32 v50, v2
	v_mov_b32_e32 v51, v2
	v_mov_b32_e32 v52, v2
	v_mov_b32_e32 v53, v2
	v_mov_b32_e32 v82, v2
	v_mov_b32_e32 v83, v2
	v_mov_b32_e32 v84, v2
	v_mov_b32_e32 v85, v2
	v_mov_b32_e32 v114, v2
	v_mov_b32_e32 v115, v2
	v_mov_b32_e32 v116, v2
	v_mov_b32_e32 v117, v2
	s_waitcnt vmcnt(0)
	v_mov_b32_e32 v22, v2
	v_mov_b32_e32 v23, v2
	v_mov_b32_e32 v24, v2
	v_mov_b32_e32 v25, v2
	v_mov_b32_e32 v54, v2
	v_mov_b32_e32 v55, v2
	v_mov_b32_e32 v56, v2
	v_mov_b32_e32 v57, v2
	v_mov_b32_e32 v86, v2
	v_mov_b32_e32 v87, v2
	v_mov_b32_e32 v88, v2
	v_mov_b32_e32 v89, v2
	v_mov_b32_e32 v118, v2
	v_mov_b32_e32 v119, v2
	v_mov_b32_e32 v120, v2
	v_mov_b32_e32 v121, v2
	v_mov_b32_e32 v26, v2
	v_mov_b32_e32 v27, v2
	v_mov_b32_e32 v28, v2
	v_mov_b32_e32 v29, v2
	v_mov_b32_e32 v58, v2
	v_mov_b32_e32 v59, v2
	v_mov_b32_e32 v60, v2
	v_mov_b32_e32 v61, v2
	v_mov_b32_e32 v90, v2
	v_mov_b32_e32 v91, v2
	v_mov_b32_e32 v92, v2
	v_mov_b32_e32 v93, v2
	v_mov_b32_e32 v122, v2
	v_mov_b32_e32 v123, v2
	v_mov_b32_e32 v124, v2
	v_mov_b32_e32 v125, v2
	v_mov_b32_e32 v30, v2
	v_mov_b32_e32 v31, v2
	v_mov_b32_e32 v32, v2
	v_mov_b32_e32 v33, v2
	v_mov_b32_e32 v66, v2
	v_mov_b32_e32 v67, v2
	v_mov_b32_e32 v68, v2
	v_mov_b32_e32 v69, v2
	v_mov_b32_e32 v94, v2
	v_mov_b32_e32 v95, v2
	v_mov_b32_e32 v96, v2
	v_mov_b32_e32 v97, v2
	v_mov_b32_e32 v126, v2
	v_mov_b32_e32 v127, v2
	v_mov_b32_e32 v128, v2
	v_mov_b32_e32 v129, v2
	v_lshlrev_b32_e32 v152, 1, v133
	v_add_u32_e32 v160, 32, v172
	v_add_u32_e32 v161, 0x10020, v172
	v_add_u32_e32 v162, 0x8020, v173
	v_add_u32_e32 v163, 0x18020, v173
	v_readfirstlane_b32 s38, v142
	v_readfirstlane_b32 s39, v143
	v_readfirstlane_b32 s40, v146
	v_readfirstlane_b32 s41, v131
	v_add_u32_e32 v153, 0x40, v152
	v_add_u32_e32 v154, 0x4000, v152
	v_add_u32_e32 v155, 0x4040, v152
	v_add_u32_e32 v156, 0x8000, v152
	v_add_u32_e32 v157, 0x8040, v152
	v_add_u32_e32 v158, 0xc000, v152
	v_add_u32_e32 v159, 0xc040, v152
	s_add_i32 s42, s27, 32
	s_add_i32 s43, s27, s35
	s_add_u32 s38, s38, 0x80
	s_addc_u32 s39, s39, 0
	s_add_i32 m0, s43, 0x0
	s_nop 0
	global_load_lds_dwordx4 v152, s[38:39]
	s_add_i32 m0, s43, 0x400
	s_nop 0
	global_load_lds_dwordx4 v153, s[38:39]
	s_add_i32 m0, s43, 0x800
	s_nop 0
	global_load_lds_dwordx4 v154, s[38:39]
	s_add_i32 m0, s43, 0xc00
	s_nop 0
	global_load_lds_dwordx4 v155, s[38:39]
	s_add_i32 m0, s43, 0x1000
	s_nop 0
	global_load_lds_dwordx4 v156, s[38:39]
	s_add_i32 m0, s43, 0x1400
	s_nop 0
	global_load_lds_dwordx4 v157, s[38:39]
	s_add_i32 m0, s43, 0x1800
	s_nop 0
	global_load_lds_dwordx4 v158, s[38:39]
	s_add_i32 m0, s43, 0x1c00
	s_nop 0
	global_load_lds_dwordx4 v159, s[38:39]
	s_add_u32 s38, s38, 0x80
	s_addc_u32 s39, s39, 0
	ds_read_b128 v[174:177], v162
	ds_read_b128 v[178:181], v162 offset:2048
	ds_read_b128 v[182:185], v162 offset:4096
	ds_read_b128 v[186:189], v162 offset:6144
	ds_read_b128 v[190:193], v160
	ds_read_b128 v[194:197], v160 offset:2048
	ds_read_b128 v[198:201], v160 offset:4096
	ds_read_b128 v[202:205], v160 offset:6144
	s_mov_b32 s48, 0
; #define G_LDA(dst, ih, ks) _Pragma("unroll") for (int i = 0; i < 4; ++i) dst[i] = mk8(*(const u32x4*)(stage + ra + (((ih) * 4 + i) * 2 + (ks)) * 1024))
; #define G_LDB(dst, ks) _Pragma("unroll") for (int j = 0; j < 4; ++j) dst[j] = mk8(*(const u32x4*)(stage + TILE_B + rb + (j * 2 + (ks)) * 1024))
; #define G_MMA(ih, A, B) do { _Pragma("unroll") for (int i = 0; i < 4; ++i) _Pragma("unroll") for (int j = 0; j < 4; ++j) acc[(ih) * 4 + i][j] = MFMA16(A[i], B[j], acc[(ih) * 4 + i][j]); } while (0)
; DI void g_compute(const unsigned char* stage, int ra, int rb, f32x4 (&acc)[8][4]) {
;   bf16x8 b0[4], b1[4], a0[4], a1[4];
;   G_LDB(b0, 0); G_LDA(a0, 0, 0);
;   __builtin_amdgcn_sched_barrier(0);
;   G_LDA(a1, 1, 0);
;   G_MMA(0, a0, b0);
;   __builtin_amdgcn_sched_barrier(0);
;   G_LDB(b1, 1); G_LDA(a0, 0, 1);
;   G_MMA(1, a1, b0);
;   __builtin_amdgcn_sched_barrier(0);
;   G_LDA(a1, 1, 1);
;   G_MMA(0, a0, b1);
;   __builtin_amdgcn_sched_barrier(0);
;   G_MMA(1, a1, b1);
;   __builtin_amdgcn_sched_barrier(0);
; }
;     ...
;   for (int kt = 0; kt < KT; kt += 2) {
;     g_dma(base, off, (kt + 1) * kstep, buf1, w);
;     g_compute(buf0, ra, rb, acc);
;     asm volatile("s_waitcnt vmcnt(0)" ::: "memory");
;     __syncthreads();
.LgD_loop:
	s_waitcnt lgkmcnt(0)
	v_mfma_f32_16x16x32_bf16 v[126:129], v[190:193], v[174:177], v[126:129]
	v_mfma_f32_16x16x32_bf16 v[94:97], v[190:193], v[178:181], v[94:97]
	ds_read_b128 v[206:209], v160 offset:8192
	v_mfma_f32_16x16x32_bf16 v[66:69], v[190:193], v[182:185], v[66:69]
	v_mfma_f32_16x16x32_bf16 v[30:33], v[190:193], v[186:189], v[30:33]
	v_mfma_f32_16x16x32_bf16 v[122:125], v[194:197], v[174:177], v[122:125]
	ds_read_b128 v[216:219], v160 offset:10240
	v_mfma_f32_16x16x32_bf16 v[90:93], v[194:197], v[178:181], v[90:93]
	v_mfma_f32_16x16x32_bf16 v[58:61], v[194:197], v[182:185], v[58:61]
	v_mfma_f32_16x16x32_bf16 v[26:29], v[194:197], v[186:189], v[26:29]
	ds_read_b128 v[220:223], v160 offset:12288
	v_mfma_f32_16x16x32_bf16 v[118:121], v[198:201], v[174:177], v[118:121]
	v_mfma_f32_16x16x32_bf16 v[86:89], v[198:201], v[178:181], v[86:89]
	v_mfma_f32_16x16x32_bf16 v[54:57], v[198:201], v[182:185], v[54:57]
	ds_read_b128 v[224:227], v160 offset:14336
	v_mfma_f32_16x16x32_bf16 v[22:25], v[198:201], v[186:189], v[22:25]
	v_mfma_f32_16x16x32_bf16 v[114:117], v[202:205], v[174:177], v[114:117]
	v_mfma_f32_16x16x32_bf16 v[82:85], v[202:205], v[178:181], v[82:85]
	v_mfma_f32_16x16x32_bf16 v[50:53], v[202:205], v[182:185], v[50:53]
	v_mfma_f32_16x16x32_bf16 v[18:21], v[202:205], v[186:189], v[18:21]
	s_waitcnt lgkmcnt(0)
	v_mfma_f32_16x16x32_bf16 v[110:113], v[206:209], v[174:177], v[110:113]
	ds_read_b128 v[240:243], v162 offset:1024
	v_mfma_f32_16x16x32_bf16 v[78:81], v[206:209], v[178:181], v[78:81]
	v_mfma_f32_16x16x32_bf16 v[46:49], v[206:209], v[182:185], v[46:49]
	ds_read_b128 v[244:247], v162 offset:3072
	v_mfma_f32_16x16x32_bf16 v[14:17], v[206:209], v[186:189], v[14:17]
	v_mfma_f32_16x16x32_bf16 v[106:109], v[216:219], v[174:177], v[106:109]
	ds_read_b128 v[248:251], v162 offset:5120
	v_mfma_f32_16x16x32_bf16 v[74:77], v[216:219], v[178:181], v[74:77]
	v_mfma_f32_16x16x32_bf16 v[42:45], v[216:219], v[182:185], v[42:45]
	ds_read_b128 v[148:151], v162 offset:7168
	v_mfma_f32_16x16x32_bf16 v[10:13], v[216:219], v[186:189], v[10:13]
	v_mfma_f32_16x16x32_bf16 v[102:105], v[220:223], v[174:177], v[102:105]
	ds_read_b128 v[190:193], v160 offset:1024
	v_mfma_f32_16x16x32_bf16 v[70:73], v[220:223], v[178:181], v[70:73]
	ds_read_b128 v[194:197], v160 offset:3072
	v_mfma_f32_16x16x32_bf16 v[38:41], v[220:223], v[182:185], v[38:41]
	ds_read_b128 v[198:201], v160 offset:5120
	v_mfma_f32_16x16x32_bf16 v[6:9], v[220:223], v[186:189], v[6:9]
	ds_read_b128 v[202:205], v160 offset:7168
	v_mfma_f32_16x16x32_bf16 v[98:101], v[224:227], v[174:177], v[98:101]
	v_mfma_f32_16x16x32_bf16 v[62:65], v[224:227], v[178:181], v[62:65]
	v_mfma_f32_16x16x32_bf16 v[34:37], v[224:227], v[182:185], v[34:37]
	v_mfma_f32_16x16x32_bf16 v[2:5], v[224:227], v[186:189], v[2:5]
	s_waitcnt lgkmcnt(0)
	v_mfma_f32_16x16x32_bf16 v[126:129], v[190:193], v[240:243], v[126:129]
	v_mfma_f32_16x16x32_bf16 v[94:97], v[190:193], v[244:247], v[94:97]
	ds_read_b128 v[206:209], v160 offset:9216
	v_mfma_f32_16x16x32_bf16 v[66:69], v[190:193], v[248:251], v[66:69]
	v_mfma_f32_16x16x32_bf16 v[30:33], v[190:193], v[148:151], v[30:33]
	v_mfma_f32_16x16x32_bf16 v[122:125], v[194:197], v[240:243], v[122:125]
	ds_read_b128 v[216:219], v160 offset:11264
	v_mfma_f32_16x16x32_bf16 v[90:93], v[194:197], v[244:247], v[90:93]
	v_mfma_f32_16x16x32_bf16 v[58:61], v[194:197], v[248:251], v[58:61]
	v_mfma_f32_16x16x32_bf16 v[26:29], v[194:197], v[148:151], v[26:29]
	ds_read_b128 v[220:223], v160 offset:13312
	v_mfma_f32_16x16x32_bf16 v[118:121], v[198:201], v[240:243], v[118:121]
	v_mfma_f32_16x16x32_bf16 v[86:89], v[198:201], v[244:247], v[86:89]
	v_mfma_f32_16x16x32_bf16 v[54:57], v[198:201], v[248:251], v[54:57]
	ds_read_b128 v[224:227], v160 offset:15360
	v_mfma_f32_16x16x32_bf16 v[22:25], v[198:201], v[148:151], v[22:25]
	v_mfma_f32_16x16x32_bf16 v[114:117], v[202:205], v[240:243], v[114:117]
	v_mfma_f32_16x16x32_bf16 v[82:85], v[202:205], v[244:247], v[82:85]
	v_mfma_f32_16x16x32_bf16 v[50:53], v[202:205], v[248:251], v[50:53]
	v_mfma_f32_16x16x32_bf16 v[18:21], v[202:205], v[148:151], v[18:21]
	s_waitcnt lgkmcnt(0)
	s_waitcnt vmcnt(0)
	s_barrier
	s_add_i32 m0, s42, 0x0
	v_mfma_f32_16x16x32_bf16 v[110:113], v[206:209], v[240:243], v[110:113]
	global_load_lds_dwordx4 v152, s[38:39]
	ds_read_b128 v[174:177], v163
	v_mfma_f32_16x16x32_bf16 v[78:81], v[206:209], v[244:247], v[78:81]
	ds_read_b128 v[178:181], v163 offset:2048
	s_add_i32 m0, s42, 0x400
	v_mfma_f32_16x16x32_bf16 v[46:49], v[206:209], v[248:251], v[46:49]
	global_load_lds_dwordx4 v153, s[38:39]
	ds_read_b128 v[182:185], v163 offset:4096
	v_mfma_f32_16x16x32_bf16 v[14:17], v[206:209], v[148:151], v[14:17]
	ds_read_b128 v[186:189], v163 offset:6144
	s_add_i32 m0, s42, 0x800
	v_mfma_f32_16x16x32_bf16 v[106:109], v[216:219], v[240:243], v[106:109]
	global_load_lds_dwordx4 v154, s[38:39]
	ds_read_b128 v[190:193], v161
	v_mfma_f32_16x16x32_bf16 v[74:77], v[216:219], v[244:247], v[74:77]
	ds_read_b128 v[194:197], v161 offset:2048
	s_add_i32 m0, s42, 0xc00
	v_mfma_f32_16x16x32_bf16 v[42:45], v[216:219], v[248:251], v[42:45]
	global_load_lds_dwordx4 v155, s[38:39]
	ds_read_b128 v[198:201], v161 offset:4096
	v_mfma_f32_16x16x32_bf16 v[10:13], v[216:219], v[148:151], v[10:13]
	ds_read_b128 v[202:205], v161 offset:6144
	s_add_i32 m0, s42, 0x1000
	v_mfma_f32_16x16x32_bf16 v[102:105], v[220:223], v[240:243], v[102:105]
	global_load_lds_dwordx4 v156, s[38:39]
	v_mfma_f32_16x16x32_bf16 v[70:73], v[220:223], v[244:247], v[70:73]
	s_add_i32 m0, s42, 0x1400
	v_mfma_f32_16x16x32_bf16 v[38:41], v[220:223], v[248:251], v[38:41]
	global_load_lds_dwordx4 v157, s[38:39]
	v_mfma_f32_16x16x32_bf16 v[6:9], v[220:223], v[148:151], v[6:9]
	s_add_i32 m0, s42, 0x1800
	v_mfma_f32_16x16x32_bf16 v[98:101], v[224:227], v[240:243], v[98:101]
	global_load_lds_dwordx4 v158, s[38:39]
	v_mfma_f32_16x16x32_bf16 v[62:65], v[224:227], v[244:247], v[62:65]
	s_add_i32 m0, s42, 0x1c00
	v_mfma_f32_16x16x32_bf16 v[34:37], v[224:227], v[248:251], v[34:37]
	global_load_lds_dwordx4 v159, s[38:39]
	v_mfma_f32_16x16x32_bf16 v[2:5], v[224:227], v[148:151], v[2:5]
	s_add_u32 s38, s38, 0x80
	s_addc_u32 s39, s39, 0
	s_waitcnt lgkmcnt(0)
;     ...
;     const bool last = kt + 2 >= KT;
;     g_dma(last ? nbase : base, off, last ? 0 : (kt + 2) * kstep, buf0, w);
;     g_compute(buf1, ra, rb, acc);
;     asm volatile("s_waitcnt vmcnt(0)" ::: "memory");
;     __syncthreads();
	v_mfma_f32_16x16x32_bf16 v[126:129], v[190:193], v[174:177], v[126:129]
	v_mfma_f32_16x16x32_bf16 v[94:97], v[190:193], v[178:181], v[94:97]
	ds_read_b128 v[206:209], v161 offset:8192
	v_mfma_f32_16x16x32_bf16 v[66:69], v[190:193], v[182:185], v[66:69]
	v_mfma_f32_16x16x32_bf16 v[30:33], v[190:193], v[186:189], v[30:33]
	v_mfma_f32_16x16x32_bf16 v[122:125], v[194:197], v[174:177], v[122:125]
	ds_read_b128 v[216:219], v161 offset:10240
	v_mfma_f32_16x16x32_bf16 v[90:93], v[194:197], v[178:181], v[90:93]
	v_mfma_f32_16x16x32_bf16 v[58:61], v[194:197], v[182:185], v[58:61]
	v_mfma_f32_16x16x32_bf16 v[26:29], v[194:197], v[186:189], v[26:29]
	ds_read_b128 v[220:223], v161 offset:12288
	v_mfma_f32_16x16x32_bf16 v[118:121], v[198:201], v[174:177], v[118:121]
	v_mfma_f32_16x16x32_bf16 v[86:89], v[198:201], v[178:181], v[86:89]
	v_mfma_f32_16x16x32_bf16 v[54:57], v[198:201], v[182:185], v[54:57]
	ds_read_b128 v[224:227], v161 offset:14336
	v_mfma_f32_16x16x32_bf16 v[22:25], v[198:201], v[186:189], v[22:25]
	v_mfma_f32_16x16x32_bf16 v[114:117], v[202:205], v[174:177], v[114:117]
	v_mfma_f32_16x16x32_bf16 v[82:85], v[202:205], v[178:181], v[82:85]
	v_mfma_f32_16x16x32_bf16 v[50:53], v[202:205], v[182:185], v[50:53]
	v_mfma_f32_16x16x32_bf16 v[18:21], v[202:205], v[186:189], v[18:21]
	s_waitcnt lgkmcnt(0)
	v_mfma_f32_16x16x32_bf16 v[110:113], v[206:209], v[174:177], v[110:113]
	ds_read_b128 v[240:243], v163 offset:1024
	v_mfma_f32_16x16x32_bf16 v[78:81], v[206:209], v[178:181], v[78:81]
	v_mfma_f32_16x16x32_bf16 v[46:49], v[206:209], v[182:185], v[46:49]
	ds_read_b128 v[244:247], v163 offset:3072
	v_mfma_f32_16x16x32_bf16 v[14:17], v[206:209], v[186:189], v[14:17]
	v_mfma_f32_16x16x32_bf16 v[106:109], v[216:219], v[174:177], v[106:109]
	ds_read_b128 v[248:251], v163 offset:5120
	v_mfma_f32_16x16x32_bf16 v[74:77], v[216:219], v[178:181], v[74:77]
	v_mfma_f32_16x16x32_bf16 v[42:45], v[216:219], v[182:185], v[42:45]
	ds_read_b128 v[148:151], v163 offset:7168
	v_mfma_f32_16x16x32_bf16 v[10:13], v[216:219], v[186:189], v[10:13]
	v_mfma_f32_16x16x32_bf16 v[102:105], v[220:223], v[174:177], v[102:105]
	ds_read_b128 v[190:193], v161 offset:1024
	v_mfma_f32_16x16x32_bf16 v[70:73], v[220:223], v[178:181], v[70:73]
	ds_read_b128 v[194:197], v161 offset:3072
	v_mfma_f32_16x16x32_bf16 v[38:41], v[220:223], v[182:185], v[38:41]
	ds_read_b128 v[198:201], v161 offset:5120
	v_mfma_f32_16x16x32_bf16 v[6:9], v[220:223], v[186:189], v[6:9]
	ds_read_b128 v[202:205], v161 offset:7168
	v_mfma_f32_16x16x32_bf16 v[98:101], v[224:227], v[174:177], v[98:101]
	v_mfma_f32_16x16x32_bf16 v[62:65], v[224:227], v[178:181], v[62:65]
	v_mfma_f32_16x16x32_bf16 v[34:37], v[224:227], v[182:185], v[34:37]
	v_mfma_f32_16x16x32_bf16 v[2:5], v[224:227], v[186:189], v[2:5]
	s_waitcnt lgkmcnt(0)
	v_mfma_f32_16x16x32_bf16 v[126:129], v[190:193], v[240:243], v[126:129]
	v_mfma_f32_16x16x32_bf16 v[94:97], v[190:193], v[244:247], v[94:97]
	ds_read_b128 v[206:209], v161 offset:9216
	v_mfma_f32_16x16x32_bf16 v[66:69], v[190:193], v[248:251], v[66:69]
	v_mfma_f32_16x16x32_bf16 v[30:33], v[190:193], v[148:151], v[30:33]
	v_mfma_f32_16x16x32_bf16 v[122:125], v[194:197], v[240:243], v[122:125]
	ds_read_b128 v[216:219], v161 offset:11264
	v_mfma_f32_16x16x32_bf16 v[90:93], v[194:197], v[244:247], v[90:93]
	v_mfma_f32_16x16x32_bf16 v[58:61], v[194:197], v[248:251], v[58:61]
	v_mfma_f32_16x16x32_bf16 v[26:29], v[194:197], v[148:151], v[26:29]
	ds_read_b128 v[220:223], v161 offset:13312
	v_mfma_f32_16x16x32_bf16 v[118:121], v[198:201], v[240:243], v[118:121]
	v_mfma_f32_16x16x32_bf16 v[86:89], v[198:201], v[244:247], v[86:89]
	v_mfma_f32_16x16x32_bf16 v[54:57], v[198:201], v[248:251], v[54:57]
	ds_read_b128 v[224:227], v161 offset:15360
	v_mfma_f32_16x16x32_bf16 v[22:25], v[198:201], v[148:151], v[22:25]
	v_mfma_f32_16x16x32_bf16 v[114:117], v[202:205], v[240:243], v[114:117]
	v_mfma_f32_16x16x32_bf16 v[82:85], v[202:205], v[244:247], v[82:85]
	v_mfma_f32_16x16x32_bf16 v[50:53], v[202:205], v[248:251], v[50:53]
	v_mfma_f32_16x16x32_bf16 v[18:21], v[202:205], v[148:151], v[18:21]
	s_waitcnt lgkmcnt(0)
	s_waitcnt vmcnt(0)
	s_barrier
	s_add_i32 m0, s43, 0x0
	v_mfma_f32_16x16x32_bf16 v[110:113], v[206:209], v[240:243], v[110:113]
	global_load_lds_dwordx4 v152, s[38:39]
	ds_read_b128 v[174:177], v162
	v_mfma_f32_16x16x32_bf16 v[78:81], v[206:209], v[244:247], v[78:81]
	ds_read_b128 v[178:181], v162 offset:2048
	s_add_i32 m0, s43, 0x400
	v_mfma_f32_16x16x32_bf16 v[46:49], v[206:209], v[248:251], v[46:49]
	global_load_lds_dwordx4 v153, s[38:39]
	ds_read_b128 v[182:185], v162 offset:4096
	v_mfma_f32_16x16x32_bf16 v[14:17], v[206:209], v[148:151], v[14:17]
	ds_read_b128 v[186:189], v162 offset:6144
	s_add_i32 m0, s43, 0x800
	v_mfma_f32_16x16x32_bf16 v[106:109], v[216:219], v[240:243], v[106:109]
	global_load_lds_dwordx4 v154, s[38:39]
	ds_read_b128 v[190:193], v160
	v_mfma_f32_16x16x32_bf16 v[74:77], v[216:219], v[244:247], v[74:77]
	ds_read_b128 v[194:197], v160 offset:2048
	s_add_i32 m0, s43, 0xc00
	v_mfma_f32_16x16x32_bf16 v[42:45], v[216:219], v[248:251], v[42:45]
	global_load_lds_dwordx4 v155, s[38:39]
	ds_read_b128 v[198:201], v160 offset:4096
	v_mfma_f32_16x16x32_bf16 v[10:13], v[216:219], v[148:151], v[10:13]
	ds_read_b128 v[202:205], v160 offset:6144
	s_add_i32 m0, s43, 0x1000
	v_mfma_f32_16x16x32_bf16 v[102:105], v[220:223], v[240:243], v[102:105]
	global_load_lds_dwordx4 v156, s[38:39]
	v_mfma_f32_16x16x32_bf16 v[70:73], v[220:223], v[244:247], v[70:73]
	s_add_i32 m0, s43, 0x1400
	v_mfma_f32_16x16x32_bf16 v[38:41], v[220:223], v[248:251], v[38:41]
	global_load_lds_dwordx4 v157, s[38:39]
	v_mfma_f32_16x16x32_bf16 v[6:9], v[220:223], v[148:151], v[6:9]
	s_add_i32 m0, s43, 0x1800
	v_mfma_f32_16x16x32_bf16 v[98:101], v[224:227], v[240:243], v[98:101]
	global_load_lds_dwordx4 v158, s[38:39]
	v_mfma_f32_16x16x32_bf16 v[62:65], v[224:227], v[244:247], v[62:65]
	s_add_i32 m0, s43, 0x1c00
	v_mfma_f32_16x16x32_bf16 v[34:37], v[224:227], v[248:251], v[34:37]
	global_load_lds_dwordx4 v159, s[38:39]
	v_mfma_f32_16x16x32_bf16 v[2:5], v[224:227], v[148:151], v[2:5]
	s_add_u32 s38, s38, 0x80
	s_addc_u32 s39, s39, 0
	s_add_i32 s48, s48, 1
	s_cmp_lt_u32 s48, 3
	s_cbranch_scc1 .LgD_loop
;     ...
;   for (int kt = 0; kt < KT; kt += 2) {
;     g_dma(base, off, (kt + 1) * kstep, buf1, w);
;     g_compute(buf0, ra, rb, acc);
;     asm volatile("s_waitcnt vmcnt(0)" ::: "memory");
;     __syncthreads();
;     const bool last = kt + 2 >= KT;
;     g_dma(last ? nbase : base, off, last ? 0 : (kt + 2) * kstep, buf0, w);
	s_waitcnt lgkmcnt(0)
	v_mfma_f32_16x16x32_bf16 v[126:129], v[190:193], v[174:177], v[126:129]
	v_mfma_f32_16x16x32_bf16 v[94:97], v[190:193], v[178:181], v[94:97]
	ds_read_b128 v[206:209], v160 offset:8192
	v_mfma_f32_16x16x32_bf16 v[66:69], v[190:193], v[182:185], v[66:69]
	v_mfma_f32_16x16x32_bf16 v[30:33], v[190:193], v[186:189], v[30:33]
	v_mfma_f32_16x16x32_bf16 v[122:125], v[194:197], v[174:177], v[122:125]
	ds_read_b128 v[216:219], v160 offset:10240
	v_mfma_f32_16x16x32_bf16 v[90:93], v[194:197], v[178:181], v[90:93]
	v_mfma_f32_16x16x32_bf16 v[58:61], v[194:197], v[182:185], v[58:61]
	v_mfma_f32_16x16x32_bf16 v[26:29], v[194:197], v[186:189], v[26:29]
	ds_read_b128 v[220:223], v160 offset:12288
	v_mfma_f32_16x16x32_bf16 v[118:121], v[198:201], v[174:177], v[118:121]
	v_mfma_f32_16x16x32_bf16 v[86:89], v[198:201], v[178:181], v[86:89]
	v_mfma_f32_16x16x32_bf16 v[54:57], v[198:201], v[182:185], v[54:57]
	ds_read_b128 v[224:227], v160 offset:14336
	v_mfma_f32_16x16x32_bf16 v[22:25], v[198:201], v[186:189], v[22:25]
	v_mfma_f32_16x16x32_bf16 v[114:117], v[202:205], v[174:177], v[114:117]
	v_mfma_f32_16x16x32_bf16 v[82:85], v[202:205], v[178:181], v[82:85]
	v_mfma_f32_16x16x32_bf16 v[50:53], v[202:205], v[182:185], v[50:53]
	v_mfma_f32_16x16x32_bf16 v[18:21], v[202:205], v[186:189], v[18:21]
	s_waitcnt lgkmcnt(0)
	v_mfma_f32_16x16x32_bf16 v[110:113], v[206:209], v[174:177], v[110:113]
	ds_read_b128 v[240:243], v162 offset:1024
	v_mfma_f32_16x16x32_bf16 v[78:81], v[206:209], v[178:181], v[78:81]
	v_mfma_f32_16x16x32_bf16 v[46:49], v[206:209], v[182:185], v[46:49]
	ds_read_b128 v[244:247], v162 offset:3072
	v_mfma_f32_16x16x32_bf16 v[14:17], v[206:209], v[186:189], v[14:17]
	v_mfma_f32_16x16x32_bf16 v[106:109], v[216:219], v[174:177], v[106:109]
	ds_read_b128 v[248:251], v162 offset:5120
	v_mfma_f32_16x16x32_bf16 v[74:77], v[216:219], v[178:181], v[74:77]
	v_mfma_f32_16x16x32_bf16 v[42:45], v[216:219], v[182:185], v[42:45]
	ds_read_b128 v[148:151], v162 offset:7168
	v_mfma_f32_16x16x32_bf16 v[10:13], v[216:219], v[186:189], v[10:13]
	v_mfma_f32_16x16x32_bf16 v[102:105], v[220:223], v[174:177], v[102:105]
	ds_read_b128 v[190:193], v160 offset:1024
	v_mfma_f32_16x16x32_bf16 v[70:73], v[220:223], v[178:181], v[70:73]
	ds_read_b128 v[194:197], v160 offset:3072
	v_mfma_f32_16x16x32_bf16 v[38:41], v[220:223], v[182:185], v[38:41]
	ds_read_b128 v[198:201], v160 offset:5120
	v_mfma_f32_16x16x32_bf16 v[6:9], v[220:223], v[186:189], v[6:9]
	ds_read_b128 v[202:205], v160 offset:7168
	v_mfma_f32_16x16x32_bf16 v[98:101], v[224:227], v[174:177], v[98:101]
	v_mfma_f32_16x16x32_bf16 v[62:65], v[224:227], v[178:181], v[62:65]
	v_mfma_f32_16x16x32_bf16 v[34:37], v[224:227], v[182:185], v[34:37]
	v_mfma_f32_16x16x32_bf16 v[2:5], v[224:227], v[186:189], v[2:5]
	s_waitcnt lgkmcnt(0)
	v_mfma_f32_16x16x32_bf16 v[126:129], v[190:193], v[240:243], v[126:129]
	v_mfma_f32_16x16x32_bf16 v[94:97], v[190:193], v[244:247], v[94:97]
	ds_read_b128 v[206:209], v160 offset:9216
	v_mfma_f32_16x16x32_bf16 v[66:69], v[190:193], v[248:251], v[66:69]
	v_mfma_f32_16x16x32_bf16 v[30:33], v[190:193], v[148:151], v[30:33]
	v_mfma_f32_16x16x32_bf16 v[122:125], v[194:197], v[240:243], v[122:125]
	ds_read_b128 v[216:219], v160 offset:11264
	v_mfma_f32_16x16x32_bf16 v[90:93], v[194:197], v[244:247], v[90:93]
	v_mfma_f32_16x16x32_bf16 v[58:61], v[194:197], v[248:251], v[58:61]
	v_mfma_f32_16x16x32_bf16 v[26:29], v[194:197], v[148:151], v[26:29]
	ds_read_b128 v[220:223], v160 offset:13312
	v_mfma_f32_16x16x32_bf16 v[118:121], v[198:201], v[240:243], v[118:121]
	v_mfma_f32_16x16x32_bf16 v[86:89], v[198:201], v[244:247], v[86:89]
	v_mfma_f32_16x16x32_bf16 v[54:57], v[198:201], v[248:251], v[54:57]
	ds_read_b128 v[224:227], v160 offset:15360
	v_mfma_f32_16x16x32_bf16 v[22:25], v[198:201], v[148:151], v[22:25]
	v_mfma_f32_16x16x32_bf16 v[114:117], v[202:205], v[240:243], v[114:117]
	v_mfma_f32_16x16x32_bf16 v[82:85], v[202:205], v[244:247], v[82:85]
	v_mfma_f32_16x16x32_bf16 v[50:53], v[202:205], v[248:251], v[50:53]
	v_mfma_f32_16x16x32_bf16 v[18:21], v[202:205], v[148:151], v[18:21]
	s_waitcnt lgkmcnt(0)
	s_waitcnt vmcnt(0)
	s_barrier
	s_add_i32 m0, s42, 0x0
	v_mfma_f32_16x16x32_bf16 v[110:113], v[206:209], v[240:243], v[110:113]
	global_load_lds_dwordx4 v152, s[40:41]
	ds_read_b128 v[174:177], v163
	v_mfma_f32_16x16x32_bf16 v[78:81], v[206:209], v[244:247], v[78:81]
	ds_read_b128 v[178:181], v163 offset:2048
	s_add_i32 m0, s42, 0x400
	v_mfma_f32_16x16x32_bf16 v[46:49], v[206:209], v[248:251], v[46:49]
	global_load_lds_dwordx4 v153, s[40:41]
	ds_read_b128 v[182:185], v163 offset:4096
	v_mfma_f32_16x16x32_bf16 v[14:17], v[206:209], v[148:151], v[14:17]
	ds_read_b128 v[186:189], v163 offset:6144
	s_add_i32 m0, s42, 0x800
	v_mfma_f32_16x16x32_bf16 v[106:109], v[216:219], v[240:243], v[106:109]
	global_load_lds_dwordx4 v154, s[40:41]
	ds_read_b128 v[190:193], v161
	v_mfma_f32_16x16x32_bf16 v[74:77], v[216:219], v[244:247], v[74:77]
	ds_read_b128 v[194:197], v161 offset:2048
	s_add_i32 m0, s42, 0xc00
	v_mfma_f32_16x16x32_bf16 v[42:45], v[216:219], v[248:251], v[42:45]
	global_load_lds_dwordx4 v155, s[40:41]
	ds_read_b128 v[198:201], v161 offset:4096
	v_mfma_f32_16x16x32_bf16 v[10:13], v[216:219], v[148:151], v[10:13]
	ds_read_b128 v[202:205], v161 offset:6144
	s_add_i32 m0, s42, 0x1000
	v_mfma_f32_16x16x32_bf16 v[102:105], v[220:223], v[240:243], v[102:105]
	global_load_lds_dwordx4 v156, s[40:41]
	v_mfma_f32_16x16x32_bf16 v[70:73], v[220:223], v[244:247], v[70:73]
	s_add_i32 m0, s42, 0x1400
	v_mfma_f32_16x16x32_bf16 v[38:41], v[220:223], v[248:251], v[38:41]
	global_load_lds_dwordx4 v157, s[40:41]
	v_mfma_f32_16x16x32_bf16 v[6:9], v[220:223], v[148:151], v[6:9]
	s_add_i32 m0, s42, 0x1800
	v_mfma_f32_16x16x32_bf16 v[98:101], v[224:227], v[240:243], v[98:101]
	global_load_lds_dwordx4 v158, s[40:41]
	v_mfma_f32_16x16x32_bf16 v[62:65], v[224:227], v[244:247], v[62:65]
	s_add_i32 m0, s42, 0x1c00
	v_mfma_f32_16x16x32_bf16 v[34:37], v[224:227], v[248:251], v[34:37]
	global_load_lds_dwordx4 v159, s[40:41]
	v_mfma_f32_16x16x32_bf16 v[2:5], v[224:227], v[148:151], v[2:5]
	s_add_u32 s40, s40, 0x80
	s_addc_u32 s41, s41, 0
	s_waitcnt lgkmcnt(0)
; DI unsigned pk2(float lo, float hi) { f32x2 v = {lo, hi}; bf16x2_t b = __builtin_convertvector(v, bf16x2_t); return __builtin_bit_cast(unsigned, b); }
; DI float bflo(unsigned u) { return __uint_as_float(u << 16); }
; DI float bfhi(unsigned u) { return __uint_as_float(u & 0xffff0000u); }
; DI int my_tid() { int t = threadIdx.x; asm volatile("" : "+v"(t)); return t; }
;     ...
;     g_compute(buf1, ra, rb, acc);
;     asm volatile("s_waitcnt vmcnt(0)" ::: "memory");
;     __syncthreads();
; DI void phaseD(const Params& p0, const Slot sl, int layer, unsigned char* lds) {
;     ...
;       const int tid = my_tid(), lane = tid & 63, w = tid >> 6, wa = w >> 2, wb = w & 3, qi = lane & 15, quad = lane >> 4;
; #pragma unroll
;       for (int j = 0; j < 4; ++j) {
;         const long tok = (long)mt * 256 + wb * 64 + j * 16 + qi;
; #pragma unroll
;         for (int i = 0; i < 8; ++i) {
;           const long off = tok * 1024 + nt * 256 + wa * 128 + i * 16 + quad * 4;
;           const u32x2 xg = *(const u32x2*)(Gg + off);
;           const f32x4 v = acc[i][j];
;           float o0 = bflo(xg[0]) * v[0], o1 = bfhi(xg[0]) * v[1], o2 = bflo(xg[1]) * v[2], o3 = bfhi(xg[1]) * v[3];
;           if (which) { const u32x2 a = *(const u32x2*)(p.merged() + off); o0 += bflo(a[0]); o1 += bfhi(a[0]); o2 += bflo(a[1]); o3 += bfhi(a[1]); }
;           *(u32x2*)(p.merged() + off) = (u32x2){pk2(o0, o1), pk2(o2, o3)};
	v_mfma_f32_16x16x32_bf16 v[126:129], v[190:193], v[174:177], v[126:129]
	v_mfma_f32_16x16x32_bf16 v[94:97], v[190:193], v[178:181], v[94:97]
	ds_read_b128 v[206:209], v161 offset:8192
	v_mfma_f32_16x16x32_bf16 v[66:69], v[190:193], v[182:185], v[66:69]
	v_mfma_f32_16x16x32_bf16 v[30:33], v[190:193], v[186:189], v[30:33]
	v_mfma_f32_16x16x32_bf16 v[122:125], v[194:197], v[174:177], v[122:125]
	ds_read_b128 v[216:219], v161 offset:10240
	v_mfma_f32_16x16x32_bf16 v[90:93], v[194:197], v[178:181], v[90:93]
	v_mfma_f32_16x16x32_bf16 v[58:61], v[194:197], v[182:185], v[58:61]
	v_mfma_f32_16x16x32_bf16 v[26:29], v[194:197], v[186:189], v[26:29]
	ds_read_b128 v[220:223], v161 offset:12288
	v_mfma_f32_16x16x32_bf16 v[118:121], v[198:201], v[174:177], v[118:121]
	v_mfma_f32_16x16x32_bf16 v[86:89], v[198:201], v[178:181], v[86:89]
	v_mfma_f32_16x16x32_bf16 v[54:57], v[198:201], v[182:185], v[54:57]
	ds_read_b128 v[224:227], v161 offset:14336
	v_mfma_f32_16x16x32_bf16 v[22:25], v[198:201], v[186:189], v[22:25]
	v_mfma_f32_16x16x32_bf16 v[114:117], v[202:205], v[174:177], v[114:117]
	v_mfma_f32_16x16x32_bf16 v[82:85], v[202:205], v[178:181], v[82:85]
	v_mfma_f32_16x16x32_bf16 v[50:53], v[202:205], v[182:185], v[50:53]
	v_mfma_f32_16x16x32_bf16 v[18:21], v[202:205], v[186:189], v[18:21]
	s_waitcnt lgkmcnt(0)
	v_mfma_f32_16x16x32_bf16 v[110:113], v[206:209], v[174:177], v[110:113]
	ds_read_b128 v[240:243], v163 offset:1024
	v_mfma_f32_16x16x32_bf16 v[78:81], v[206:209], v[178:181], v[78:81]
	v_mfma_f32_16x16x32_bf16 v[46:49], v[206:209], v[182:185], v[46:49]
	ds_read_b128 v[244:247], v163 offset:3072
	v_mfma_f32_16x16x32_bf16 v[14:17], v[206:209], v[186:189], v[14:17]
	v_mfma_f32_16x16x32_bf16 v[106:109], v[216:219], v[174:177], v[106:109]
	ds_read_b128 v[248:251], v163 offset:5120
	v_mfma_f32_16x16x32_bf16 v[74:77], v[216:219], v[178:181], v[74:77]
	v_mfma_f32_16x16x32_bf16 v[42:45], v[216:219], v[182:185], v[42:45]
	ds_read_b128 v[148:151], v163 offset:7168
	v_mfma_f32_16x16x32_bf16 v[10:13], v[216:219], v[186:189], v[10:13]
	v_mfma_f32_16x16x32_bf16 v[102:105], v[220:223], v[174:177], v[102:105]
	ds_read_b128 v[190:193], v161 offset:1024
	v_mfma_f32_16x16x32_bf16 v[70:73], v[220:223], v[178:181], v[70:73]
	ds_read_b128 v[194:197], v161 offset:3072
	v_mfma_f32_16x16x32_bf16 v[38:41], v[220:223], v[182:185], v[38:41]
	ds_read_b128 v[198:201], v161 offset:5120
	v_mfma_f32_16x16x32_bf16 v[6:9], v[220:223], v[186:189], v[6:9]
	ds_read_b128 v[202:205], v161 offset:7168
	v_mfma_f32_16x16x32_bf16 v[98:101], v[224:227], v[174:177], v[98:101]
	v_mfma_f32_16x16x32_bf16 v[62:65], v[224:227], v[178:181], v[62:65]
	v_mfma_f32_16x16x32_bf16 v[34:37], v[224:227], v[182:185], v[34:37]
	v_mfma_f32_16x16x32_bf16 v[2:5], v[224:227], v[186:189], v[2:5]
	s_waitcnt lgkmcnt(0)
	v_mfma_f32_16x16x32_bf16 v[126:129], v[190:193], v[240:243], v[126:129]
	v_mfma_f32_16x16x32_bf16 v[94:97], v[190:193], v[244:247], v[94:97]
	ds_read_b128 v[206:209], v161 offset:9216
	v_mfma_f32_16x16x32_bf16 v[66:69], v[190:193], v[248:251], v[66:69]
	v_mfma_f32_16x16x32_bf16 v[30:33], v[190:193], v[148:151], v[30:33]
	v_mfma_f32_16x16x32_bf16 v[122:125], v[194:197], v[240:243], v[122:125]
	ds_read_b128 v[216:219], v161 offset:11264
	v_mfma_f32_16x16x32_bf16 v[90:93], v[194:197], v[244:247], v[90:93]
	v_mfma_f32_16x16x32_bf16 v[58:61], v[194:197], v[248:251], v[58:61]
	v_mfma_f32_16x16x32_bf16 v[26:29], v[194:197], v[148:151], v[26:29]
	ds_read_b128 v[220:223], v161 offset:13312
	v_mfma_f32_16x16x32_bf16 v[118:121], v[198:201], v[240:243], v[118:121]
	v_mfma_f32_16x16x32_bf16 v[86:89], v[198:201], v[244:247], v[86:89]
	v_mfma_f32_16x16x32_bf16 v[54:57], v[198:201], v[248:251], v[54:57]
	ds_read_b128 v[224:227], v161 offset:15360
	v_mfma_f32_16x16x32_bf16 v[22:25], v[198:201], v[148:151], v[22:25]
	v_mfma_f32_16x16x32_bf16 v[114:117], v[202:205], v[240:243], v[114:117]
	v_mfma_f32_16x16x32_bf16 v[82:85], v[202:205], v[244:247], v[82:85]
	v_mfma_f32_16x16x32_bf16 v[50:53], v[202:205], v[248:251], v[50:53]
	v_mfma_f32_16x16x32_bf16 v[18:21], v[202:205], v[148:151], v[18:21]
	s_waitcnt lgkmcnt(0)
	s_waitcnt vmcnt(0)
	s_barrier
	v_mfma_f32_16x16x32_bf16 v[110:113], v[206:209], v[240:243], v[110:113]
	v_mfma_f32_16x16x32_bf16 v[78:81], v[206:209], v[244:247], v[78:81]
	v_mfma_f32_16x16x32_bf16 v[46:49], v[206:209], v[248:251], v[46:49]
	v_mfma_f32_16x16x32_bf16 v[14:17], v[206:209], v[148:151], v[14:17]
	v_mfma_f32_16x16x32_bf16 v[106:109], v[216:219], v[240:243], v[106:109]
	v_mfma_f32_16x16x32_bf16 v[74:77], v[216:219], v[244:247], v[74:77]
	v_mfma_f32_16x16x32_bf16 v[42:45], v[216:219], v[248:251], v[42:45]
	v_mfma_f32_16x16x32_bf16 v[10:13], v[216:219], v[148:151], v[10:13]
	v_mfma_f32_16x16x32_bf16 v[102:105], v[220:223], v[240:243], v[102:105]
	v_mfma_f32_16x16x32_bf16 v[70:73], v[220:223], v[244:247], v[70:73]
	v_mfma_f32_16x16x32_bf16 v[38:41], v[220:223], v[248:251], v[38:41]
	v_mfma_f32_16x16x32_bf16 v[6:9], v[220:223], v[148:151], v[6:9]
	v_mfma_f32_16x16x32_bf16 v[98:101], v[224:227], v[240:243], v[98:101]
	v_mfma_f32_16x16x32_bf16 v[62:65], v[224:227], v[244:247], v[62:65]
	v_mfma_f32_16x16x32_bf16 v[34:37], v[224:227], v[248:251], v[34:37]
	v_mfma_f32_16x16x32_bf16 v[2:5], v[224:227], v[148:151], v[2:5]
	s_nop 7
	s_nop 3
	v_mov_b32_e32 v0, v210
	s_and_b64 s[0:1], s[16:17], exec
	v_and_b32_e32 v131, 0xc0, v0
	v_and_b32_e32 v133, 15, v0
	v_or3_b32 v142, v138, v131, v133
	v_ashrrev_i32_e32 v131, 1, v0
	v_and_b32_e32 v144, 0xffffff80, v131
	s_mov_b32 s0, 0x19570000
	v_ashrrev_i32_e32 v145, 31, v144
	s_cselect_b32 s0, 0x15570000, s0
	v_mov_b32_e32 v143, v139
	v_lshl_add_u64 v[144:145], v[144:145], 0, v[140:141]
	v_lshrrev_b32_e32 v0, 2, v0
	s_add_u32 s0, s4, s0
	v_and_or_b32 v144, v0, 12, v144
	v_lshlrev_b64 v[142:143], 10, v[142:143]
	s_addc_u32 s1, s5, 0
	v_lshl_add_u64 v[142:143], v[144:145], 0, v[142:143]
	v_lshl_add_u64 v[144:145], v[142:143], 1, s[0:1]
	global_load_dwordx2 v[146:147], v[144:145], off
	v_cndmask_b32_e64 v0, 0, 1, s[14:15]
	v_cmp_ne_u32_e64 s[48:49], 1, v0
	s_andn2_b64 vcc, exec, s[14:15]
	s_waitcnt vmcnt(0)
	v_lshlrev_b32_e32 v148, 16, v146
	v_and_b32_e32 v149, 0xffff0000, v146
	v_lshlrev_b32_e32 v146, 16, v147
	v_and_b32_e32 v147, 0xffff0000, v147
	v_pk_mul_f32 v[126:127], v[126:127], v[148:149]
	v_pk_mul_f32 v[128:129], v[128:129], v[146:147]
	v_lshl_add_u64 v[146:147], v[142:143], 1, s[10:11]
	s_cbranch_vccnz .LBB0_842
	global_load_dwordx2 v[148:149], v[146:147], off
	s_waitcnt vmcnt(0)
	v_lshlrev_b32_e32 v150, 16, v148
	v_and_b32_e32 v151, 0xffff0000, v148
	v_lshlrev_b32_e32 v148, 16, v149
	v_and_b32_e32 v149, 0xffff0000, v149
	v_pk_add_f32 v[126:127], v[126:127], v[150:151]
	v_pk_add_f32 v[128:129], v[128:129], v[148:149]

; DI int my_tid() { int t = threadIdx.x; asm volatile("" : "+v"(t)); return t; }
;     ...
;   const int tid = my_tid(), lane = tid & 63, w = __builtin_amdgcn_readfirstlane(tid >> 6), wa = w >> 2, wb = w & 3, qi = lane & 15, quad = lane >> 4;
;   const bf16_t* base = w >= 4 ? Bg : Ag; const int ld = (int)(w >= 4 ? ldb : lda);
;   const bf16_t* nbase = nAg ? (w >= 4 ? nBg : nAg) : base;
;   unsigned off[8];
; #pragma unroll
;   for (int u = 0; u < 8; ++u) {
;     const int blk = (w & 3) * 8 + u, rg = blk >> 1, kh = blk & 1;
;     int R = rg * 16 + (lane >> 2);
;     if (perm) { const int rho = R & 31; R = (R & ~31) + ((rho >> 2) & 3) * 8 + (rho >> 4) * 4 + (rho & 3); }
;     off[u] = (unsigned)(R * ld + kh * 32 + (lane & 3) * 8);
;   }
;   const int ra = (wa * 8) * 2 * 1024 + (qi * 4 + quad) * 16, rb = (wb * 4) * 2 * 1024 + (qi * 4 + quad) * 16;
;   unsigned char* buf0 = lds; unsigned char* buf1 = lds + STAGE_B;
;   const int KT = K >> 6;
;   if (!pre) {
;     g_dma(base, off, 0, buf0, w);
;     asm volatile("s_waitcnt vmcnt(0)" ::: "memory");
;     __syncthreads();
;   }
; DI void phaseE(const Params& p0, const Slot sl, int layer, unsigned char* lds, const float* xsrc) {
;     ...
;     const bf16_t* Wg = p.wout_t() + ((long)nt * 256) * 1024; const bf16_t* Mg = p.merged() + (long)mt * 256 * 1024;
;     gemm_core(Wg, 1024, Mg, 1024, 1024, gl, acc, 64, it > 0, more ? p.wout_t() + ((long)nt2 * 256) * 1024 : Wg, more ? p.merged() + (long)mt2 * 256 * 1024 : Mg);
.LBB0_968:
	v_ashrrev_i32_e32 v131, 31, v130
	v_lshlrev_b64 v[10:11], 19, v[130:131]
	v_lshl_add_u64 v[10:11], s[0:1], 0, v[10:11]
	v_ashrrev_i32_e32 v133, 31, v132
	v_cndmask_b32_e64 v0, v4, v10, s[8:9]
	v_cndmask_b32_e64 v9, v5, v11, s[8:9]
	v_lshlrev_b64 v[4:5], 19, v[132:133]
	s_and_b64 s[10:11], exec, s[10:11]
	v_lshl_add_u64 v[4:5], s[4:5], 0, v[4:5]
	s_or_b64 s[18:19], s[10:11], s[18:19]
	v_cndmask_b32_e64 v2, v2, v4, s[8:9]
	v_cndmask_b32_e64 v3, v3, v5, s[8:9]
	v_and_b32_e32 v4, 48, v8
	v_cndmask_b32_e64 v142, v0, v2, s[12:13]
	s_lshl_b32 s8, s36, 6
	v_lshlrev_b32_e32 v0, 6, v8
	s_movk_i32 s9, 0x3c0
	s_and_b32 s8, s8, 0xffffc000
	v_and_or_b32 v0, v0, s9, v4
	v_or_b32_e32 v133, s8, v0
	s_add_i32 s8, s29, 0xc020
	v_lshl_or_b32 v166, s30, 13, v0
	v_add_u32_e32 v0, s8, v7
	v_add_lshl_u32 v0, v0, v6, 1
	s_add_i32 s8, s29, 0xc000
	v_lshl_add_u64 v[144:145], v[0:1], 0, s[6:7]
	v_add_u32_e32 v0, s8, v7
	v_add_lshl_u32 v0, v0, v6, 1
	s_add_i32 s8, s29, 0x8020
	v_lshl_add_u64 v[146:147], v[0:1], 0, s[6:7]
	v_add_u32_e32 v0, s8, v7
	v_add_lshl_u32 v0, v0, v6, 1
	s_add_i32 s8, s29, 0x8000
	v_lshl_add_u64 v[148:149], v[0:1], 0, s[6:7]
	v_add_u32_e32 v0, s8, v7
	v_add_lshl_u32 v0, v0, v6, 1
	s_add_i32 s8, s29, 0x4020
	v_lshl_add_u64 v[150:151], v[0:1], 0, s[6:7]
	v_add_u32_e32 v0, s8, v7
	v_add_lshl_u32 v0, v0, v6, 1
	s_add_i32 s8, s29, 0x4000
	v_lshl_add_u64 v[152:153], v[0:1], 0, s[6:7]
	v_add_u32_e32 v0, s8, v7
	v_add_lshl_u32 v0, v0, v6, 1
	v_lshl_add_u64 v[154:155], v[0:1], 0, s[6:7]
	v_add3_u32 v0, s29, 32, v7
	v_add_lshl_u32 v0, v0, v6, 1
	v_lshl_add_u64 v[156:157], v[0:1], 0, s[6:7]
	v_add_u32_e32 v0, s29, v7
	v_add_lshl_u32 v0, v0, v6, 1
	v_mov_b32_e32 v2, 0
	v_cndmask_b32_e64 v131, v9, v3, s[12:13]
	v_lshl_add_u64 v[158:159], v[0:1], 0, s[6:7]
	s_mov_b32 s9, 0
	s_movk_i32 s8, 0x80
	v_mov_b32_e32 v3, v2
	v_mov_b32_e32 v4, v2
	v_mov_b32_e32 v5, v2
	v_mov_b32_e32 v26, v2
	v_mov_b32_e32 v27, v2
	v_mov_b32_e32 v28, v2
	v_mov_b32_e32 v29, v2
	v_mov_b32_e32 v58, v2
	v_mov_b32_e32 v59, v2
	v_mov_b32_e32 v60, v2
	v_mov_b32_e32 v61, v2
	v_mov_b32_e32 v90, v2
	v_mov_b32_e32 v91, v2
	v_mov_b32_e32 v92, v2
	v_mov_b32_e32 v93, v2
	v_mov_b32_e32 v6, v2
	v_mov_b32_e32 v7, v2
	v_mov_b32_e32 v8, v2
	v_mov_b32_e32 v9, v2
	v_mov_b32_e32 v38, v2
	v_mov_b32_e32 v39, v2
	v_mov_b32_e32 v40, v2
	v_mov_b32_e32 v41, v2
	v_mov_b32_e32 v70, v2
	v_mov_b32_e32 v71, v2
	v_mov_b32_e32 v72, v2
	v_mov_b32_e32 v73, v2
	v_mov_b32_e32 v102, v2
	v_mov_b32_e32 v103, v2
	v_mov_b32_e32 v104, v2
	v_mov_b32_e32 v105, v2
	v_mov_b32_e32 v10, v2
	v_mov_b32_e32 v11, v2
	v_mov_b32_e32 v12, v2
	v_mov_b32_e32 v13, v2
	v_mov_b32_e32 v42, v2
	v_mov_b32_e32 v43, v2
	v_mov_b32_e32 v44, v2
	v_mov_b32_e32 v45, v2
	v_mov_b32_e32 v74, v2
	v_mov_b32_e32 v75, v2
	v_mov_b32_e32 v76, v2
	v_mov_b32_e32 v77, v2
	v_mov_b32_e32 v106, v2
	v_mov_b32_e32 v107, v2
	v_mov_b32_e32 v108, v2
	v_mov_b32_e32 v109, v2
	v_mov_b32_e32 v14, v2
	v_mov_b32_e32 v15, v2
	v_mov_b32_e32 v16, v2
	v_mov_b32_e32 v17, v2
	v_mov_b32_e32 v46, v2
	v_mov_b32_e32 v47, v2
	v_mov_b32_e32 v48, v2
	v_mov_b32_e32 v49, v2
	v_mov_b32_e32 v78, v2
	v_mov_b32_e32 v79, v2
	v_mov_b32_e32 v80, v2
	v_mov_b32_e32 v81, v2
	v_mov_b32_e32 v110, v2
	v_mov_b32_e32 v111, v2
	v_mov_b32_e32 v112, v2
	v_mov_b32_e32 v113, v2
	v_mov_b32_e32 v18, v2
	v_mov_b32_e32 v19, v2
	v_mov_b32_e32 v20, v2
	v_mov_b32_e32 v21, v2
	v_mov_b32_e32 v50, v2
	v_mov_b32_e32 v51, v2
	v_mov_b32_e32 v52, v2
	v_mov_b32_e32 v53, v2
	v_mov_b32_e32 v82, v2
	v_mov_b32_e32 v83, v2
	v_mov_b32_e32 v84, v2
	v_mov_b32_e32 v85, v2
	v_mov_b32_e32 v114, v2
	v_mov_b32_e32 v115, v2
	v_mov_b32_e32 v116, v2
	v_mov_b32_e32 v117, v2
	s_waitcnt vmcnt(0)
	v_mov_b32_e32 v22, v2
	v_mov_b32_e32 v23, v2
	v_mov_b32_e32 v24, v2
	v_mov_b32_e32 v25, v2
	v_mov_b32_e32 v54, v2
	v_mov_b32_e32 v55, v2
	v_mov_b32_e32 v56, v2
	v_mov_b32_e32 v57, v2
	v_mov_b32_e32 v86, v2
	v_mov_b32_e32 v87, v2
	v_mov_b32_e32 v88, v2
	v_mov_b32_e32 v89, v2
	v_mov_b32_e32 v118, v2
	v_mov_b32_e32 v119, v2
	v_mov_b32_e32 v120, v2
	v_mov_b32_e32 v121, v2
	v_mov_b32_e32 v30, v2
	v_mov_b32_e32 v31, v2
	v_mov_b32_e32 v32, v2
	v_mov_b32_e32 v33, v2
	v_mov_b32_e32 v62, v2
	v_mov_b32_e32 v63, v2
	v_mov_b32_e32 v64, v2
	v_mov_b32_e32 v65, v2
	v_mov_b32_e32 v94, v2
	v_mov_b32_e32 v95, v2
	v_mov_b32_e32 v96, v2
	v_mov_b32_e32 v97, v2
	v_mov_b32_e32 v122, v2
	v_mov_b32_e32 v123, v2
	v_mov_b32_e32 v124, v2
	v_mov_b32_e32 v125, v2
	v_mov_b32_e32 v34, v2
	v_mov_b32_e32 v35, v2
	v_mov_b32_e32 v36, v2
	v_mov_b32_e32 v37, v2
	v_mov_b32_e32 v66, v2
	v_mov_b32_e32 v67, v2
	v_mov_b32_e32 v68, v2
	v_mov_b32_e32 v69, v2
	v_mov_b32_e32 v98, v2
	v_mov_b32_e32 v99, v2
	v_mov_b32_e32 v100, v2
	v_mov_b32_e32 v101, v2
	v_mov_b32_e32 v126, v2
	v_mov_b32_e32 v127, v2
	v_mov_b32_e32 v128, v2
	v_mov_b32_e32 v129, v2
	v_lshlrev_b32_e32 v144, 1, v135
	v_add_u32_e32 v152, 32, v133
	v_add_u32_e32 v153, 0x10020, v133
	v_add_u32_e32 v154, 0x8020, v166
	v_add_u32_e32 v155, 0x18020, v166
	v_readfirstlane_b32 s38, v138
	v_readfirstlane_b32 s39, v139
	v_readfirstlane_b32 s40, v142
	v_readfirstlane_b32 s41, v131
	v_add_u32_e32 v145, 0x40, v144
	v_add_u32_e32 v146, 0x8000, v144
	v_add_u32_e32 v147, 0x8040, v144
	v_add_u32_e32 v148, 0x10000, v144
	v_add_u32_e32 v149, 0x10040, v144
	v_add_u32_e32 v150, 0x18000, v144
	v_add_u32_e32 v151, 0x18040, v144
	s_add_i32 s42, s28, 32
	s_add_i32 s43, s28, s35
	s_add_u32 s38, s38, 0x80
	s_addc_u32 s39, s39, 0
	s_add_i32 m0, s43, 0x0
	s_nop 0
	global_load_lds_dwordx4 v144, s[38:39]
	s_add_i32 m0, s43, 0x400
	s_nop 0
	global_load_lds_dwordx4 v145, s[38:39]
	s_add_i32 m0, s43, 0x800
	s_nop 0
	global_load_lds_dwordx4 v146, s[38:39]
	s_add_i32 m0, s43, 0xc00
	s_nop 0
	global_load_lds_dwordx4 v147, s[38:39]
	s_add_i32 m0, s43, 0x1000
	s_nop 0
	global_load_lds_dwordx4 v148, s[38:39]
	s_add_i32 m0, s43, 0x1400
	s_nop 0
	global_load_lds_dwordx4 v149, s[38:39]
	s_add_i32 m0, s43, 0x1800
	s_nop 0
	global_load_lds_dwordx4 v150, s[38:39]
	s_add_i32 m0, s43, 0x1c00
	s_nop 0
	global_load_lds_dwordx4 v151, s[38:39]
	s_add_u32 s38, s38, 0x80
	s_addc_u32 s39, s39, 0
	ds_read_b128 v[168:171], v154
	ds_read_b128 v[172:175], v154 offset:2048
	ds_read_b128 v[176:179], v154 offset:4096
	ds_read_b128 v[180:183], v154 offset:6144
	ds_read_b128 v[184:187], v152
	ds_read_b128 v[188:191], v152 offset:2048
	ds_read_b128 v[192:195], v152 offset:4096
	ds_read_b128 v[196:199], v152 offset:6144
	s_mov_b32 s46, 0
; #define G_LDA(dst, ih, ks) _Pragma("unroll") for (int i = 0; i < 4; ++i) dst[i] = mk8(*(const u32x4*)(stage + ra + (((ih) * 4 + i) * 2 + (ks)) * 1024))
; #define G_LDB(dst, ks) _Pragma("unroll") for (int j = 0; j < 4; ++j) dst[j] = mk8(*(const u32x4*)(stage + TILE_B + rb + (j * 2 + (ks)) * 1024))
; #define G_MMA(ih, A, B) do { _Pragma("unroll") for (int i = 0; i < 4; ++i) _Pragma("unroll") for (int j = 0; j < 4; ++j) acc[(ih) * 4 + i][j] = MFMA16(A[i], B[j], acc[(ih) * 4 + i][j]); } while (0)
; DI void g_compute(const unsigned char* stage, int ra, int rb, f32x4 (&acc)[8][4]) {
;   bf16x8 b0[4], b1[4], a0[4], a1[4];
;   G_LDB(b0, 0); G_LDA(a0, 0, 0);
;   __builtin_amdgcn_sched_barrier(0);
;   G_LDA(a1, 1, 0);
;   G_MMA(0, a0, b0);
;   __builtin_amdgcn_sched_barrier(0);
;   G_LDB(b1, 1); G_LDA(a0, 0, 1);
;   G_MMA(1, a1, b0);
;   __builtin_amdgcn_sched_barrier(0);
;   G_LDA(a1, 1, 1);
;   G_MMA(0, a0, b1);
;   __builtin_amdgcn_sched_barrier(0);
;   G_MMA(1, a1, b1);
;   __builtin_amdgcn_sched_barrier(0);
; }
;     ...
;   for (int kt = 0; kt < KT; kt += 2) {
;     g_dma(base, off, (kt + 1) * kstep, buf1, w);
;     g_compute(buf0, ra, rb, acc);
;     asm volatile("s_waitcnt vmcnt(0)" ::: "memory");
;     __syncthreads();
.LgE0_loop:
	s_waitcnt lgkmcnt(0)
	v_mfma_f32_16x16x32_bf16 v[126:129], v[184:187], v[168:171], v[126:129]
	v_mfma_f32_16x16x32_bf16 v[98:101], v[184:187], v[172:175], v[98:101]
	ds_read_b128 v[200:203], v152 offset:8192
	v_mfma_f32_16x16x32_bf16 v[66:69], v[184:187], v[176:179], v[66:69]
	v_mfma_f32_16x16x32_bf16 v[34:37], v[184:187], v[180:183], v[34:37]
	v_mfma_f32_16x16x32_bf16 v[122:125], v[188:191], v[168:171], v[122:125]
	ds_read_b128 v[204:207], v152 offset:10240
	v_mfma_f32_16x16x32_bf16 v[94:97], v[188:191], v[172:175], v[94:97]
	v_mfma_f32_16x16x32_bf16 v[62:65], v[188:191], v[176:179], v[62:65]
	v_mfma_f32_16x16x32_bf16 v[30:33], v[188:191], v[180:183], v[30:33]
	ds_read_b128 v[216:219], v152 offset:12288
	v_mfma_f32_16x16x32_bf16 v[118:121], v[192:195], v[168:171], v[118:121]
	v_mfma_f32_16x16x32_bf16 v[86:89], v[192:195], v[172:175], v[86:89]
	v_mfma_f32_16x16x32_bf16 v[54:57], v[192:195], v[176:179], v[54:57]
	ds_read_b128 v[220:223], v152 offset:14336
	v_mfma_f32_16x16x32_bf16 v[22:25], v[192:195], v[180:183], v[22:25]
	v_mfma_f32_16x16x32_bf16 v[114:117], v[196:199], v[168:171], v[114:117]
	v_mfma_f32_16x16x32_bf16 v[82:85], v[196:199], v[172:175], v[82:85]
	v_mfma_f32_16x16x32_bf16 v[50:53], v[196:199], v[176:179], v[50:53]
	v_mfma_f32_16x16x32_bf16 v[18:21], v[196:199], v[180:183], v[18:21]
	s_waitcnt lgkmcnt(0)
	v_mfma_f32_16x16x32_bf16 v[110:113], v[200:203], v[168:171], v[110:113]
	ds_read_b128 v[224:227], v154 offset:1024
	v_mfma_f32_16x16x32_bf16 v[78:81], v[200:203], v[172:175], v[78:81]
	v_mfma_f32_16x16x32_bf16 v[46:49], v[200:203], v[176:179], v[46:49]
	ds_read_b128 v[240:243], v154 offset:3072
	v_mfma_f32_16x16x32_bf16 v[14:17], v[200:203], v[180:183], v[14:17]
	v_mfma_f32_16x16x32_bf16 v[106:109], v[204:207], v[168:171], v[106:109]
	ds_read_b128 v[244:247], v154 offset:5120
	v_mfma_f32_16x16x32_bf16 v[74:77], v[204:207], v[172:175], v[74:77]
	v_mfma_f32_16x16x32_bf16 v[42:45], v[204:207], v[176:179], v[42:45]
	ds_read_b128 v[248:251], v154 offset:7168
	v_mfma_f32_16x16x32_bf16 v[10:13], v[204:207], v[180:183], v[10:13]
	v_mfma_f32_16x16x32_bf16 v[102:105], v[216:219], v[168:171], v[102:105]
	ds_read_b128 v[184:187], v152 offset:1024
	v_mfma_f32_16x16x32_bf16 v[70:73], v[216:219], v[172:175], v[70:73]
	ds_read_b128 v[188:191], v152 offset:3072
	v_mfma_f32_16x16x32_bf16 v[38:41], v[216:219], v[176:179], v[38:41]
	ds_read_b128 v[192:195], v152 offset:5120
	v_mfma_f32_16x16x32_bf16 v[6:9], v[216:219], v[180:183], v[6:9]
	ds_read_b128 v[196:199], v152 offset:7168
	v_mfma_f32_16x16x32_bf16 v[90:93], v[220:223], v[168:171], v[90:93]
	v_mfma_f32_16x16x32_bf16 v[58:61], v[220:223], v[172:175], v[58:61]
	v_mfma_f32_16x16x32_bf16 v[26:29], v[220:223], v[176:179], v[26:29]
	v_mfma_f32_16x16x32_bf16 v[2:5], v[220:223], v[180:183], v[2:5]
	s_waitcnt lgkmcnt(0)
	v_mfma_f32_16x16x32_bf16 v[126:129], v[184:187], v[224:227], v[126:129]
	v_mfma_f32_16x16x32_bf16 v[98:101], v[184:187], v[240:243], v[98:101]
	ds_read_b128 v[200:203], v152 offset:9216
	v_mfma_f32_16x16x32_bf16 v[66:69], v[184:187], v[244:247], v[66:69]
	v_mfma_f32_16x16x32_bf16 v[34:37], v[184:187], v[248:251], v[34:37]
	v_mfma_f32_16x16x32_bf16 v[122:125], v[188:191], v[224:227], v[122:125]
	ds_read_b128 v[204:207], v152 offset:11264
	v_mfma_f32_16x16x32_bf16 v[94:97], v[188:191], v[240:243], v[94:97]
	v_mfma_f32_16x16x32_bf16 v[62:65], v[188:191], v[244:247], v[62:65]
	v_mfma_f32_16x16x32_bf16 v[30:33], v[188:191], v[248:251], v[30:33]
	ds_read_b128 v[216:219], v152 offset:13312
	v_mfma_f32_16x16x32_bf16 v[118:121], v[192:195], v[224:227], v[118:121]
	v_mfma_f32_16x16x32_bf16 v[86:89], v[192:195], v[240:243], v[86:89]
	v_mfma_f32_16x16x32_bf16 v[54:57], v[192:195], v[244:247], v[54:57]
	ds_read_b128 v[220:223], v152 offset:15360
	v_mfma_f32_16x16x32_bf16 v[22:25], v[192:195], v[248:251], v[22:25]
	v_mfma_f32_16x16x32_bf16 v[114:117], v[196:199], v[224:227], v[114:117]
	v_mfma_f32_16x16x32_bf16 v[82:85], v[196:199], v[240:243], v[82:85]
	v_mfma_f32_16x16x32_bf16 v[50:53], v[196:199], v[244:247], v[50:53]
	v_mfma_f32_16x16x32_bf16 v[18:21], v[196:199], v[248:251], v[18:21]
	s_waitcnt lgkmcnt(0)
	s_waitcnt vmcnt(0)
	s_barrier
	s_add_i32 m0, s42, 0x0
	v_mfma_f32_16x16x32_bf16 v[110:113], v[200:203], v[224:227], v[110:113]
	global_load_lds_dwordx4 v144, s[38:39]
	ds_read_b128 v[168:171], v155
	v_mfma_f32_16x16x32_bf16 v[78:81], v[200:203], v[240:243], v[78:81]
	ds_read_b128 v[172:175], v155 offset:2048
	s_add_i32 m0, s42, 0x400
	v_mfma_f32_16x16x32_bf16 v[46:49], v[200:203], v[244:247], v[46:49]
	global_load_lds_dwordx4 v145, s[38:39]
	ds_read_b128 v[176:179], v155 offset:4096
	v_mfma_f32_16x16x32_bf16 v[14:17], v[200:203], v[248:251], v[14:17]
	ds_read_b128 v[180:183], v155 offset:6144
	s_add_i32 m0, s42, 0x800
	v_mfma_f32_16x16x32_bf16 v[106:109], v[204:207], v[224:227], v[106:109]
	global_load_lds_dwordx4 v146, s[38:39]
	ds_read_b128 v[184:187], v153
	v_mfma_f32_16x16x32_bf16 v[74:77], v[204:207], v[240:243], v[74:77]
	ds_read_b128 v[188:191], v153 offset:2048
	s_add_i32 m0, s42, 0xc00
	v_mfma_f32_16x16x32_bf16 v[42:45], v[204:207], v[244:247], v[42:45]
	global_load_lds_dwordx4 v147, s[38:39]
	ds_read_b128 v[192:195], v153 offset:4096
	v_mfma_f32_16x16x32_bf16 v[10:13], v[204:207], v[248:251], v[10:13]
	ds_read_b128 v[196:199], v153 offset:6144
	s_add_i32 m0, s42, 0x1000
	v_mfma_f32_16x16x32_bf16 v[102:105], v[216:219], v[224:227], v[102:105]
	global_load_lds_dwordx4 v148, s[38:39]
	v_mfma_f32_16x16x32_bf16 v[70:73], v[216:219], v[240:243], v[70:73]
	s_add_i32 m0, s42, 0x1400
	v_mfma_f32_16x16x32_bf16 v[38:41], v[216:219], v[244:247], v[38:41]
	global_load_lds_dwordx4 v149, s[38:39]
	v_mfma_f32_16x16x32_bf16 v[6:9], v[216:219], v[248:251], v[6:9]
	s_add_i32 m0, s42, 0x1800
	v_mfma_f32_16x16x32_bf16 v[90:93], v[220:223], v[224:227], v[90:93]
	global_load_lds_dwordx4 v150, s[38:39]
	v_mfma_f32_16x16x32_bf16 v[58:61], v[220:223], v[240:243], v[58:61]
	s_add_i32 m0, s42, 0x1c00
	v_mfma_f32_16x16x32_bf16 v[26:29], v[220:223], v[244:247], v[26:29]
	global_load_lds_dwordx4 v151, s[38:39]
	v_mfma_f32_16x16x32_bf16 v[2:5], v[220:223], v[248:251], v[2:5]
	s_add_u32 s38, s38, 0x80
	s_addc_u32 s39, s39, 0
	s_waitcnt lgkmcnt(0)
;     ...
;     const bool last = kt + 2 >= KT;
;     g_dma(last ? nbase : base, off, last ? 0 : (kt + 2) * kstep, buf0, w);
;     g_compute(buf1, ra, rb, acc);
;     asm volatile("s_waitcnt vmcnt(0)" ::: "memory");
;     __syncthreads();
	v_mfma_f32_16x16x32_bf16 v[126:129], v[184:187], v[168:171], v[126:129]
	v_mfma_f32_16x16x32_bf16 v[98:101], v[184:187], v[172:175], v[98:101]
	ds_read_b128 v[200:203], v153 offset:8192
	v_mfma_f32_16x16x32_bf16 v[66:69], v[184:187], v[176:179], v[66:69]
	v_mfma_f32_16x16x32_bf16 v[34:37], v[184:187], v[180:183], v[34:37]
	v_mfma_f32_16x16x32_bf16 v[122:125], v[188:191], v[168:171], v[122:125]
	ds_read_b128 v[204:207], v153 offset:10240
	v_mfma_f32_16x16x32_bf16 v[94:97], v[188:191], v[172:175], v[94:97]
	v_mfma_f32_16x16x32_bf16 v[62:65], v[188:191], v[176:179], v[62:65]
	v_mfma_f32_16x16x32_bf16 v[30:33], v[188:191], v[180:183], v[30:33]
	ds_read_b128 v[216:219], v153 offset:12288
	v_mfma_f32_16x16x32_bf16 v[118:121], v[192:195], v[168:171], v[118:121]
	v_mfma_f32_16x16x32_bf16 v[86:89], v[192:195], v[172:175], v[86:89]
	v_mfma_f32_16x16x32_bf16 v[54:57], v[192:195], v[176:179], v[54:57]
	ds_read_b128 v[220:223], v153 offset:14336
	v_mfma_f32_16x16x32_bf16 v[22:25], v[192:195], v[180:183], v[22:25]
	v_mfma_f32_16x16x32_bf16 v[114:117], v[196:199], v[168:171], v[114:117]
	v_mfma_f32_16x16x32_bf16 v[82:85], v[196:199], v[172:175], v[82:85]
	v_mfma_f32_16x16x32_bf16 v[50:53], v[196:199], v[176:179], v[50:53]
	v_mfma_f32_16x16x32_bf16 v[18:21], v[196:199], v[180:183], v[18:21]
	s_waitcnt lgkmcnt(0)
	v_mfma_f32_16x16x32_bf16 v[110:113], v[200:203], v[168:171], v[110:113]
	ds_read_b128 v[224:227], v155 offset:1024
	v_mfma_f32_16x16x32_bf16 v[78:81], v[200:203], v[172:175], v[78:81]
	v_mfma_f32_16x16x32_bf16 v[46:49], v[200:203], v[176:179], v[46:49]
	ds_read_b128 v[240:243], v155 offset:3072
	v_mfma_f32_16x16x32_bf16 v[14:17], v[200:203], v[180:183], v[14:17]
	v_mfma_f32_16x16x32_bf16 v[106:109], v[204:207], v[168:171], v[106:109]
	ds_read_b128 v[244:247], v155 offset:5120
	v_mfma_f32_16x16x32_bf16 v[74:77], v[204:207], v[172:175], v[74:77]
	v_mfma_f32_16x16x32_bf16 v[42:45], v[204:207], v[176:179], v[42:45]
	ds_read_b128 v[248:251], v155 offset:7168
	v_mfma_f32_16x16x32_bf16 v[10:13], v[204:207], v[180:183], v[10:13]
	v_mfma_f32_16x16x32_bf16 v[102:105], v[216:219], v[168:171], v[102:105]
	ds_read_b128 v[184:187], v153 offset:1024
	v_mfma_f32_16x16x32_bf16 v[70:73], v[216:219], v[172:175], v[70:73]
	ds_read_b128 v[188:191], v153 offset:3072
	v_mfma_f32_16x16x32_bf16 v[38:41], v[216:219], v[176:179], v[38:41]
	ds_read_b128 v[192:195], v153 offset:5120
	v_mfma_f32_16x16x32_bf16 v[6:9], v[216:219], v[180:183], v[6:9]
	ds_read_b128 v[196:199], v153 offset:7168
	v_mfma_f32_16x16x32_bf16 v[90:93], v[220:223], v[168:171], v[90:93]
	v_mfma_f32_16x16x32_bf16 v[58:61], v[220:223], v[172:175], v[58:61]
	v_mfma_f32_16x16x32_bf16 v[26:29], v[220:223], v[176:179], v[26:29]
	v_mfma_f32_16x16x32_bf16 v[2:5], v[220:223], v[180:183], v[2:5]
	s_waitcnt lgkmcnt(0)
	v_mfma_f32_16x16x32_bf16 v[126:129], v[184:187], v[224:227], v[126:129]
	v_mfma_f32_16x16x32_bf16 v[98:101], v[184:187], v[240:243], v[98:101]
	ds_read_b128 v[200:203], v153 offset:9216
	v_mfma_f32_16x16x32_bf16 v[66:69], v[184:187], v[244:247], v[66:69]
	v_mfma_f32_16x16x32_bf16 v[34:37], v[184:187], v[248:251], v[34:37]
	v_mfma_f32_16x16x32_bf16 v[122:125], v[188:191], v[224:227], v[122:125]
	ds_read_b128 v[204:207], v153 offset:11264
	v_mfma_f32_16x16x32_bf16 v[94:97], v[188:191], v[240:243], v[94:97]
	v_mfma_f32_16x16x32_bf16 v[62:65], v[188:191], v[244:247], v[62:65]
	v_mfma_f32_16x16x32_bf16 v[30:33], v[188:191], v[248:251], v[30:33]
	ds_read_b128 v[216:219], v153 offset:13312
	v_mfma_f32_16x16x32_bf16 v[118:121], v[192:195], v[224:227], v[118:121]
	v_mfma_f32_16x16x32_bf16 v[86:89], v[192:195], v[240:243], v[86:89]
	v_mfma_f32_16x16x32_bf16 v[54:57], v[192:195], v[244:247], v[54:57]
	ds_read_b128 v[220:223], v153 offset:15360
	v_mfma_f32_16x16x32_bf16 v[22:25], v[192:195], v[248:251], v[22:25]
	v_mfma_f32_16x16x32_bf16 v[114:117], v[196:199], v[224:227], v[114:117]
	v_mfma_f32_16x16x32_bf16 v[82:85], v[196:199], v[240:243], v[82:85]
	v_mfma_f32_16x16x32_bf16 v[50:53], v[196:199], v[244:247], v[50:53]
	v_mfma_f32_16x16x32_bf16 v[18:21], v[196:199], v[248:251], v[18:21]
	s_waitcnt lgkmcnt(0)
	s_waitcnt vmcnt(0)
	s_barrier
	s_add_i32 m0, s43, 0x0
	v_mfma_f32_16x16x32_bf16 v[110:113], v[200:203], v[224:227], v[110:113]
	global_load_lds_dwordx4 v144, s[38:39]
	ds_read_b128 v[168:171], v154
	v_mfma_f32_16x16x32_bf16 v[78:81], v[200:203], v[240:243], v[78:81]
	ds_read_b128 v[172:175], v154 offset:2048
	s_add_i32 m0, s43, 0x400
	v_mfma_f32_16x16x32_bf16 v[46:49], v[200:203], v[244:247], v[46:49]
	global_load_lds_dwordx4 v145, s[38:39]
	ds_read_b128 v[176:179], v154 offset:4096
	v_mfma_f32_16x16x32_bf16 v[14:17], v[200:203], v[248:251], v[14:17]
	ds_read_b128 v[180:183], v154 offset:6144
	s_add_i32 m0, s43, 0x800
	v_mfma_f32_16x16x32_bf16 v[106:109], v[204:207], v[224:227], v[106:109]
	global_load_lds_dwordx4 v146, s[38:39]
	ds_read_b128 v[184:187], v152
	v_mfma_f32_16x16x32_bf16 v[74:77], v[204:207], v[240:243], v[74:77]
	ds_read_b128 v[188:191], v152 offset:2048
	s_add_i32 m0, s43, 0xc00
	v_mfma_f32_16x16x32_bf16 v[42:45], v[204:207], v[244:247], v[42:45]
	global_load_lds_dwordx4 v147, s[38:39]
	ds_read_b128 v[192:195], v152 offset:4096
	v_mfma_f32_16x16x32_bf16 v[10:13], v[204:207], v[248:251], v[10:13]
	ds_read_b128 v[196:199], v152 offset:6144
	s_add_i32 m0, s43, 0x1000
	v_mfma_f32_16x16x32_bf16 v[102:105], v[216:219], v[224:227], v[102:105]
	global_load_lds_dwordx4 v148, s[38:39]
	v_mfma_f32_16x16x32_bf16 v[70:73], v[216:219], v[240:243], v[70:73]
	s_add_i32 m0, s43, 0x1400
	v_mfma_f32_16x16x32_bf16 v[38:41], v[216:219], v[244:247], v[38:41]
	global_load_lds_dwordx4 v149, s[38:39]
	v_mfma_f32_16x16x32_bf16 v[6:9], v[216:219], v[248:251], v[6:9]
	s_add_i32 m0, s43, 0x1800
	v_mfma_f32_16x16x32_bf16 v[90:93], v[220:223], v[224:227], v[90:93]
	global_load_lds_dwordx4 v150, s[38:39]
	v_mfma_f32_16x16x32_bf16 v[58:61], v[220:223], v[240:243], v[58:61]
	s_add_i32 m0, s43, 0x1c00
	v_mfma_f32_16x16x32_bf16 v[26:29], v[220:223], v[244:247], v[26:29]
	global_load_lds_dwordx4 v151, s[38:39]
	v_mfma_f32_16x16x32_bf16 v[2:5], v[220:223], v[248:251], v[2:5]
	s_add_u32 s38, s38, 0x80
	s_addc_u32 s39, s39, 0
	s_add_i32 s46, s46, 1
	s_cmp_lt_u32 s46, 7
	s_cbranch_scc1 .LgE0_loop
; DI unsigned pk2(float lo, float hi) { f32x2 v = {lo, hi}; bf16x2_t b = __builtin_convertvector(v, bf16x2_t); return __builtin_bit_cast(unsigned, b); }
;     ...
;   for (int kt = 0; kt < KT; kt += 2) {
;     g_dma(base, off, (kt + 1) * kstep, buf1, w);
;     g_compute(buf0, ra, rb, acc);
;     asm volatile("s_waitcnt vmcnt(0)" ::: "memory");
;     __syncthreads();
;     const bool last = kt + 2 >= KT;
;     g_dma(last ? nbase : base, off, last ? 0 : (kt + 2) * kstep, buf0, w);
; DI void phaseE(const Params& p0, const Slot sl, int layer, unsigned char* lds, const float* xsrc) {
;     ...
;         const long off = tok * 1024 + nt * 256 + wa * 128 + i * 16 + quad * 4;
;         const f32x4 xo = *(const f32x4*)(xsrc + off);
;         const f32x4 xn = xo + acc[i][j];
;         *(f32x4*)(p.out + off) = xn;
;         *(u32x2*)(p.xb() + off + tok * (LDX - D_MODEL)) = (u32x2){pk2(xn[0], xn[1]), pk2(xn[2], xn[3])};
	s_waitcnt lgkmcnt(0)
	v_mfma_f32_16x16x32_bf16 v[126:129], v[184:187], v[168:171], v[126:129]
	v_mfma_f32_16x16x32_bf16 v[98:101], v[184:187], v[172:175], v[98:101]
	ds_read_b128 v[200:203], v152 offset:8192
	v_mfma_f32_16x16x32_bf16 v[66:69], v[184:187], v[176:179], v[66:69]
	v_mfma_f32_16x16x32_bf16 v[34:37], v[184:187], v[180:183], v[34:37]
	v_mfma_f32_16x16x32_bf16 v[122:125], v[188:191], v[168:171], v[122:125]
	ds_read_b128 v[204:207], v152 offset:10240
	v_mfma_f32_16x16x32_bf16 v[94:97], v[188:191], v[172:175], v[94:97]
	v_mfma_f32_16x16x32_bf16 v[62:65], v[188:191], v[176:179], v[62:65]
	v_mfma_f32_16x16x32_bf16 v[30:33], v[188:191], v[180:183], v[30:33]
	ds_read_b128 v[216:219], v152 offset:12288
	v_mfma_f32_16x16x32_bf16 v[118:121], v[192:195], v[168:171], v[118:121]
	v_mfma_f32_16x16x32_bf16 v[86:89], v[192:195], v[172:175], v[86:89]
	v_mfma_f32_16x16x32_bf16 v[54:57], v[192:195], v[176:179], v[54:57]
	ds_read_b128 v[220:223], v152 offset:14336
	v_mfma_f32_16x16x32_bf16 v[22:25], v[192:195], v[180:183], v[22:25]
	v_mfma_f32_16x16x32_bf16 v[114:117], v[196:199], v[168:171], v[114:117]
	v_mfma_f32_16x16x32_bf16 v[82:85], v[196:199], v[172:175], v[82:85]
	v_mfma_f32_16x16x32_bf16 v[50:53], v[196:199], v[176:179], v[50:53]
	v_mfma_f32_16x16x32_bf16 v[18:21], v[196:199], v[180:183], v[18:21]
	s_waitcnt lgkmcnt(0)
	v_mfma_f32_16x16x32_bf16 v[110:113], v[200:203], v[168:171], v[110:113]
	ds_read_b128 v[224:227], v154 offset:1024
	v_mfma_f32_16x16x32_bf16 v[78:81], v[200:203], v[172:175], v[78:81]
	v_mfma_f32_16x16x32_bf16 v[46:49], v[200:203], v[176:179], v[46:49]
	ds_read_b128 v[240:243], v154 offset:3072
	v_mfma_f32_16x16x32_bf16 v[14:17], v[200:203], v[180:183], v[14:17]
	v_mfma_f32_16x16x32_bf16 v[106:109], v[204:207], v[168:171], v[106:109]
	ds_read_b128 v[244:247], v154 offset:5120
	v_mfma_f32_16x16x32_bf16 v[74:77], v[204:207], v[172:175], v[74:77]
	v_mfma_f32_16x16x32_bf16 v[42:45], v[204:207], v[176:179], v[42:45]
	ds_read_b128 v[248:251], v154 offset:7168
	v_mfma_f32_16x16x32_bf16 v[10:13], v[204:207], v[180:183], v[10:13]
	v_mfma_f32_16x16x32_bf16 v[102:105], v[216:219], v[168:171], v[102:105]
	ds_read_b128 v[184:187], v152 offset:1024
	v_mfma_f32_16x16x32_bf16 v[70:73], v[216:219], v[172:175], v[70:73]
	ds_read_b128 v[188:191], v152 offset:3072
	v_mfma_f32_16x16x32_bf16 v[38:41], v[216:219], v[176:179], v[38:41]
	ds_read_b128 v[192:195], v152 offset:5120
	v_mfma_f32_16x16x32_bf16 v[6:9], v[216:219], v[180:183], v[6:9]
	ds_read_b128 v[196:199], v152 offset:7168
	v_mfma_f32_16x16x32_bf16 v[90:93], v[220:223], v[168:171], v[90:93]
	v_mfma_f32_16x16x32_bf16 v[58:61], v[220:223], v[172:175], v[58:61]
	v_mfma_f32_16x16x32_bf16 v[26:29], v[220:223], v[176:179], v[26:29]
	v_mfma_f32_16x16x32_bf16 v[2:5], v[220:223], v[180:183], v[2:5]
	s_waitcnt lgkmcnt(0)
	v_mfma_f32_16x16x32_bf16 v[126:129], v[184:187], v[224:227], v[126:129]
	v_mfma_f32_16x16x32_bf16 v[98:101], v[184:187], v[240:243], v[98:101]
	ds_read_b128 v[200:203], v152 offset:9216
	v_mfma_f32_16x16x32_bf16 v[66:69], v[184:187], v[244:247], v[66:69]
	v_mfma_f32_16x16x32_bf16 v[34:37], v[184:187], v[248:251], v[34:37]
	v_mfma_f32_16x16x32_bf16 v[122:125], v[188:191], v[224:227], v[122:125]
	ds_read_b128 v[204:207], v152 offset:11264
	v_mfma_f32_16x16x32_bf16 v[94:97], v[188:191], v[240:243], v[94:97]
	v_mfma_f32_16x16x32_bf16 v[62:65], v[188:191], v[244:247], v[62:65]
	v_mfma_f32_16x16x32_bf16 v[30:33], v[188:191], v[248:251], v[30:33]
	ds_read_b128 v[216:219], v152 offset:13312
	v_mfma_f32_16x16x32_bf16 v[118:121], v[192:195], v[224:227], v[118:121]
	v_mfma_f32_16x16x32_bf16 v[86:89], v[192:195], v[240:243], v[86:89]
	v_mfma_f32_16x16x32_bf16 v[54:57], v[192:195], v[244:247], v[54:57]
	ds_read_b128 v[220:223], v152 offset:15360
	v_mfma_f32_16x16x32_bf16 v[22:25], v[192:195], v[248:251], v[22:25]
	v_mfma_f32_16x16x32_bf16 v[114:117], v[196:199], v[224:227], v[114:117]
	v_mfma_f32_16x16x32_bf16 v[82:85], v[196:199], v[240:243], v[82:85]
	v_mfma_f32_16x16x32_bf16 v[50:53], v[196:199], v[244:247], v[50:53]
	v_mfma_f32_16x16x32_bf16 v[18:21], v[196:199], v[248:251], v[18:21]
	s_waitcnt lgkmcnt(0)
	s_waitcnt vmcnt(0)
	s_barrier
	s_add_i32 m0, s42, 0x0
	v_mfma_f32_16x16x32_bf16 v[110:113], v[200:203], v[224:227], v[110:113]
	global_load_lds_dwordx4 v144, s[40:41]
	ds_read_b128 v[168:171], v155
	v_mfma_f32_16x16x32_bf16 v[78:81], v[200:203], v[240:243], v[78:81]
	ds_read_b128 v[172:175], v155 offset:2048
	s_add_i32 m0, s42, 0x400
	v_mfma_f32_16x16x32_bf16 v[46:49], v[200:203], v[244:247], v[46:49]
	global_load_lds_dwordx4 v145, s[40:41]
	ds_read_b128 v[176:179], v155 offset:4096
	v_mfma_f32_16x16x32_bf16 v[14:17], v[200:203], v[248:251], v[14:17]
	ds_read_b128 v[180:183], v155 offset:6144
	s_add_i32 m0, s42, 0x800
	v_mfma_f32_16x16x32_bf16 v[106:109], v[204:207], v[224:227], v[106:109]
	global_load_lds_dwordx4 v146, s[40:41]
	ds_read_b128 v[184:187], v153
	v_mfma_f32_16x16x32_bf16 v[74:77], v[204:207], v[240:243], v[74:77]
	ds_read_b128 v[188:191], v153 offset:2048
	s_add_i32 m0, s42, 0xc00
	v_mfma_f32_16x16x32_bf16 v[42:45], v[204:207], v[244:247], v[42:45]
	global_load_lds_dwordx4 v147, s[40:41]
	ds_read_b128 v[192:195], v153 offset:4096
	v_mfma_f32_16x16x32_bf16 v[10:13], v[204:207], v[248:251], v[10:13]
	ds_read_b128 v[196:199], v153 offset:6144
	s_add_i32 m0, s42, 0x1000
	v_mfma_f32_16x16x32_bf16 v[102:105], v[216:219], v[224:227], v[102:105]
	global_load_lds_dwordx4 v148, s[40:41]
	v_mfma_f32_16x16x32_bf16 v[70:73], v[216:219], v[240:243], v[70:73]
	s_add_i32 m0, s42, 0x1400
	v_mfma_f32_16x16x32_bf16 v[38:41], v[216:219], v[244:247], v[38:41]
	global_load_lds_dwordx4 v149, s[40:41]
	v_mfma_f32_16x16x32_bf16 v[6:9], v[216:219], v[248:251], v[6:9]
	s_add_i32 m0, s42, 0x1800
	v_mfma_f32_16x16x32_bf16 v[90:93], v[220:223], v[224:227], v[90:93]
	global_load_lds_dwordx4 v150, s[40:41]
	v_mfma_f32_16x16x32_bf16 v[58:61], v[220:223], v[240:243], v[58:61]
	s_add_i32 m0, s42, 0x1c00
	v_mfma_f32_16x16x32_bf16 v[26:29], v[220:223], v[244:247], v[26:29]
	global_load_lds_dwordx4 v151, s[40:41]
	v_mfma_f32_16x16x32_bf16 v[2:5], v[220:223], v[248:251], v[2:5]
	s_add_u32 s40, s40, 0x80
	s_addc_u32 s41, s41, 0
	s_waitcnt lgkmcnt(0)
; DI unsigned pk2(float lo, float hi) { f32x2 v = {lo, hi}; bf16x2_t b = __builtin_convertvector(v, bf16x2_t); return __builtin_bit_cast(unsigned, b); }
; DI int my_tid() { int t = threadIdx.x; asm volatile("" : "+v"(t)); return t; }
;     ...
;     g_compute(buf1, ra, rb, acc);
;     asm volatile("s_waitcnt vmcnt(0)" ::: "memory");
;     __syncthreads();
; DI void phaseE(const Params& p0, const Slot sl, int layer, unsigned char* lds, const float* xsrc) {
;     ...
;     const int tid = my_tid(), lane = tid & 63, w = tid >> 6, wa = w >> 2, wb = w & 3, qi = lane & 15, quad = lane >> 4;
; #pragma unroll
;     for (int j = 0; j < 4; ++j) {
;       const long tok = (long)mt * 256 + wb * 64 + j * 16 + qi;
;       float ss = 0.f;
; #pragma unroll
;       for (int i = 0; i < 8; ++i) {
;         const long off = tok * 1024 + nt * 256 + wa * 128 + i * 16 + quad * 4;
;         const f32x4 xo = *(const f32x4*)(xsrc + off);
;         const f32x4 xn = xo + acc[i][j];
;         *(f32x4*)(p.out + off) = xn;
;         *(u32x2*)(p.xb() + off + tok * (LDX - D_MODEL)) = (u32x2){pk2(xn[0], xn[1]), pk2(xn[2], xn[3])};
;         ss += xn[0] * xn[0] + xn[1] * xn[1] + xn[2] * xn[2] + xn[3] * xn[3];
	v_mfma_f32_16x16x32_bf16 v[126:129], v[184:187], v[168:171], v[126:129]
	v_mfma_f32_16x16x32_bf16 v[98:101], v[184:187], v[172:175], v[98:101]
	ds_read_b128 v[200:203], v153 offset:8192
	v_mfma_f32_16x16x32_bf16 v[66:69], v[184:187], v[176:179], v[66:69]
	v_mfma_f32_16x16x32_bf16 v[34:37], v[184:187], v[180:183], v[34:37]
	v_mfma_f32_16x16x32_bf16 v[122:125], v[188:191], v[168:171], v[122:125]
	ds_read_b128 v[204:207], v153 offset:10240
	v_mfma_f32_16x16x32_bf16 v[94:97], v[188:191], v[172:175], v[94:97]
	v_mfma_f32_16x16x32_bf16 v[62:65], v[188:191], v[176:179], v[62:65]
	v_mfma_f32_16x16x32_bf16 v[30:33], v[188:191], v[180:183], v[30:33]
	ds_read_b128 v[216:219], v153 offset:12288
	v_mfma_f32_16x16x32_bf16 v[118:121], v[192:195], v[168:171], v[118:121]
	v_mfma_f32_16x16x32_bf16 v[86:89], v[192:195], v[172:175], v[86:89]
	v_mfma_f32_16x16x32_bf16 v[54:57], v[192:195], v[176:179], v[54:57]
	ds_read_b128 v[220:223], v153 offset:14336
	v_mfma_f32_16x16x32_bf16 v[22:25], v[192:195], v[180:183], v[22:25]
	v_mfma_f32_16x16x32_bf16 v[114:117], v[196:199], v[168:171], v[114:117]
	v_mfma_f32_16x16x32_bf16 v[82:85], v[196:199], v[172:175], v[82:85]
	v_mfma_f32_16x16x32_bf16 v[50:53], v[196:199], v[176:179], v[50:53]
	v_mfma_f32_16x16x32_bf16 v[18:21], v[196:199], v[180:183], v[18:21]
	s_waitcnt lgkmcnt(0)
	v_mfma_f32_16x16x32_bf16 v[110:113], v[200:203], v[168:171], v[110:113]
	ds_read_b128 v[224:227], v155 offset:1024
	v_mfma_f32_16x16x32_bf16 v[78:81], v[200:203], v[172:175], v[78:81]
	v_mfma_f32_16x16x32_bf16 v[46:49], v[200:203], v[176:179], v[46:49]
	ds_read_b128 v[240:243], v155 offset:3072
	v_mfma_f32_16x16x32_bf16 v[14:17], v[200:203], v[180:183], v[14:17]
	v_mfma_f32_16x16x32_bf16 v[106:109], v[204:207], v[168:171], v[106:109]
	ds_read_b128 v[244:247], v155 offset:5120
	v_mfma_f32_16x16x32_bf16 v[74:77], v[204:207], v[172:175], v[74:77]
	v_mfma_f32_16x16x32_bf16 v[42:45], v[204:207], v[176:179], v[42:45]
	ds_read_b128 v[248:251], v155 offset:7168
	v_mfma_f32_16x16x32_bf16 v[10:13], v[204:207], v[180:183], v[10:13]
	v_mfma_f32_16x16x32_bf16 v[102:105], v[216:219], v[168:171], v[102:105]
	ds_read_b128 v[184:187], v153 offset:1024
	v_mfma_f32_16x16x32_bf16 v[70:73], v[216:219], v[172:175], v[70:73]
	ds_read_b128 v[188:191], v153 offset:3072
	v_mfma_f32_16x16x32_bf16 v[38:41], v[216:219], v[176:179], v[38:41]
	ds_read_b128 v[192:195], v153 offset:5120
	v_mfma_f32_16x16x32_bf16 v[6:9], v[216:219], v[180:183], v[6:9]
	ds_read_b128 v[196:199], v153 offset:7168
	v_mfma_f32_16x16x32_bf16 v[90:93], v[220:223], v[168:171], v[90:93]
	v_mfma_f32_16x16x32_bf16 v[58:61], v[220:223], v[172:175], v[58:61]
	v_mfma_f32_16x16x32_bf16 v[26:29], v[220:223], v[176:179], v[26:29]
	v_mfma_f32_16x16x32_bf16 v[2:5], v[220:223], v[180:183], v[2:5]
	s_waitcnt lgkmcnt(0)
	v_mfma_f32_16x16x32_bf16 v[126:129], v[184:187], v[224:227], v[126:129]
	v_mfma_f32_16x16x32_bf16 v[98:101], v[184:187], v[240:243], v[98:101]
	ds_read_b128 v[200:203], v153 offset:9216
	v_mfma_f32_16x16x32_bf16 v[66:69], v[184:187], v[244:247], v[66:69]
	v_mfma_f32_16x16x32_bf16 v[34:37], v[184:187], v[248:251], v[34:37]
	v_mfma_f32_16x16x32_bf16 v[122:125], v[188:191], v[224:227], v[122:125]
	ds_read_b128 v[204:207], v153 offset:11264
	v_mfma_f32_16x16x32_bf16 v[94:97], v[188:191], v[240:243], v[94:97]
	v_mfma_f32_16x16x32_bf16 v[62:65], v[188:191], v[244:247], v[62:65]
	v_mfma_f32_16x16x32_bf16 v[30:33], v[188:191], v[248:251], v[30:33]
	ds_read_b128 v[216:219], v153 offset:13312
	v_mfma_f32_16x16x32_bf16 v[118:121], v[192:195], v[224:227], v[118:121]
	v_mfma_f32_16x16x32_bf16 v[86:89], v[192:195], v[240:243], v[86:89]
	v_mfma_f32_16x16x32_bf16 v[54:57], v[192:195], v[244:247], v[54:57]
	ds_read_b128 v[220:223], v153 offset:15360
	v_mfma_f32_16x16x32_bf16 v[22:25], v[192:195], v[248:251], v[22:25]
	v_mfma_f32_16x16x32_bf16 v[114:117], v[196:199], v[224:227], v[114:117]
	v_mfma_f32_16x16x32_bf16 v[82:85], v[196:199], v[240:243], v[82:85]
	v_mfma_f32_16x16x32_bf16 v[50:53], v[196:199], v[244:247], v[50:53]
	v_mfma_f32_16x16x32_bf16 v[18:21], v[196:199], v[248:251], v[18:21]
	s_waitcnt lgkmcnt(0)
	s_waitcnt vmcnt(0)
	s_barrier
	v_mfma_f32_16x16x32_bf16 v[110:113], v[200:203], v[224:227], v[110:113]
	v_mfma_f32_16x16x32_bf16 v[78:81], v[200:203], v[240:243], v[78:81]
	v_mfma_f32_16x16x32_bf16 v[46:49], v[200:203], v[244:247], v[46:49]
	v_mfma_f32_16x16x32_bf16 v[14:17], v[200:203], v[248:251], v[14:17]
	v_mfma_f32_16x16x32_bf16 v[106:109], v[204:207], v[224:227], v[106:109]
	v_mfma_f32_16x16x32_bf16 v[74:77], v[204:207], v[240:243], v[74:77]
	v_mfma_f32_16x16x32_bf16 v[42:45], v[204:207], v[244:247], v[42:45]
	v_mfma_f32_16x16x32_bf16 v[10:13], v[204:207], v[248:251], v[10:13]
	v_mfma_f32_16x16x32_bf16 v[102:105], v[216:219], v[224:227], v[102:105]
	v_mfma_f32_16x16x32_bf16 v[70:73], v[216:219], v[240:243], v[70:73]
	v_mfma_f32_16x16x32_bf16 v[38:41], v[216:219], v[244:247], v[38:41]
	v_mfma_f32_16x16x32_bf16 v[6:9], v[216:219], v[248:251], v[6:9]
	v_mfma_f32_16x16x32_bf16 v[90:93], v[220:223], v[224:227], v[90:93]
	v_mfma_f32_16x16x32_bf16 v[58:61], v[220:223], v[240:243], v[58:61]
	v_mfma_f32_16x16x32_bf16 v[26:29], v[220:223], v[244:247], v[26:29]
	v_mfma_f32_16x16x32_bf16 v[2:5], v[220:223], v[248:251], v[2:5]
	s_nop 7
	s_nop 3
	s_mov_b64 s[56:57], s[90:91]
	v_and_b32_e32 v248, 0xc0, v210
	v_and_b32_e32 v249, 15, v210
	v_lshl_or_b32 v248, v136, 8, v248
	v_or_b32_e32 v248, v248, v249
	v_ashrrev_i32_e32 v249, 8, v210
	v_bfe_u32 v231, v210, 4, 2
	v_lshlrev_b32_e32 v251, 8, v134
	v_lshl_or_b32 v251, v249, 7, v251
	v_lshl_or_b32 v251, v231, 2, v251
	v_lshlrev_b32_e32 v130, 12, v248
; DI unsigned pk2(float lo, float hi) { f32x2 v = {lo, hi}; bf16x2_t b = __builtin_convertvector(v, bf16x2_t); return __builtin_bit_cast(unsigned, b); }
; DI int my_tid() { int t = threadIdx.x; asm volatile("" : "+v"(t)); return t; }
; DI void phaseE(const Params& p0, const Slot sl, int layer, unsigned char* lds, const float* xsrc) {
;     ...
;     const int tid = my_tid(), lane = tid & 63, w = tid >> 6, wa = w >> 2, wb = w & 3, qi = lane & 15, quad = lane >> 4;
; #pragma unroll
;     for (int j = 0; j < 4; ++j) {
;       const long tok = (long)mt * 256 + wb * 64 + j * 16 + qi;
;       float ss = 0.f;
; #pragma unroll
;       for (int i = 0; i < 8; ++i) {
;         const long off = tok * 1024 + nt * 256 + wa * 128 + i * 16 + quad * 4;
;         const f32x4 xo = *(const f32x4*)(xsrc + off);
;         const f32x4 xn = xo + acc[i][j];
;         *(f32x4*)(p.out + off) = xn;
;         *(u32x2*)(p.xb() + off + tok * (LDX - D_MODEL)) = (u32x2){pk2(xn[0], xn[1]), pk2(xn[2], xn[3])};
;         ss += xn[0] * xn[0] + xn[1] * xn[1] + xn[2] * xn[2] + xn[3] * xn[3];
	v_lshl_add_u32 v130, v251, 2, v130
	v_add_u32_e32 v161, 0x10000, v130
	v_add_u32_e32 v163, 0x20000, v130
	v_add_u32_e32 v205, 0x30000, v130
	s_movk_i32 s10, 0x880
	v_mul_lo_u32 v200, v248, s10
	v_lshl_add_u32 v200, v251, 1, v200
	v_and_b32_e32 v250, 1, v231
	v_lshlrev_b32_e32 v250, 5, v250
	v_lshrrev_b32_e32 v242, 1, v231
	v_lshl_add_u32 v250, v242, 4, v250
	v_lshlrev_b32_e32 v242, 3, v231
	v_sub_u32_e32 v250, v250, v242
	v_add_u32_e32 v200, v200, v250
	v_add_u32_e32 v201, 0x8800, v200
	v_add_u32_e32 v158, 0x11000, v200
	v_add_u32_e32 v159, 0x19800, v200
	v_lshl_add_u32 v251, v134, 1, v249
	v_lshlrev_b32_e32 v230, 6, v248
	v_lshl_add_u32 v230, v251, 2, v230
	v_xor_b32_e32 v239, 16, v228
	v_xor_b32_e32 v243, 32, v228
	v_lshlrev_b32_e32 v239, 2, v239
	v_lshlrev_b32_e32 v243, 2, v243
	global_load_dwordx4 v[164:167], v130, s[56:57]
	global_load_dwordx4 v[168:171], v130, s[56:57] offset:64
	global_load_dwordx4 v[172:175], v130, s[56:57] offset:128
	global_load_dwordx4 v[176:179], v130, s[56:57] offset:192
	global_load_dwordx4 v[180:183], v130, s[56:57] offset:256
	global_load_dwordx4 v[184:187], v130, s[56:57] offset:320
	global_load_dwordx4 v[188:191], v130, s[56:57] offset:384
	global_load_dwordx4 v[192:195], v130, s[56:57] offset:448
	global_load_dwordx4 v[196:199], v161, s[56:57]
	global_load_dwordx4 v[216:219], v161, s[56:57] offset:64
	global_load_dwordx4 v[220:223], v161, s[56:57] offset:128
	global_load_dwordx4 v[224:227], v161, s[56:57] offset:192
	s_waitcnt vmcnt(11)
	v_pk_add_f32 v[126:127], v[126:127], v[164:165]
	v_pk_add_f32 v[128:129], v[128:129], v[166:167]
	v_mul_f32_e32 v244, v127, v127
	v_fmac_f32_e32 v244, v126, v126
	v_fmac_f32_e32 v244, v128, v128
	v_fmac_f32_e32 v244, v129, v129
	global_load_dwordx4 v[164:167], v161, s[56:57] offset:256
	s_waitcnt vmcnt(11)
	v_pk_add_f32 v[122:123], v[122:123], v[168:169]
	v_pk_add_f32 v[124:125], v[124:125], v[170:171]
	v_mul_f32_e32 v242, v123, v123
	v_fmac_f32_e32 v242, v122, v122
	v_fmac_f32_e32 v242, v124, v124
	v_fmac_f32_e32 v242, v125, v125
	v_add_f32_e32 v244, v244, v242
	global_load_dwordx4 v[168:171], v161, s[56:57] offset:320
	s_waitcnt vmcnt(11)
	v_pk_add_f32 v[118:119], v[118:119], v[172:173]
	v_pk_add_f32 v[120:121], v[120:121], v[174:175]
	v_mul_f32_e32 v242, v119, v119
	v_fmac_f32_e32 v242, v118, v118
	v_fmac_f32_e32 v242, v120, v120
	v_fmac_f32_e32 v242, v121, v121
	v_add_f32_e32 v244, v244, v242
	global_load_dwordx4 v[172:175], v161, s[56:57] offset:384
	s_waitcnt vmcnt(11)
	v_pk_add_f32 v[114:115], v[114:115], v[176:177]
	v_pk_add_f32 v[116:117], v[116:117], v[178:179]
	v_mul_f32_e32 v242, v115, v115
	v_fmac_f32_e32 v242, v114, v114
	v_fmac_f32_e32 v242, v116, v116
	v_fmac_f32_e32 v242, v117, v117
	v_add_f32_e32 v244, v244, v242
	global_load_dwordx4 v[176:179], v161, s[56:57] offset:448
	s_waitcnt vmcnt(11)
	v_pk_add_f32 v[110:111], v[110:111], v[180:181]
	v_pk_add_f32 v[112:113], v[112:113], v[182:183]
	v_mul_f32_e32 v242, v111, v111
	v_fmac_f32_e32 v242, v110, v110
	v_fmac_f32_e32 v242, v112, v112
	v_fmac_f32_e32 v242, v113, v113
	v_add_f32_e32 v244, v244, v242
	global_load_dwordx4 v[180:183], v163, s[56:57]
	s_waitcnt vmcnt(11)
	v_pk_add_f32 v[106:107], v[106:107], v[184:185]
	v_pk_add_f32 v[108:109], v[108:109], v[186:187]
	v_mul_f32_e32 v242, v107, v107
	v_fmac_f32_e32 v242, v106, v106
	v_fmac_f32_e32 v242, v108, v108
	v_fmac_f32_e32 v242, v109, v109
	v_add_f32_e32 v244, v244, v242
	global_load_dwordx4 v[184:187], v163, s[56:57] offset:64
	s_waitcnt vmcnt(11)
	v_pk_add_f32 v[102:103], v[102:103], v[188:189]
	v_pk_add_f32 v[104:105], v[104:105], v[190:191]
	v_mul_f32_e32 v242, v103, v103
	v_fmac_f32_e32 v242, v102, v102
	v_fmac_f32_e32 v242, v104, v104
	v_fmac_f32_e32 v242, v105, v105
	v_add_f32_e32 v244, v244, v242
	global_load_dwordx4 v[188:191], v163, s[56:57] offset:128
	s_waitcnt vmcnt(11)
	v_pk_add_f32 v[90:91], v[90:91], v[192:193]
	v_pk_add_f32 v[92:93], v[92:93], v[194:195]
	v_mul_f32_e32 v242, v91, v91
	v_fmac_f32_e32 v242, v90, v90
	v_fmac_f32_e32 v242, v92, v92
	v_fmac_f32_e32 v242, v93, v93
	v_add_f32_e32 v244, v244, v242
	global_load_dwordx4 v[192:195], v163, s[56:57] offset:192
	s_waitcnt vmcnt(11)
	v_pk_add_f32 v[98:99], v[98:99], v[196:197]
	v_pk_add_f32 v[100:101], v[100:101], v[198:199]
	v_mul_f32_e32 v245, v99, v99
	v_fmac_f32_e32 v245, v98, v98
	v_fmac_f32_e32 v245, v100, v100
	v_fmac_f32_e32 v245, v101, v101
	global_load_dwordx4 v[196:199], v163, s[56:57] offset:256
	s_waitcnt vmcnt(11)
	v_pk_add_f32 v[94:95], v[94:95], v[216:217]
	v_pk_add_f32 v[96:97], v[96:97], v[218:219]
	v_mul_f32_e32 v242, v95, v95
	v_fmac_f32_e32 v242, v94, v94
	v_fmac_f32_e32 v242, v96, v96
	v_fmac_f32_e32 v242, v97, v97
	v_add_f32_e32 v245, v245, v242
	global_load_dwordx4 v[216:219], v163, s[56:57] offset:320
	s_waitcnt vmcnt(11)
	v_pk_add_f32 v[86:87], v[86:87], v[220:221]
	v_pk_add_f32 v[88:89], v[88:89], v[222:223]
	v_mul_f32_e32 v242, v87, v87
	v_fmac_f32_e32 v242, v86, v86
	v_fmac_f32_e32 v242, v88, v88
	v_fmac_f32_e32 v242, v89, v89
	v_add_f32_e32 v245, v245, v242
	global_load_dwordx4 v[220:223], v163, s[56:57] offset:384
	s_waitcnt vmcnt(11)
	v_pk_add_f32 v[82:83], v[82:83], v[224:225]
	v_pk_add_f32 v[84:85], v[84:85], v[226:227]
	v_mul_f32_e32 v242, v83, v83
	v_fmac_f32_e32 v242, v82, v82
	v_fmac_f32_e32 v242, v84, v84
	v_fmac_f32_e32 v242, v85, v85
	v_add_f32_e32 v245, v245, v242
	global_load_dwordx4 v[224:227], v163, s[56:57] offset:448
	s_waitcnt vmcnt(11)
	v_pk_add_f32 v[78:79], v[78:79], v[164:165]
	v_pk_add_f32 v[80:81], v[80:81], v[166:167]
	v_mul_f32_e32 v242, v79, v79
	v_fmac_f32_e32 v242, v78, v78
	v_fmac_f32_e32 v242, v80, v80
	v_fmac_f32_e32 v242, v81, v81
	v_add_f32_e32 v245, v245, v242
	global_load_dwordx4 v[164:167], v205, s[56:57]
	s_waitcnt vmcnt(11)
; DI unsigned pk2(float lo, float hi) { f32x2 v = {lo, hi}; bf16x2_t b = __builtin_convertvector(v, bf16x2_t); return __builtin_bit_cast(unsigned, b); }
; DI void phaseE(const Params& p0, const Slot sl, int layer, unsigned char* lds, const float* xsrc) {
;     ...
;     for (int j = 0; j < 4; ++j) {
;       const long tok = (long)mt * 256 + wb * 64 + j * 16 + qi;
;       float ss = 0.f;
; #pragma unroll
;       for (int i = 0; i < 8; ++i) {
;         const long off = tok * 1024 + nt * 256 + wa * 128 + i * 16 + quad * 4;
;         const f32x4 xo = *(const f32x4*)(xsrc + off);
;         const f32x4 xn = xo + acc[i][j];
;         *(f32x4*)(p.out + off) = xn;
;         *(u32x2*)(p.xb() + off + tok * (LDX - D_MODEL)) = (u32x2){pk2(xn[0], xn[1]), pk2(xn[2], xn[3])};
;         ss += xn[0] * xn[0] + xn[1] * xn[1] + xn[2] * xn[2] + xn[3] * xn[3];
;       }
;       ss += __shfl_xor(ss, 16); ss += __shfl_xor(ss, 32);
;       if (quad == 0) p.part()[tok * 16 + nt * 2 + wa] = ss;
;     }
	v_pk_add_f32 v[74:75], v[74:75], v[168:169]
	v_pk_add_f32 v[76:77], v[76:77], v[170:171]
	v_mul_f32_e32 v242, v75, v75
	v_fmac_f32_e32 v242, v74, v74
	v_fmac_f32_e32 v242, v76, v76
	v_fmac_f32_e32 v242, v77, v77
	v_add_f32_e32 v245, v245, v242
	global_load_dwordx4 v[168:171], v205, s[56:57] offset:64
	s_waitcnt vmcnt(11)
	v_pk_add_f32 v[70:71], v[70:71], v[172:173]
	v_pk_add_f32 v[72:73], v[72:73], v[174:175]
	v_mul_f32_e32 v242, v71, v71
	v_fmac_f32_e32 v242, v70, v70
	v_fmac_f32_e32 v242, v72, v72
	v_fmac_f32_e32 v242, v73, v73
	v_add_f32_e32 v245, v245, v242
	global_load_dwordx4 v[172:175], v205, s[56:57] offset:128
	s_waitcnt vmcnt(11)
	v_pk_add_f32 v[58:59], v[58:59], v[176:177]
	v_pk_add_f32 v[60:61], v[60:61], v[178:179]
	v_mul_f32_e32 v242, v59, v59
	v_fmac_f32_e32 v242, v58, v58
	v_fmac_f32_e32 v242, v60, v60
	v_fmac_f32_e32 v242, v61, v61
	v_add_f32_e32 v245, v245, v242
	global_load_dwordx4 v[176:179], v205, s[56:57] offset:192
	s_waitcnt vmcnt(11)
	v_pk_add_f32 v[66:67], v[66:67], v[180:181]
	v_pk_add_f32 v[68:69], v[68:69], v[182:183]
	v_mul_f32_e32 v246, v67, v67
	v_fmac_f32_e32 v246, v66, v66
	v_fmac_f32_e32 v246, v68, v68
	v_fmac_f32_e32 v246, v69, v69
	global_load_dwordx4 v[180:183], v205, s[56:57] offset:256
	s_waitcnt vmcnt(11)
	v_pk_add_f32 v[62:63], v[62:63], v[184:185]
	v_pk_add_f32 v[64:65], v[64:65], v[186:187]
	v_mul_f32_e32 v242, v63, v63
	v_fmac_f32_e32 v242, v62, v62
	v_fmac_f32_e32 v242, v64, v64
	v_fmac_f32_e32 v242, v65, v65
	v_add_f32_e32 v246, v246, v242
	global_load_dwordx4 v[184:187], v205, s[56:57] offset:320
	s_waitcnt vmcnt(11)
	v_pk_add_f32 v[54:55], v[54:55], v[188:189]
	v_pk_add_f32 v[56:57], v[56:57], v[190:191]
	v_mul_f32_e32 v242, v55, v55
	v_fmac_f32_e32 v242, v54, v54
	v_fmac_f32_e32 v242, v56, v56
	v_fmac_f32_e32 v242, v57, v57
	v_add_f32_e32 v246, v246, v242
	global_load_dwordx4 v[188:191], v205, s[56:57] offset:384
	s_waitcnt vmcnt(11)
	v_pk_add_f32 v[50:51], v[50:51], v[192:193]
	v_pk_add_f32 v[52:53], v[52:53], v[194:195]
	v_mul_f32_e32 v242, v51, v51
	v_fmac_f32_e32 v242, v50, v50
	v_fmac_f32_e32 v242, v52, v52
	v_fmac_f32_e32 v242, v53, v53
	v_add_f32_e32 v246, v246, v242
	global_load_dwordx4 v[192:195], v205, s[56:57] offset:448
	v_cvt_pk_bf16_f32 v248, v126, v127
	v_cvt_pk_bf16_f32 v249, v128, v129
	v_cvt_pk_bf16_f32 v250, v122, v123
	v_cvt_pk_bf16_f32 v251, v124, v125
	global_store_dwordx4 v130, v[126:129], s[90:91]
	global_store_dwordx4 v130, v[122:125], s[90:91] offset:64
	v_permlane16_swap_b32_e32 v248, v250
	v_permlane16_swap_b32_e32 v249, v251
	global_store_dwordx4 v200, v[248:251], s[14:15]
	v_cvt_pk_bf16_f32 v206, v118, v119
	v_cvt_pk_bf16_f32 v207, v120, v121
	v_cvt_pk_bf16_f32 v208, v114, v115
	v_cvt_pk_bf16_f32 v209, v116, v117
	global_store_dwordx4 v130, v[118:121], s[90:91] offset:128
	global_store_dwordx4 v130, v[114:117], s[90:91] offset:192
	v_permlane16_swap_b32_e32 v206, v208
	v_permlane16_swap_b32_e32 v207, v209
	global_store_dwordx4 v200, v[206:209], s[14:15] offset:64
	ds_bpermute_b32 v242, v239, v244
	s_waitcnt lgkmcnt(0)
	v_add_f32_e32 v244, v244, v242
	ds_bpermute_b32 v242, v243, v244
	s_waitcnt lgkmcnt(0)
	v_add_f32_e32 v244, v244, v242
	v_cmp_eq_u32_e32 vcc, 0, v231
	s_nop 0
	s_and_saveexec_b64 s[10:11], vcc
	global_store_dword v230, v244, s[16:17]
	s_mov_b64 exec, s[10:11]
	s_waitcnt vmcnt(18)
	v_pk_add_f32 v[46:47], v[46:47], v[196:197]
	v_pk_add_f32 v[48:49], v[48:49], v[198:199]
	v_mul_f32_e32 v242, v47, v47
	v_fmac_f32_e32 v242, v46, v46
	v_fmac_f32_e32 v242, v48, v48
	v_fmac_f32_e32 v242, v49, v49
	v_add_f32_e32 v246, v246, v242
	s_waitcnt vmcnt(17)
	v_pk_add_f32 v[42:43], v[42:43], v[216:217]
	v_pk_add_f32 v[44:45], v[44:45], v[218:219]
	v_mul_f32_e32 v242, v43, v43
	v_fmac_f32_e32 v242, v42, v42
	v_fmac_f32_e32 v242, v44, v44
	v_fmac_f32_e32 v242, v45, v45
	v_add_f32_e32 v246, v246, v242
	v_cvt_pk_bf16_f32 v248, v110, v111
	v_cvt_pk_bf16_f32 v249, v112, v113
	v_cvt_pk_bf16_f32 v250, v106, v107
	v_cvt_pk_bf16_f32 v251, v108, v109
	global_store_dwordx4 v130, v[110:113], s[90:91] offset:256
	global_store_dwordx4 v130, v[106:109], s[90:91] offset:320
	v_permlane16_swap_b32_e32 v248, v250
	v_permlane16_swap_b32_e32 v249, v251
	global_store_dwordx4 v200, v[248:251], s[14:15] offset:128
	v_cvt_pk_bf16_f32 v206, v102, v103
	v_cvt_pk_bf16_f32 v207, v104, v105
	v_cvt_pk_bf16_f32 v208, v90, v91
	v_cvt_pk_bf16_f32 v209, v92, v93
	global_store_dwordx4 v130, v[102:105], s[90:91] offset:384
	global_store_dwordx4 v130, v[90:93], s[90:91] offset:448
	v_permlane16_swap_b32_e32 v206, v208
	v_permlane16_swap_b32_e32 v207, v209
	global_store_dwordx4 v200, v[206:209], s[14:15] offset:192
	ds_bpermute_b32 v242, v239, v245
	s_waitcnt lgkmcnt(0)
	v_add_f32_e32 v245, v245, v242
	ds_bpermute_b32 v242, v243, v245
	s_waitcnt lgkmcnt(0)
	v_add_f32_e32 v245, v245, v242
	v_cmp_eq_u32_e32 vcc, 0, v231
	s_nop 0
	s_and_saveexec_b64 s[10:11], vcc
	global_store_dword v230, v245, s[16:17] offset:1024
	s_mov_b64 exec, s[10:11]
	s_waitcnt vmcnt(23)
	v_pk_add_f32 v[38:39], v[38:39], v[220:221]
	v_pk_add_f32 v[40:41], v[40:41], v[222:223]
	v_mul_f32_e32 v242, v39, v39
	v_fmac_f32_e32 v242, v38, v38
	v_fmac_f32_e32 v242, v40, v40
	v_fmac_f32_e32 v242, v41, v41
	v_add_f32_e32 v246, v246, v242
	s_waitcnt vmcnt(22)
; DI unsigned pk2(float lo, float hi) { f32x2 v = {lo, hi}; bf16x2_t b = __builtin_convertvector(v, bf16x2_t); return __builtin_bit_cast(unsigned, b); }
; DI void phaseE(const Params& p0, const Slot sl, int layer, unsigned char* lds, const float* xsrc) {
;     ...
;     for (int j = 0; j < 4; ++j) {
;       const long tok = (long)mt * 256 + wb * 64 + j * 16 + qi;
;       float ss = 0.f;
; #pragma unroll
;       for (int i = 0; i < 8; ++i) {
;         const long off = tok * 1024 + nt * 256 + wa * 128 + i * 16 + quad * 4;
;         const f32x4 xo = *(const f32x4*)(xsrc + off);
;         const f32x4 xn = xo + acc[i][j];
;         *(f32x4*)(p.out + off) = xn;
;         *(u32x2*)(p.xb() + off + tok * (LDX - D_MODEL)) = (u32x2){pk2(xn[0], xn[1]), pk2(xn[2], xn[3])};
;         ss += xn[0] * xn[0] + xn[1] * xn[1] + xn[2] * xn[2] + xn[3] * xn[3];
;       }
;       ss += __shfl_xor(ss, 16); ss += __shfl_xor(ss, 32);
;       if (quad == 0) p.part()[tok * 16 + nt * 2 + wa] = ss;
;     }
	v_pk_add_f32 v[26:27], v[26:27], v[224:225]
	v_pk_add_f32 v[28:29], v[28:29], v[226:227]
	v_mul_f32_e32 v242, v27, v27
	v_fmac_f32_e32 v242, v26, v26
	v_fmac_f32_e32 v242, v28, v28
	v_fmac_f32_e32 v242, v29, v29
	v_add_f32_e32 v246, v246, v242
	v_cvt_pk_bf16_f32 v248, v98, v99
	v_cvt_pk_bf16_f32 v249, v100, v101
	v_cvt_pk_bf16_f32 v250, v94, v95
	v_cvt_pk_bf16_f32 v251, v96, v97
	global_store_dwordx4 v161, v[98:101], s[90:91]
	global_store_dwordx4 v161, v[94:97], s[90:91] offset:64
	v_permlane16_swap_b32_e32 v248, v250
	v_permlane16_swap_b32_e32 v249, v251
	global_store_dwordx4 v201, v[248:251], s[14:15]
	v_cvt_pk_bf16_f32 v206, v86, v87
	v_cvt_pk_bf16_f32 v207, v88, v89
	v_cvt_pk_bf16_f32 v208, v82, v83
	v_cvt_pk_bf16_f32 v209, v84, v85
	global_store_dwordx4 v161, v[86:89], s[90:91] offset:128
	global_store_dwordx4 v161, v[82:85], s[90:91] offset:192
	v_permlane16_swap_b32_e32 v206, v208
	v_permlane16_swap_b32_e32 v207, v209
	global_store_dwordx4 v201, v[206:209], s[14:15] offset:64
	ds_bpermute_b32 v242, v239, v246
	s_waitcnt lgkmcnt(0)
	v_add_f32_e32 v246, v246, v242
	ds_bpermute_b32 v242, v243, v246
	s_waitcnt lgkmcnt(0)
	v_add_f32_e32 v246, v246, v242
	v_cmp_eq_u32_e32 vcc, 0, v231
	s_nop 0
	s_and_saveexec_b64 s[10:11], vcc
	global_store_dword v230, v246, s[16:17] offset:2048
	s_mov_b64 exec, s[10:11]
	s_waitcnt vmcnt(28)
	v_pk_add_f32 v[34:35], v[34:35], v[164:165]
	v_pk_add_f32 v[36:37], v[36:37], v[166:167]
	v_mul_f32_e32 v247, v35, v35
	v_fmac_f32_e32 v247, v34, v34
	v_fmac_f32_e32 v247, v36, v36
	v_fmac_f32_e32 v247, v37, v37
	s_waitcnt vmcnt(27)
	v_pk_add_f32 v[30:31], v[30:31], v[168:169]
	v_pk_add_f32 v[32:33], v[32:33], v[170:171]
	v_mul_f32_e32 v242, v31, v31
	v_fmac_f32_e32 v242, v30, v30
	v_fmac_f32_e32 v242, v32, v32
	v_fmac_f32_e32 v242, v33, v33
	v_add_f32_e32 v247, v247, v242
	v_cvt_pk_bf16_f32 v248, v78, v79
	v_cvt_pk_bf16_f32 v249, v80, v81
	v_cvt_pk_bf16_f32 v250, v74, v75
	v_cvt_pk_bf16_f32 v251, v76, v77
	global_store_dwordx4 v161, v[78:81], s[90:91] offset:256
	global_store_dwordx4 v161, v[74:77], s[90:91] offset:320
	v_permlane16_swap_b32_e32 v248, v250
	v_permlane16_swap_b32_e32 v249, v251
	global_store_dwordx4 v201, v[248:251], s[14:15] offset:128
	v_cvt_pk_bf16_f32 v206, v70, v71
	v_cvt_pk_bf16_f32 v207, v72, v73
	v_cvt_pk_bf16_f32 v208, v58, v59
	v_cvt_pk_bf16_f32 v209, v60, v61
	global_store_dwordx4 v161, v[70:73], s[90:91] offset:384
	global_store_dwordx4 v161, v[58:61], s[90:91] offset:448
	v_permlane16_swap_b32_e32 v206, v208
	v_permlane16_swap_b32_e32 v207, v209
	global_store_dwordx4 v201, v[206:209], s[14:15] offset:192
	s_waitcnt vmcnt(32)
	v_pk_add_f32 v[22:23], v[22:23], v[172:173]
	v_pk_add_f32 v[24:25], v[24:25], v[174:175]
	v_mul_f32_e32 v242, v23, v23
	v_fmac_f32_e32 v242, v22, v22
	v_fmac_f32_e32 v242, v24, v24
	v_fmac_f32_e32 v242, v25, v25
	v_add_f32_e32 v247, v247, v242
	s_waitcnt vmcnt(31)
	v_pk_add_f32 v[18:19], v[18:19], v[176:177]
	v_pk_add_f32 v[20:21], v[20:21], v[178:179]
	v_mul_f32_e32 v242, v19, v19
	v_fmac_f32_e32 v242, v18, v18
	v_fmac_f32_e32 v242, v20, v20
	v_fmac_f32_e32 v242, v21, v21
	v_add_f32_e32 v247, v247, v242
	v_cvt_pk_bf16_f32 v248, v66, v67
	v_cvt_pk_bf16_f32 v249, v68, v69
	v_cvt_pk_bf16_f32 v250, v62, v63
	v_cvt_pk_bf16_f32 v251, v64, v65
	global_store_dwordx4 v163, v[66:69], s[90:91]
	global_store_dwordx4 v163, v[62:65], s[90:91] offset:64
	v_permlane16_swap_b32_e32 v248, v250
	v_permlane16_swap_b32_e32 v249, v251
	global_store_dwordx4 v158, v[248:251], s[14:15]
	v_cvt_pk_bf16_f32 v206, v54, v55
	v_cvt_pk_bf16_f32 v207, v56, v57
	v_cvt_pk_bf16_f32 v208, v50, v51
	v_cvt_pk_bf16_f32 v209, v52, v53
	global_store_dwordx4 v163, v[54:57], s[90:91] offset:128
	global_store_dwordx4 v163, v[50:53], s[90:91] offset:192
	v_permlane16_swap_b32_e32 v206, v208
	v_permlane16_swap_b32_e32 v207, v209
	global_store_dwordx4 v158, v[206:209], s[14:15] offset:64
	s_waitcnt vmcnt(36)
; DI unsigned pk2(float lo, float hi) { f32x2 v = {lo, hi}; bf16x2_t b = __builtin_convertvector(v, bf16x2_t); return __builtin_bit_cast(unsigned, b); }
; DI void phaseE(const Params& p0, const Slot sl, int layer, unsigned char* lds, const float* xsrc) {
;     ...
;     for (int j = 0; j < 4; ++j) {
;       const long tok = (long)mt * 256 + wb * 64 + j * 16 + qi;
;       float ss = 0.f;
; #pragma unroll
;       for (int i = 0; i < 8; ++i) {
;         const long off = tok * 1024 + nt * 256 + wa * 128 + i * 16 + quad * 4;
;         const f32x4 xo = *(const f32x4*)(xsrc + off);
;         const f32x4 xn = xo + acc[i][j];
;         *(f32x4*)(p.out + off) = xn;
;         *(u32x2*)(p.xb() + off + tok * (LDX - D_MODEL)) = (u32x2){pk2(xn[0], xn[1]), pk2(xn[2], xn[3])};
;         ss += xn[0] * xn[0] + xn[1] * xn[1] + xn[2] * xn[2] + xn[3] * xn[3];
;       }
;       ss += __shfl_xor(ss, 16); ss += __shfl_xor(ss, 32);
;       if (quad == 0) p.part()[tok * 16 + nt * 2 + wa] = ss;
;     }
	v_pk_add_f32 v[14:15], v[14:15], v[180:181]
	v_pk_add_f32 v[16:17], v[16:17], v[182:183]
	v_mul_f32_e32 v242, v15, v15
	v_fmac_f32_e32 v242, v14, v14
	v_fmac_f32_e32 v242, v16, v16
	v_fmac_f32_e32 v242, v17, v17
	v_add_f32_e32 v247, v247, v242
	s_waitcnt vmcnt(35)
	v_pk_add_f32 v[10:11], v[10:11], v[184:185]
	v_pk_add_f32 v[12:13], v[12:13], v[186:187]
	v_mul_f32_e32 v242, v11, v11
	v_fmac_f32_e32 v242, v10, v10
	v_fmac_f32_e32 v242, v12, v12
	v_fmac_f32_e32 v242, v13, v13
	v_add_f32_e32 v247, v247, v242
	v_cvt_pk_bf16_f32 v248, v46, v47
	v_cvt_pk_bf16_f32 v249, v48, v49
	v_cvt_pk_bf16_f32 v250, v42, v43
	v_cvt_pk_bf16_f32 v251, v44, v45
	global_store_dwordx4 v163, v[46:49], s[90:91] offset:256
	global_store_dwordx4 v163, v[42:45], s[90:91] offset:320
	v_permlane16_swap_b32_e32 v248, v250
	v_permlane16_swap_b32_e32 v249, v251
	global_store_dwordx4 v158, v[248:251], s[14:15] offset:128
	v_cvt_pk_bf16_f32 v206, v38, v39
	v_cvt_pk_bf16_f32 v207, v40, v41
	v_cvt_pk_bf16_f32 v208, v26, v27
	v_cvt_pk_bf16_f32 v209, v28, v29
	global_store_dwordx4 v163, v[38:41], s[90:91] offset:384
	global_store_dwordx4 v163, v[26:29], s[90:91] offset:448
	v_permlane16_swap_b32_e32 v206, v208
	v_permlane16_swap_b32_e32 v207, v209
	global_store_dwordx4 v158, v[206:209], s[14:15] offset:192
	s_waitcnt vmcnt(40)
	v_pk_add_f32 v[6:7], v[6:7], v[188:189]
	v_pk_add_f32 v[8:9], v[8:9], v[190:191]
	v_mul_f32_e32 v242, v7, v7
	v_fmac_f32_e32 v242, v6, v6
	v_fmac_f32_e32 v242, v8, v8
	v_fmac_f32_e32 v242, v9, v9
	v_add_f32_e32 v247, v247, v242
	s_waitcnt vmcnt(39)
	v_pk_add_f32 v[2:3], v[2:3], v[192:193]
	v_pk_add_f32 v[4:5], v[4:5], v[194:195]
	v_mul_f32_e32 v242, v3, v3
	v_fmac_f32_e32 v242, v2, v2
	v_fmac_f32_e32 v242, v4, v4
	v_fmac_f32_e32 v242, v5, v5
	v_add_f32_e32 v247, v247, v242
	v_cvt_pk_bf16_f32 v248, v34, v35
	v_cvt_pk_bf16_f32 v249, v36, v37
	v_cvt_pk_bf16_f32 v250, v30, v31
	v_cvt_pk_bf16_f32 v251, v32, v33
	global_store_dwordx4 v205, v[34:37], s[90:91]
	global_store_dwordx4 v205, v[30:33], s[90:91] offset:64
	v_permlane16_swap_b32_e32 v248, v250
	v_permlane16_swap_b32_e32 v249, v251
	global_store_dwordx4 v159, v[248:251], s[14:15]
	v_cvt_pk_bf16_f32 v206, v22, v23
	v_cvt_pk_bf16_f32 v207, v24, v25
	v_cvt_pk_bf16_f32 v208, v18, v19
	v_cvt_pk_bf16_f32 v209, v20, v21
	global_store_dwordx4 v205, v[22:25], s[90:91] offset:128
	global_store_dwordx4 v205, v[18:21], s[90:91] offset:192
	v_permlane16_swap_b32_e32 v206, v208
	v_permlane16_swap_b32_e32 v207, v209
	global_store_dwordx4 v159, v[206:209], s[14:15] offset:64
	ds_bpermute_b32 v242, v239, v247
	s_waitcnt lgkmcnt(0)
	v_add_f32_e32 v247, v247, v242
	ds_bpermute_b32 v242, v243, v247
	s_waitcnt lgkmcnt(0)
	v_add_f32_e32 v247, v247, v242
	v_cmp_eq_u32_e32 vcc, 0, v231
	s_nop 0
	s_and_saveexec_b64 s[10:11], vcc
	global_store_dword v230, v247, s[16:17] offset:3072
	s_mov_b64 exec, s[10:11]
	v_cvt_pk_bf16_f32 v248, v14, v15
	v_cvt_pk_bf16_f32 v249, v16, v17
	v_cvt_pk_bf16_f32 v250, v10, v11
	v_cvt_pk_bf16_f32 v251, v12, v13
	global_store_dwordx4 v205, v[14:17], s[90:91] offset:256
	global_store_dwordx4 v205, v[10:13], s[90:91] offset:320
	v_permlane16_swap_b32_e32 v248, v250
	v_permlane16_swap_b32_e32 v249, v251
	global_store_dwordx4 v159, v[248:251], s[14:15] offset:128
	v_cvt_pk_bf16_f32 v206, v6, v7
	v_cvt_pk_bf16_f32 v207, v8, v9
	v_cvt_pk_bf16_f32 v208, v2, v3
	v_cvt_pk_bf16_f32 v209, v4, v5
	global_store_dwordx4 v205, v[6:9], s[90:91] offset:384
	global_store_dwordx4 v205, v[2:5], s[90:91] offset:448
	v_permlane16_swap_b32_e32 v206, v208
	v_permlane16_swap_b32_e32 v207, v209
	global_store_dwordx4 v159, v[206:209], s[14:15] offset:192
	s_mov_b64 s[8:9], exec
	s_branch .LBB0_960

; DI int my_tid() { int t = threadIdx.x; asm volatile("" : "+v"(t)); return t; }
;   unsigned char* lds = (unsigned char*)ldsb;
;   const int tid = my_tid(), lane = tid & 63, w = __builtin_amdgcn_readfirstlane(tid >> 6), wa = w >> 2, wb = w & 3, qi = lane & 15, quad = lane >> 4;
;   const bf16_t* base = w >= 4 ? Bg : Ag; const int ld = (int)(w >= 4 ? ldb : lda);
;   const bf16_t* nbase = nAg ? (w >= 4 ? nBg : nAg) : base;
;   unsigned off[8];
; #pragma unroll
;   for (int u = 0; u < 8; ++u) {
;     const int blk = (w & 3) * 8 + u, rg = blk >> 1, kh = blk & 1;
;     int R = rg * 16 + (lane >> 2);
;     if (perm) { const int rho = R & 31; R = (R & ~31) + ((rho >> 2) & 3) * 8 + (rho >> 4) * 4 + (rho & 3); }
;     off[u] = (unsigned)(R * ld + kh * 32 + (lane & 3) * 8);
;   }
;   const int ra = (wa * 8) * 2 * 1024 + (qi * 4 + quad) * 16, rb = (wb * 4) * 2 * 1024 + (qi * 4 + quad) * 16;
;   unsigned char* buf0 = lds; unsigned char* buf1 = lds + STAGE_B;
;   const int KT = K >> 6;
;   if (!pre) {
;     g_dma(base, off, 0, buf0, w);
;     asm volatile("s_waitcnt vmcnt(0)" ::: "memory");
;     __syncthreads();
;   }
;   for (int kt = 0; kt < KT; kt += 2) {
;     g_dma(base, off, (kt + 1) * kstep, buf1, w);
; DI void phaseE(const Params& p0, const Slot sl, int layer, unsigned char* lds, const float* xsrc) {
;     ...
;     f32x4 acc[8][4]; zero_acc(acc);
;     int mt2, nt2;
;     const bool more = tile_order(sl, it + 1, 4, mt2, nt2);
;     const bf16_t* Wg = p.wout_t() + ((long)nt * 256) * 1024; const bf16_t* Mg = p.merged() + (long)mt * 256 * 1024;
;     gemm_core(Wg, 1024, Mg, 1024, 1024, gl, acc, 64, it > 0, more ? p.wout_t() + ((long)nt2 * 256) * 1024 : Wg, more ? p.merged() + (long)mt2 * 256 * 1024 : Mg);
.LBB0_991:
	v_ashrrev_i32_e32 v131, 31, v130
	v_lshlrev_b64 v[10:11], 19, v[130:131]
	v_lshl_add_u64 v[10:11], s[0:1], 0, v[10:11]
	v_ashrrev_i32_e32 v133, 31, v132
	v_cndmask_b32_e64 v0, v4, v10, s[8:9]
	v_cndmask_b32_e64 v9, v5, v11, s[8:9]
	v_lshlrev_b64 v[4:5], 19, v[132:133]
	s_and_b64 s[10:11], exec, s[10:11]
	v_lshl_add_u64 v[4:5], s[4:5], 0, v[4:5]
	s_or_b64 s[18:19], s[10:11], s[18:19]
	v_cndmask_b32_e64 v2, v2, v4, s[8:9]
	v_cndmask_b32_e64 v3, v3, v5, s[8:9]
	v_and_b32_e32 v4, 48, v8
	v_cndmask_b32_e64 v142, v0, v2, s[12:13]
	s_lshl_b32 s8, s36, 6
	v_lshlrev_b32_e32 v0, 6, v8
	s_movk_i32 s9, 0x3c0
	s_and_b32 s8, s8, 0xffffc000
	v_and_or_b32 v0, v0, s9, v4
	v_or_b32_e32 v133, s8, v0
	s_add_i32 s8, s29, 0xc020
	v_lshl_or_b32 v166, s30, 13, v0
	v_add_u32_e32 v0, s8, v7
	v_add_lshl_u32 v0, v0, v6, 1
	s_add_i32 s8, s29, 0xc000
	v_lshl_add_u64 v[144:145], v[0:1], 0, s[6:7]
	v_add_u32_e32 v0, s8, v7
	v_add_lshl_u32 v0, v0, v6, 1
	s_add_i32 s8, s29, 0x8020
	v_lshl_add_u64 v[146:147], v[0:1], 0, s[6:7]
	v_add_u32_e32 v0, s8, v7
	v_add_lshl_u32 v0, v0, v6, 1
	s_add_i32 s8, s29, 0x8000
	v_lshl_add_u64 v[148:149], v[0:1], 0, s[6:7]
	v_add_u32_e32 v0, s8, v7
	v_add_lshl_u32 v0, v0, v6, 1
	s_add_i32 s8, s29, 0x4020
	v_lshl_add_u64 v[150:151], v[0:1], 0, s[6:7]
	v_add_u32_e32 v0, s8, v7
	v_add_lshl_u32 v0, v0, v6, 1
	s_add_i32 s8, s29, 0x4000
	v_lshl_add_u64 v[152:153], v[0:1], 0, s[6:7]
	v_add_u32_e32 v0, s8, v7
	v_add_lshl_u32 v0, v0, v6, 1
	v_lshl_add_u64 v[154:155], v[0:1], 0, s[6:7]
	v_add3_u32 v0, s29, 32, v7
	v_add_lshl_u32 v0, v0, v6, 1
	v_lshl_add_u64 v[156:157], v[0:1], 0, s[6:7]
	v_add_u32_e32 v0, s29, v7
	v_add_lshl_u32 v0, v0, v6, 1
	v_mov_b32_e32 v2, 0
	v_cndmask_b32_e64 v131, v9, v3, s[12:13]
	v_lshl_add_u64 v[158:159], v[0:1], 0, s[6:7]
	s_mov_b32 s9, 0
	s_movk_i32 s8, 0x80
	v_mov_b32_e32 v3, v2
	v_mov_b32_e32 v4, v2
	v_mov_b32_e32 v5, v2
	v_mov_b32_e32 v26, v2
	v_mov_b32_e32 v27, v2
	v_mov_b32_e32 v28, v2
	v_mov_b32_e32 v29, v2
	v_mov_b32_e32 v62, v2
	v_mov_b32_e32 v63, v2
	v_mov_b32_e32 v64, v2
	v_mov_b32_e32 v65, v2
	v_mov_b32_e32 v94, v2
	v_mov_b32_e32 v95, v2
	v_mov_b32_e32 v96, v2
	v_mov_b32_e32 v97, v2
	v_mov_b32_e32 v6, v2
	v_mov_b32_e32 v7, v2
	v_mov_b32_e32 v8, v2
	v_mov_b32_e32 v9, v2
	v_mov_b32_e32 v38, v2
	v_mov_b32_e32 v39, v2
	v_mov_b32_e32 v40, v2
	v_mov_b32_e32 v41, v2
	v_mov_b32_e32 v70, v2
	v_mov_b32_e32 v71, v2
	v_mov_b32_e32 v72, v2
	v_mov_b32_e32 v73, v2
	v_mov_b32_e32 v102, v2
	v_mov_b32_e32 v103, v2
	v_mov_b32_e32 v104, v2
	v_mov_b32_e32 v105, v2
	v_mov_b32_e32 v10, v2
	v_mov_b32_e32 v11, v2
	v_mov_b32_e32 v12, v2
	v_mov_b32_e32 v13, v2
	v_mov_b32_e32 v42, v2
	v_mov_b32_e32 v43, v2
	v_mov_b32_e32 v44, v2
	v_mov_b32_e32 v45, v2
	v_mov_b32_e32 v74, v2
	v_mov_b32_e32 v75, v2
	v_mov_b32_e32 v76, v2
	v_mov_b32_e32 v77, v2
	v_mov_b32_e32 v106, v2
	v_mov_b32_e32 v107, v2
	v_mov_b32_e32 v108, v2
	v_mov_b32_e32 v109, v2
	v_mov_b32_e32 v14, v2
	v_mov_b32_e32 v15, v2
	v_mov_b32_e32 v16, v2
	v_mov_b32_e32 v17, v2
	v_mov_b32_e32 v46, v2
	v_mov_b32_e32 v47, v2
	v_mov_b32_e32 v48, v2
	v_mov_b32_e32 v49, v2
	v_mov_b32_e32 v78, v2
	v_mov_b32_e32 v79, v2
	v_mov_b32_e32 v80, v2
	v_mov_b32_e32 v81, v2
	v_mov_b32_e32 v110, v2
	v_mov_b32_e32 v111, v2
	v_mov_b32_e32 v112, v2
	v_mov_b32_e32 v113, v2
	v_mov_b32_e32 v18, v2
	v_mov_b32_e32 v19, v2
	v_mov_b32_e32 v20, v2
	v_mov_b32_e32 v21, v2
	v_mov_b32_e32 v50, v2
	v_mov_b32_e32 v51, v2
	v_mov_b32_e32 v52, v2
	v_mov_b32_e32 v53, v2
	v_mov_b32_e32 v82, v2
	v_mov_b32_e32 v83, v2
	v_mov_b32_e32 v84, v2
	v_mov_b32_e32 v85, v2
	v_mov_b32_e32 v114, v2
	v_mov_b32_e32 v115, v2
	v_mov_b32_e32 v116, v2
	v_mov_b32_e32 v117, v2
	s_waitcnt vmcnt(0)
	v_mov_b32_e32 v22, v2
	v_mov_b32_e32 v23, v2
	v_mov_b32_e32 v24, v2
	v_mov_b32_e32 v25, v2
	v_mov_b32_e32 v54, v2
	v_mov_b32_e32 v55, v2
	v_mov_b32_e32 v56, v2
	v_mov_b32_e32 v57, v2
	v_mov_b32_e32 v86, v2
	v_mov_b32_e32 v87, v2
	v_mov_b32_e32 v88, v2
	v_mov_b32_e32 v89, v2
	v_mov_b32_e32 v118, v2
	v_mov_b32_e32 v119, v2
	v_mov_b32_e32 v120, v2
	v_mov_b32_e32 v121, v2
	v_mov_b32_e32 v30, v2
	v_mov_b32_e32 v31, v2
	v_mov_b32_e32 v32, v2
	v_mov_b32_e32 v33, v2
	v_mov_b32_e32 v58, v2
	v_mov_b32_e32 v59, v2
	v_mov_b32_e32 v60, v2
	v_mov_b32_e32 v61, v2
	v_mov_b32_e32 v90, v2
	v_mov_b32_e32 v91, v2
	v_mov_b32_e32 v92, v2
	v_mov_b32_e32 v93, v2
	v_mov_b32_e32 v122, v2
	v_mov_b32_e32 v123, v2
	v_mov_b32_e32 v124, v2
	v_mov_b32_e32 v125, v2
	v_mov_b32_e32 v34, v2
	v_mov_b32_e32 v35, v2
	v_mov_b32_e32 v36, v2
	v_mov_b32_e32 v37, v2
	v_mov_b32_e32 v66, v2
	v_mov_b32_e32 v67, v2
	v_mov_b32_e32 v68, v2
	v_mov_b32_e32 v69, v2
	v_mov_b32_e32 v98, v2
	v_mov_b32_e32 v99, v2
	v_mov_b32_e32 v100, v2
	v_mov_b32_e32 v101, v2
	v_mov_b32_e32 v126, v2
	v_mov_b32_e32 v127, v2
	v_mov_b32_e32 v128, v2
	v_mov_b32_e32 v129, v2
	v_lshlrev_b32_e32 v144, 1, v135
	v_add_u32_e32 v152, 32, v133
	v_add_u32_e32 v153, 0x10020, v133
	v_add_u32_e32 v154, 0x8020, v166
	v_add_u32_e32 v155, 0x18020, v166
	v_readfirstlane_b32 s38, v138
	v_readfirstlane_b32 s39, v139
	v_readfirstlane_b32 s40, v142
	v_readfirstlane_b32 s41, v131
	v_add_u32_e32 v145, 0x40, v144
	v_add_u32_e32 v146, 0x8000, v144
	v_add_u32_e32 v147, 0x8040, v144
	v_add_u32_e32 v148, 0x10000, v144
	v_add_u32_e32 v149, 0x10040, v144
	v_add_u32_e32 v150, 0x18000, v144
	v_add_u32_e32 v151, 0x18040, v144
	s_add_i32 s42, s28, 32
	s_add_i32 s43, s28, s35
	s_add_u32 s38, s38, 0x80
	s_addc_u32 s39, s39, 0
	s_add_i32 m0, s43, 0x0
	s_nop 0
	global_load_lds_dwordx4 v144, s[38:39]
	s_add_i32 m0, s43, 0x400
	s_nop 0
	global_load_lds_dwordx4 v145, s[38:39]
	s_add_i32 m0, s43, 0x800
	s_nop 0
	global_load_lds_dwordx4 v146, s[38:39]
	s_add_i32 m0, s43, 0xc00
	s_nop 0
	global_load_lds_dwordx4 v147, s[38:39]
	s_add_i32 m0, s43, 0x1000
	s_nop 0
	global_load_lds_dwordx4 v148, s[38:39]
	s_add_i32 m0, s43, 0x1400
	s_nop 0
	global_load_lds_dwordx4 v149, s[38:39]
	s_add_i32 m0, s43, 0x1800
	s_nop 0
	global_load_lds_dwordx4 v150, s[38:39]
	s_add_i32 m0, s43, 0x1c00
	s_nop 0
	global_load_lds_dwordx4 v151, s[38:39]
	s_add_u32 s38, s38, 0x80
	s_addc_u32 s39, s39, 0
	ds_read_b128 v[168:171], v154
	ds_read_b128 v[172:175], v154 offset:2048
	ds_read_b128 v[176:179], v154 offset:4096
	ds_read_b128 v[180:183], v154 offset:6144
	ds_read_b128 v[184:187], v152
	ds_read_b128 v[188:191], v152 offset:2048
	ds_read_b128 v[192:195], v152 offset:4096
	ds_read_b128 v[196:199], v152 offset:6144
	s_mov_b32 s46, 0
; DI int my_tid() { int t = threadIdx.x; asm volatile("" : "+v"(t)); return t; }
; #define G_LDA(dst, ih, ks) _Pragma("unroll") for (int i = 0; i < 4; ++i) dst[i] = mk8(*(const u32x4*)(stage + ra + (((ih) * 4 + i) * 2 + (ks)) * 1024))
; #define G_LDB(dst, ks) _Pragma("unroll") for (int j = 0; j < 4; ++j) dst[j] = mk8(*(const u32x4*)(stage + TILE_B + rb + (j * 2 + (ks)) * 1024))
; DI void g_compute(const unsigned char* stage, int ra, int rb, f32x4 (&acc)[8][4]) {
;   bf16x8 b0[4], b1[4], a0[4], a1[4];
;   G_LDB(b0, 0); G_LDA(a0, 0, 0);
;   __builtin_amdgcn_sched_barrier(0);
;   G_LDA(a1, 1, 0);
;   G_MMA(0, a0, b0);
;   __builtin_amdgcn_sched_barrier(0);
;   G_LDB(b1, 1); G_LDA(a0, 0, 1);
;   G_MMA(1, a1, b0);
;   __builtin_amdgcn_sched_barrier(0);
;   G_LDA(a1, 1, 1);
;   G_MMA(0, a0, b1);
;   __builtin_amdgcn_sched_barrier(0);
;   G_MMA(1, a1, b1);
;   __builtin_amdgcn_sched_barrier(0);
; }
;   unsigned char* lds = (unsigned char*)ldsb;
;   const int tid = my_tid(), lane = tid & 63, w = __builtin_amdgcn_readfirstlane(tid >> 6), wa = w >> 2, wb = w & 3, qi = lane & 15, quad = lane >> 4;
;   const bf16_t* base = w >= 4 ? Bg : Ag; const int ld = (int)(w >= 4 ? ldb : lda);
;   const bf16_t* nbase = nAg ? (w >= 4 ? nBg : nAg) : base;
;   unsigned off[8];
; #pragma unroll
;   for (int u = 0; u < 8; ++u) {
;     const int blk = (w & 3) * 8 + u, rg = blk >> 1, kh = blk & 1;
;     int R = rg * 16 + (lane >> 2);
;     if (perm) { const int rho = R & 31; R = (R & ~31) + ((rho >> 2) & 3) * 8 + (rho >> 4) * 4 + (rho & 3); }
;     off[u] = (unsigned)(R * ld + kh * 32 + (lane & 3) * 8);
;   }
;   const int ra = (wa * 8) * 2 * 1024 + (qi * 4 + quad) * 16, rb = (wb * 4) * 2 * 1024 + (qi * 4 + quad) * 16;
;   unsigned char* buf0 = lds; unsigned char* buf1 = lds + STAGE_B;
;   const int KT = K >> 6;
;   if (!pre) {
;     g_dma(base, off, 0, buf0, w);
;     asm volatile("s_waitcnt vmcnt(0)" ::: "memory");
;     __syncthreads();
;   }
;   for (int kt = 0; kt < KT; kt += 2) {
;     g_dma(base, off, (kt + 1) * kstep, buf1, w);
;     g_compute(buf0, ra, rb, acc);
;     asm volatile("s_waitcnt vmcnt(0)" ::: "memory");
;     __syncthreads();
;     const bool last = kt + 2 >= KT;
;     g_dma(last ? nbase : base, off, last ? 0 : (kt + 2) * kstep, buf0, w);
;     g_compute(buf1, ra, rb, acc);
;     asm volatile("s_waitcnt vmcnt(0)" ::: "memory");
;     __syncthreads();
;   }
.LgE1_loop:
	s_waitcnt lgkmcnt(0)
	v_mfma_f32_16x16x32_bf16 v[126:129], v[184:187], v[168:171], v[126:129]
	v_mfma_f32_16x16x32_bf16 v[98:101], v[184:187], v[172:175], v[98:101]
	ds_read_b128 v[200:203], v152 offset:8192
	v_mfma_f32_16x16x32_bf16 v[66:69], v[184:187], v[176:179], v[66:69]
	v_mfma_f32_16x16x32_bf16 v[34:37], v[184:187], v[180:183], v[34:37]
	v_mfma_f32_16x16x32_bf16 v[122:125], v[188:191], v[168:171], v[122:125]
	ds_read_b128 v[204:207], v152 offset:10240
	v_mfma_f32_16x16x32_bf16 v[90:93], v[188:191], v[172:175], v[90:93]
	v_mfma_f32_16x16x32_bf16 v[58:61], v[188:191], v[176:179], v[58:61]
	v_mfma_f32_16x16x32_bf16 v[30:33], v[188:191], v[180:183], v[30:33]
	ds_read_b128 v[216:219], v152 offset:12288
	v_mfma_f32_16x16x32_bf16 v[118:121], v[192:195], v[168:171], v[118:121]
	v_mfma_f32_16x16x32_bf16 v[86:89], v[192:195], v[172:175], v[86:89]
	v_mfma_f32_16x16x32_bf16 v[54:57], v[192:195], v[176:179], v[54:57]
	ds_read_b128 v[220:223], v152 offset:14336
	v_mfma_f32_16x16x32_bf16 v[22:25], v[192:195], v[180:183], v[22:25]
	v_mfma_f32_16x16x32_bf16 v[114:117], v[196:199], v[168:171], v[114:117]
	v_mfma_f32_16x16x32_bf16 v[82:85], v[196:199], v[172:175], v[82:85]
	v_mfma_f32_16x16x32_bf16 v[50:53], v[196:199], v[176:179], v[50:53]
	v_mfma_f32_16x16x32_bf16 v[18:21], v[196:199], v[180:183], v[18:21]
	s_waitcnt lgkmcnt(0)
	v_mfma_f32_16x16x32_bf16 v[110:113], v[200:203], v[168:171], v[110:113]
	ds_read_b128 v[224:227], v154 offset:1024
	v_mfma_f32_16x16x32_bf16 v[78:81], v[200:203], v[172:175], v[78:81]
	v_mfma_f32_16x16x32_bf16 v[46:49], v[200:203], v[176:179], v[46:49]
	ds_read_b128 v[240:243], v154 offset:3072
	v_mfma_f32_16x16x32_bf16 v[14:17], v[200:203], v[180:183], v[14:17]
	v_mfma_f32_16x16x32_bf16 v[106:109], v[204:207], v[168:171], v[106:109]
	ds_read_b128 v[244:247], v154 offset:5120
	v_mfma_f32_16x16x32_bf16 v[74:77], v[204:207], v[172:175], v[74:77]
	v_mfma_f32_16x16x32_bf16 v[42:45], v[204:207], v[176:179], v[42:45]
	ds_read_b128 v[248:251], v154 offset:7168
	v_mfma_f32_16x16x32_bf16 v[10:13], v[204:207], v[180:183], v[10:13]
	v_mfma_f32_16x16x32_bf16 v[102:105], v[216:219], v[168:171], v[102:105]
	ds_read_b128 v[184:187], v152 offset:1024
	v_mfma_f32_16x16x32_bf16 v[70:73], v[216:219], v[172:175], v[70:73]
	ds_read_b128 v[188:191], v152 offset:3072
	v_mfma_f32_16x16x32_bf16 v[38:41], v[216:219], v[176:179], v[38:41]
	ds_read_b128 v[192:195], v152 offset:5120
	v_mfma_f32_16x16x32_bf16 v[6:9], v[216:219], v[180:183], v[6:9]
	ds_read_b128 v[196:199], v152 offset:7168
	v_mfma_f32_16x16x32_bf16 v[94:97], v[220:223], v[168:171], v[94:97]
	v_mfma_f32_16x16x32_bf16 v[62:65], v[220:223], v[172:175], v[62:65]
	v_mfma_f32_16x16x32_bf16 v[26:29], v[220:223], v[176:179], v[26:29]
	v_mfma_f32_16x16x32_bf16 v[2:5], v[220:223], v[180:183], v[2:5]
	s_waitcnt lgkmcnt(0)
	v_mfma_f32_16x16x32_bf16 v[126:129], v[184:187], v[224:227], v[126:129]
	v_mfma_f32_16x16x32_bf16 v[98:101], v[184:187], v[240:243], v[98:101]
	ds_read_b128 v[200:203], v152 offset:9216
	v_mfma_f32_16x16x32_bf16 v[66:69], v[184:187], v[244:247], v[66:69]
	v_mfma_f32_16x16x32_bf16 v[34:37], v[184:187], v[248:251], v[34:37]
	v_mfma_f32_16x16x32_bf16 v[122:125], v[188:191], v[224:227], v[122:125]
	ds_read_b128 v[204:207], v152 offset:11264
	v_mfma_f32_16x16x32_bf16 v[90:93], v[188:191], v[240:243], v[90:93]
	v_mfma_f32_16x16x32_bf16 v[58:61], v[188:191], v[244:247], v[58:61]
	v_mfma_f32_16x16x32_bf16 v[30:33], v[188:191], v[248:251], v[30:33]
	ds_read_b128 v[216:219], v152 offset:13312
	v_mfma_f32_16x16x32_bf16 v[118:121], v[192:195], v[224:227], v[118:121]
	v_mfma_f32_16x16x32_bf16 v[86:89], v[192:195], v[240:243], v[86:89]
	v_mfma_f32_16x16x32_bf16 v[54:57], v[192:195], v[244:247], v[54:57]
	ds_read_b128 v[220:223], v152 offset:15360
	v_mfma_f32_16x16x32_bf16 v[22:25], v[192:195], v[248:251], v[22:25]
	v_mfma_f32_16x16x32_bf16 v[114:117], v[196:199], v[224:227], v[114:117]
	v_mfma_f32_16x16x32_bf16 v[82:85], v[196:199], v[240:243], v[82:85]
	v_mfma_f32_16x16x32_bf16 v[50:53], v[196:199], v[244:247], v[50:53]
	v_mfma_f32_16x16x32_bf16 v[18:21], v[196:199], v[248:251], v[18:21]
	s_waitcnt lgkmcnt(0)
	s_waitcnt vmcnt(0)
	s_barrier
	s_add_i32 m0, s42, 0x0
	v_mfma_f32_16x16x32_bf16 v[110:113], v[200:203], v[224:227], v[110:113]
	global_load_lds_dwordx4 v144, s[38:39]
	ds_read_b128 v[168:171], v155
	v_mfma_f32_16x16x32_bf16 v[78:81], v[200:203], v[240:243], v[78:81]
	ds_read_b128 v[172:175], v155 offset:2048
	s_add_i32 m0, s42, 0x400
	v_mfma_f32_16x16x32_bf16 v[46:49], v[200:203], v[244:247], v[46:49]
	global_load_lds_dwordx4 v145, s[38:39]
	ds_read_b128 v[176:179], v155 offset:4096
	v_mfma_f32_16x16x32_bf16 v[14:17], v[200:203], v[248:251], v[14:17]
	ds_read_b128 v[180:183], v155 offset:6144
	s_add_i32 m0, s42, 0x800
	v_mfma_f32_16x16x32_bf16 v[106:109], v[204:207], v[224:227], v[106:109]
	global_load_lds_dwordx4 v146, s[38:39]
	ds_read_b128 v[184:187], v153
	v_mfma_f32_16x16x32_bf16 v[74:77], v[204:207], v[240:243], v[74:77]
	ds_read_b128 v[188:191], v153 offset:2048
	s_add_i32 m0, s42, 0xc00
	v_mfma_f32_16x16x32_bf16 v[42:45], v[204:207], v[244:247], v[42:45]
	global_load_lds_dwordx4 v147, s[38:39]
	ds_read_b128 v[192:195], v153 offset:4096
	v_mfma_f32_16x16x32_bf16 v[10:13], v[204:207], v[248:251], v[10:13]
	ds_read_b128 v[196:199], v153 offset:6144
	s_add_i32 m0, s42, 0x1000
	v_mfma_f32_16x16x32_bf16 v[102:105], v[216:219], v[224:227], v[102:105]
	global_load_lds_dwordx4 v148, s[38:39]
	v_mfma_f32_16x16x32_bf16 v[70:73], v[216:219], v[240:243], v[70:73]
	s_add_i32 m0, s42, 0x1400
	v_mfma_f32_16x16x32_bf16 v[38:41], v[216:219], v[244:247], v[38:41]
	global_load_lds_dwordx4 v149, s[38:39]
	v_mfma_f32_16x16x32_bf16 v[6:9], v[216:219], v[248:251], v[6:9]
	s_add_i32 m0, s42, 0x1800
	v_mfma_f32_16x16x32_bf16 v[94:97], v[220:223], v[224:227], v[94:97]
	global_load_lds_dwordx4 v150, s[38:39]
	v_mfma_f32_16x16x32_bf16 v[62:65], v[220:223], v[240:243], v[62:65]
	s_add_i32 m0, s42, 0x1c00
	v_mfma_f32_16x16x32_bf16 v[26:29], v[220:223], v[244:247], v[26:29]
	global_load_lds_dwordx4 v151, s[38:39]
	v_mfma_f32_16x16x32_bf16 v[2:5], v[220:223], v[248:251], v[2:5]
	s_add_u32 s38, s38, 0x80
	s_addc_u32 s39, s39, 0
	s_waitcnt lgkmcnt(0)
; DI int my_tid() { int t = threadIdx.x; asm volatile("" : "+v"(t)); return t; }
; #define G_LDA(dst, ih, ks) _Pragma("unroll") for (int i = 0; i < 4; ++i) dst[i] = mk8(*(const u32x4*)(stage + ra + (((ih) * 4 + i) * 2 + (ks)) * 1024))
; #define G_LDB(dst, ks) _Pragma("unroll") for (int j = 0; j < 4; ++j) dst[j] = mk8(*(const u32x4*)(stage + TILE_B + rb + (j * 2 + (ks)) * 1024))
; DI void g_compute(const unsigned char* stage, int ra, int rb, f32x4 (&acc)[8][4]) {
;   bf16x8 b0[4], b1[4], a0[4], a1[4];
;   G_LDB(b0, 0); G_LDA(a0, 0, 0);
;   __builtin_amdgcn_sched_barrier(0);
;   G_LDA(a1, 1, 0);
;   G_MMA(0, a0, b0);
;   __builtin_amdgcn_sched_barrier(0);
;   G_LDB(b1, 1); G_LDA(a0, 0, 1);
;   G_MMA(1, a1, b0);
;   __builtin_amdgcn_sched_barrier(0);
;   G_LDA(a1, 1, 1);
;   G_MMA(0, a0, b1);
;   __builtin_amdgcn_sched_barrier(0);
;   G_MMA(1, a1, b1);
;   __builtin_amdgcn_sched_barrier(0);
; }
;   unsigned char* lds = (unsigned char*)ldsb;
;   const int tid = my_tid(), lane = tid & 63, w = __builtin_amdgcn_readfirstlane(tid >> 6), wa = w >> 2, wb = w & 3, qi = lane & 15, quad = lane >> 4;
;   const bf16_t* base = w >= 4 ? Bg : Ag; const int ld = (int)(w >= 4 ? ldb : lda);
;   const bf16_t* nbase = nAg ? (w >= 4 ? nBg : nAg) : base;
;   unsigned off[8];
; #pragma unroll
;   for (int u = 0; u < 8; ++u) {
;     const int blk = (w & 3) * 8 + u, rg = blk >> 1, kh = blk & 1;
;     int R = rg * 16 + (lane >> 2);
;     if (perm) { const int rho = R & 31; R = (R & ~31) + ((rho >> 2) & 3) * 8 + (rho >> 4) * 4 + (rho & 3); }
;     off[u] = (unsigned)(R * ld + kh * 32 + (lane & 3) * 8);
;   }
;   const int ra = (wa * 8) * 2 * 1024 + (qi * 4 + quad) * 16, rb = (wb * 4) * 2 * 1024 + (qi * 4 + quad) * 16;
;   unsigned char* buf0 = lds; unsigned char* buf1 = lds + STAGE_B;
;   const int KT = K >> 6;
;   if (!pre) {
;     g_dma(base, off, 0, buf0, w);
;     asm volatile("s_waitcnt vmcnt(0)" ::: "memory");
;     __syncthreads();
;   }
;   for (int kt = 0; kt < KT; kt += 2) {
;     g_dma(base, off, (kt + 1) * kstep, buf1, w);
;     g_compute(buf0, ra, rb, acc);
;     asm volatile("s_waitcnt vmcnt(0)" ::: "memory");
;     __syncthreads();
;     const bool last = kt + 2 >= KT;
;     g_dma(last ? nbase : base, off, last ? 0 : (kt + 2) * kstep, buf0, w);
;     g_compute(buf1, ra, rb, acc);
;     asm volatile("s_waitcnt vmcnt(0)" ::: "memory");
;     __syncthreads();
;   }
	v_mfma_f32_16x16x32_bf16 v[126:129], v[184:187], v[168:171], v[126:129]
	v_mfma_f32_16x16x32_bf16 v[98:101], v[184:187], v[172:175], v[98:101]
	ds_read_b128 v[200:203], v153 offset:8192
	v_mfma_f32_16x16x32_bf16 v[66:69], v[184:187], v[176:179], v[66:69]
	v_mfma_f32_16x16x32_bf16 v[34:37], v[184:187], v[180:183], v[34:37]
	v_mfma_f32_16x16x32_bf16 v[122:125], v[188:191], v[168:171], v[122:125]
	ds_read_b128 v[204:207], v153 offset:10240
	v_mfma_f32_16x16x32_bf16 v[90:93], v[188:191], v[172:175], v[90:93]
	v_mfma_f32_16x16x32_bf16 v[58:61], v[188:191], v[176:179], v[58:61]
	v_mfma_f32_16x16x32_bf16 v[30:33], v[188:191], v[180:183], v[30:33]
	ds_read_b128 v[216:219], v153 offset:12288
	v_mfma_f32_16x16x32_bf16 v[118:121], v[192:195], v[168:171], v[118:121]
	v_mfma_f32_16x16x32_bf16 v[86:89], v[192:195], v[172:175], v[86:89]
	v_mfma_f32_16x16x32_bf16 v[54:57], v[192:195], v[176:179], v[54:57]
	ds_read_b128 v[220:223], v153 offset:14336
	v_mfma_f32_16x16x32_bf16 v[22:25], v[192:195], v[180:183], v[22:25]
	v_mfma_f32_16x16x32_bf16 v[114:117], v[196:199], v[168:171], v[114:117]
	v_mfma_f32_16x16x32_bf16 v[82:85], v[196:199], v[172:175], v[82:85]
	v_mfma_f32_16x16x32_bf16 v[50:53], v[196:199], v[176:179], v[50:53]
	v_mfma_f32_16x16x32_bf16 v[18:21], v[196:199], v[180:183], v[18:21]
	s_waitcnt lgkmcnt(0)
	v_mfma_f32_16x16x32_bf16 v[110:113], v[200:203], v[168:171], v[110:113]
	ds_read_b128 v[224:227], v155 offset:1024
	v_mfma_f32_16x16x32_bf16 v[78:81], v[200:203], v[172:175], v[78:81]
	v_mfma_f32_16x16x32_bf16 v[46:49], v[200:203], v[176:179], v[46:49]
	ds_read_b128 v[240:243], v155 offset:3072
	v_mfma_f32_16x16x32_bf16 v[14:17], v[200:203], v[180:183], v[14:17]
	v_mfma_f32_16x16x32_bf16 v[106:109], v[204:207], v[168:171], v[106:109]
	ds_read_b128 v[244:247], v155 offset:5120
	v_mfma_f32_16x16x32_bf16 v[74:77], v[204:207], v[172:175], v[74:77]
	v_mfma_f32_16x16x32_bf16 v[42:45], v[204:207], v[176:179], v[42:45]
	ds_read_b128 v[248:251], v155 offset:7168
	v_mfma_f32_16x16x32_bf16 v[10:13], v[204:207], v[180:183], v[10:13]
	v_mfma_f32_16x16x32_bf16 v[102:105], v[216:219], v[168:171], v[102:105]
	ds_read_b128 v[184:187], v153 offset:1024
	v_mfma_f32_16x16x32_bf16 v[70:73], v[216:219], v[172:175], v[70:73]
	ds_read_b128 v[188:191], v153 offset:3072
	v_mfma_f32_16x16x32_bf16 v[38:41], v[216:219], v[176:179], v[38:41]
	ds_read_b128 v[192:195], v153 offset:5120
	v_mfma_f32_16x16x32_bf16 v[6:9], v[216:219], v[180:183], v[6:9]
	ds_read_b128 v[196:199], v153 offset:7168
	v_mfma_f32_16x16x32_bf16 v[94:97], v[220:223], v[168:171], v[94:97]
	v_mfma_f32_16x16x32_bf16 v[62:65], v[220:223], v[172:175], v[62:65]
	v_mfma_f32_16x16x32_bf16 v[26:29], v[220:223], v[176:179], v[26:29]
	v_mfma_f32_16x16x32_bf16 v[2:5], v[220:223], v[180:183], v[2:5]
	s_waitcnt lgkmcnt(0)
	v_mfma_f32_16x16x32_bf16 v[126:129], v[184:187], v[224:227], v[126:129]
	v_mfma_f32_16x16x32_bf16 v[98:101], v[184:187], v[240:243], v[98:101]
	ds_read_b128 v[200:203], v153 offset:9216
	v_mfma_f32_16x16x32_bf16 v[66:69], v[184:187], v[244:247], v[66:69]
	v_mfma_f32_16x16x32_bf16 v[34:37], v[184:187], v[248:251], v[34:37]
	v_mfma_f32_16x16x32_bf16 v[122:125], v[188:191], v[224:227], v[122:125]
	ds_read_b128 v[204:207], v153 offset:11264
	v_mfma_f32_16x16x32_bf16 v[90:93], v[188:191], v[240:243], v[90:93]
	v_mfma_f32_16x16x32_bf16 v[58:61], v[188:191], v[244:247], v[58:61]
	v_mfma_f32_16x16x32_bf16 v[30:33], v[188:191], v[248:251], v[30:33]
	ds_read_b128 v[216:219], v153 offset:13312
	v_mfma_f32_16x16x32_bf16 v[118:121], v[192:195], v[224:227], v[118:121]
	v_mfma_f32_16x16x32_bf16 v[86:89], v[192:195], v[240:243], v[86:89]
	v_mfma_f32_16x16x32_bf16 v[54:57], v[192:195], v[244:247], v[54:57]
	ds_read_b128 v[220:223], v153 offset:15360
	v_mfma_f32_16x16x32_bf16 v[22:25], v[192:195], v[248:251], v[22:25]
	v_mfma_f32_16x16x32_bf16 v[114:117], v[196:199], v[224:227], v[114:117]
	v_mfma_f32_16x16x32_bf16 v[82:85], v[196:199], v[240:243], v[82:85]
	v_mfma_f32_16x16x32_bf16 v[50:53], v[196:199], v[244:247], v[50:53]
	v_mfma_f32_16x16x32_bf16 v[18:21], v[196:199], v[248:251], v[18:21]
	s_waitcnt lgkmcnt(0)
	s_waitcnt vmcnt(0)
	s_barrier
	s_add_i32 m0, s43, 0x0
	v_mfma_f32_16x16x32_bf16 v[110:113], v[200:203], v[224:227], v[110:113]
	global_load_lds_dwordx4 v144, s[38:39]
	ds_read_b128 v[168:171], v154
	v_mfma_f32_16x16x32_bf16 v[78:81], v[200:203], v[240:243], v[78:81]
	ds_read_b128 v[172:175], v154 offset:2048
	s_add_i32 m0, s43, 0x400
	v_mfma_f32_16x16x32_bf16 v[46:49], v[200:203], v[244:247], v[46:49]
	global_load_lds_dwordx4 v145, s[38:39]
	ds_read_b128 v[176:179], v154 offset:4096
	v_mfma_f32_16x16x32_bf16 v[14:17], v[200:203], v[248:251], v[14:17]
	ds_read_b128 v[180:183], v154 offset:6144
	s_add_i32 m0, s43, 0x800
	v_mfma_f32_16x16x32_bf16 v[106:109], v[204:207], v[224:227], v[106:109]
	global_load_lds_dwordx4 v146, s[38:39]
	ds_read_b128 v[184:187], v152
	v_mfma_f32_16x16x32_bf16 v[74:77], v[204:207], v[240:243], v[74:77]
	ds_read_b128 v[188:191], v152 offset:2048
	s_add_i32 m0, s43, 0xc00
	v_mfma_f32_16x16x32_bf16 v[42:45], v[204:207], v[244:247], v[42:45]
	global_load_lds_dwordx4 v147, s[38:39]
	ds_read_b128 v[192:195], v152 offset:4096
	v_mfma_f32_16x16x32_bf16 v[10:13], v[204:207], v[248:251], v[10:13]
	ds_read_b128 v[196:199], v152 offset:6144
	s_add_i32 m0, s43, 0x1000
	v_mfma_f32_16x16x32_bf16 v[102:105], v[216:219], v[224:227], v[102:105]
	global_load_lds_dwordx4 v148, s[38:39]
	v_mfma_f32_16x16x32_bf16 v[70:73], v[216:219], v[240:243], v[70:73]
	s_add_i32 m0, s43, 0x1400
	v_mfma_f32_16x16x32_bf16 v[38:41], v[216:219], v[244:247], v[38:41]
	global_load_lds_dwordx4 v149, s[38:39]
	v_mfma_f32_16x16x32_bf16 v[6:9], v[216:219], v[248:251], v[6:9]
	s_add_i32 m0, s43, 0x1800
	v_mfma_f32_16x16x32_bf16 v[94:97], v[220:223], v[224:227], v[94:97]
	global_load_lds_dwordx4 v150, s[38:39]
	v_mfma_f32_16x16x32_bf16 v[62:65], v[220:223], v[240:243], v[62:65]
	s_add_i32 m0, s43, 0x1c00
	v_mfma_f32_16x16x32_bf16 v[26:29], v[220:223], v[244:247], v[26:29]
	global_load_lds_dwordx4 v151, s[38:39]
	v_mfma_f32_16x16x32_bf16 v[2:5], v[220:223], v[248:251], v[2:5]
	s_add_u32 s38, s38, 0x80
	s_addc_u32 s39, s39, 0
	s_add_i32 s46, s46, 1
	s_cmp_lt_u32 s46, 7
	s_cbranch_scc1 .LgE1_loop
; DI int my_tid() { int t = threadIdx.x; asm volatile("" : "+v"(t)); return t; }
; #define G_LDA(dst, ih, ks) _Pragma("unroll") for (int i = 0; i < 4; ++i) dst[i] = mk8(*(const u32x4*)(stage + ra + (((ih) * 4 + i) * 2 + (ks)) * 1024))
; #define G_LDB(dst, ks) _Pragma("unroll") for (int j = 0; j < 4; ++j) dst[j] = mk8(*(const u32x4*)(stage + TILE_B + rb + (j * 2 + (ks)) * 1024))
; DI void g_compute(const unsigned char* stage, int ra, int rb, f32x4 (&acc)[8][4]) {
;   bf16x8 b0[4], b1[4], a0[4], a1[4];
;   G_LDB(b0, 0); G_LDA(a0, 0, 0);
;   __builtin_amdgcn_sched_barrier(0);
;   G_LDA(a1, 1, 0);
;   G_MMA(0, a0, b0);
;   __builtin_amdgcn_sched_barrier(0);
;   G_LDB(b1, 1); G_LDA(a0, 0, 1);
;   G_MMA(1, a1, b0);
;   __builtin_amdgcn_sched_barrier(0);
;   G_LDA(a1, 1, 1);
;   G_MMA(0, a0, b1);
;   __builtin_amdgcn_sched_barrier(0);
;   G_MMA(1, a1, b1);
;   __builtin_amdgcn_sched_barrier(0);
; }
;   unsigned char* lds = (unsigned char*)ldsb;
;   const int tid = my_tid(), lane = tid & 63, w = __builtin_amdgcn_readfirstlane(tid >> 6), wa = w >> 2, wb = w & 3, qi = lane & 15, quad = lane >> 4;
;   const bf16_t* base = w >= 4 ? Bg : Ag; const int ld = (int)(w >= 4 ? ldb : lda);
;   const bf16_t* nbase = nAg ? (w >= 4 ? nBg : nAg) : base;
;   unsigned off[8];
; #pragma unroll
;   for (int u = 0; u < 8; ++u) {
;     const int blk = (w & 3) * 8 + u, rg = blk >> 1, kh = blk & 1;
;     int R = rg * 16 + (lane >> 2);
;     if (perm) { const int rho = R & 31; R = (R & ~31) + ((rho >> 2) & 3) * 8 + (rho >> 4) * 4 + (rho & 3); }
;     off[u] = (unsigned)(R * ld + kh * 32 + (lane & 3) * 8);
;   }
;   const int ra = (wa * 8) * 2 * 1024 + (qi * 4 + quad) * 16, rb = (wb * 4) * 2 * 1024 + (qi * 4 + quad) * 16;
;   unsigned char* buf0 = lds; unsigned char* buf1 = lds + STAGE_B;
;   const int KT = K >> 6;
;   if (!pre) {
;     g_dma(base, off, 0, buf0, w);
;     asm volatile("s_waitcnt vmcnt(0)" ::: "memory");
;     __syncthreads();
;   }
;   for (int kt = 0; kt < KT; kt += 2) {
;     g_dma(base, off, (kt + 1) * kstep, buf1, w);
;     g_compute(buf0, ra, rb, acc);
;     asm volatile("s_waitcnt vmcnt(0)" ::: "memory");
;     __syncthreads();
;     const bool last = kt + 2 >= KT;
;     g_dma(last ? nbase : base, off, last ? 0 : (kt + 2) * kstep, buf0, w);
;     g_compute(buf1, ra, rb, acc);
;     asm volatile("s_waitcnt vmcnt(0)" ::: "memory");
;     __syncthreads();
;   }
	s_waitcnt lgkmcnt(0)
	v_mfma_f32_16x16x32_bf16 v[126:129], v[184:187], v[168:171], v[126:129]
	v_mfma_f32_16x16x32_bf16 v[98:101], v[184:187], v[172:175], v[98:101]
	ds_read_b128 v[200:203], v152 offset:8192
	v_mfma_f32_16x16x32_bf16 v[66:69], v[184:187], v[176:179], v[66:69]
	v_mfma_f32_16x16x32_bf16 v[34:37], v[184:187], v[180:183], v[34:37]
	v_mfma_f32_16x16x32_bf16 v[122:125], v[188:191], v[168:171], v[122:125]
	ds_read_b128 v[204:207], v152 offset:10240
	v_mfma_f32_16x16x32_bf16 v[90:93], v[188:191], v[172:175], v[90:93]
	v_mfma_f32_16x16x32_bf16 v[58:61], v[188:191], v[176:179], v[58:61]
	v_mfma_f32_16x16x32_bf16 v[30:33], v[188:191], v[180:183], v[30:33]
	ds_read_b128 v[216:219], v152 offset:12288
	v_mfma_f32_16x16x32_bf16 v[118:121], v[192:195], v[168:171], v[118:121]
	v_mfma_f32_16x16x32_bf16 v[86:89], v[192:195], v[172:175], v[86:89]
	v_mfma_f32_16x16x32_bf16 v[54:57], v[192:195], v[176:179], v[54:57]
	ds_read_b128 v[220:223], v152 offset:14336
	v_mfma_f32_16x16x32_bf16 v[22:25], v[192:195], v[180:183], v[22:25]
	v_mfma_f32_16x16x32_bf16 v[114:117], v[196:199], v[168:171], v[114:117]
	v_mfma_f32_16x16x32_bf16 v[82:85], v[196:199], v[172:175], v[82:85]
	v_mfma_f32_16x16x32_bf16 v[50:53], v[196:199], v[176:179], v[50:53]
	v_mfma_f32_16x16x32_bf16 v[18:21], v[196:199], v[180:183], v[18:21]
	s_waitcnt lgkmcnt(0)
	v_mfma_f32_16x16x32_bf16 v[110:113], v[200:203], v[168:171], v[110:113]
	ds_read_b128 v[224:227], v154 offset:1024
	v_mfma_f32_16x16x32_bf16 v[78:81], v[200:203], v[172:175], v[78:81]
	v_mfma_f32_16x16x32_bf16 v[46:49], v[200:203], v[176:179], v[46:49]
	ds_read_b128 v[240:243], v154 offset:3072
	v_mfma_f32_16x16x32_bf16 v[14:17], v[200:203], v[180:183], v[14:17]
	v_mfma_f32_16x16x32_bf16 v[106:109], v[204:207], v[168:171], v[106:109]
	ds_read_b128 v[244:247], v154 offset:5120
	v_mfma_f32_16x16x32_bf16 v[74:77], v[204:207], v[172:175], v[74:77]
	v_mfma_f32_16x16x32_bf16 v[42:45], v[204:207], v[176:179], v[42:45]
	ds_read_b128 v[248:251], v154 offset:7168
	v_mfma_f32_16x16x32_bf16 v[10:13], v[204:207], v[180:183], v[10:13]
	v_mfma_f32_16x16x32_bf16 v[102:105], v[216:219], v[168:171], v[102:105]
	ds_read_b128 v[184:187], v152 offset:1024
	v_mfma_f32_16x16x32_bf16 v[70:73], v[216:219], v[172:175], v[70:73]
	ds_read_b128 v[188:191], v152 offset:3072
	v_mfma_f32_16x16x32_bf16 v[38:41], v[216:219], v[176:179], v[38:41]
	ds_read_b128 v[192:195], v152 offset:5120
	v_mfma_f32_16x16x32_bf16 v[6:9], v[216:219], v[180:183], v[6:9]
	ds_read_b128 v[196:199], v152 offset:7168
	v_mfma_f32_16x16x32_bf16 v[94:97], v[220:223], v[168:171], v[94:97]
	v_mfma_f32_16x16x32_bf16 v[62:65], v[220:223], v[172:175], v[62:65]
	v_mfma_f32_16x16x32_bf16 v[26:29], v[220:223], v[176:179], v[26:29]
	v_mfma_f32_16x16x32_bf16 v[2:5], v[220:223], v[180:183], v[2:5]
	s_waitcnt lgkmcnt(0)
	v_mfma_f32_16x16x32_bf16 v[126:129], v[184:187], v[224:227], v[126:129]
	v_mfma_f32_16x16x32_bf16 v[98:101], v[184:187], v[240:243], v[98:101]
	ds_read_b128 v[200:203], v152 offset:9216
	v_mfma_f32_16x16x32_bf16 v[66:69], v[184:187], v[244:247], v[66:69]
	v_mfma_f32_16x16x32_bf16 v[34:37], v[184:187], v[248:251], v[34:37]
	v_mfma_f32_16x16x32_bf16 v[122:125], v[188:191], v[224:227], v[122:125]
	ds_read_b128 v[204:207], v152 offset:11264
	v_mfma_f32_16x16x32_bf16 v[90:93], v[188:191], v[240:243], v[90:93]
	v_mfma_f32_16x16x32_bf16 v[58:61], v[188:191], v[244:247], v[58:61]
	v_mfma_f32_16x16x32_bf16 v[30:33], v[188:191], v[248:251], v[30:33]
	ds_read_b128 v[216:219], v152 offset:13312
	v_mfma_f32_16x16x32_bf16 v[118:121], v[192:195], v[224:227], v[118:121]
	v_mfma_f32_16x16x32_bf16 v[86:89], v[192:195], v[240:243], v[86:89]
	v_mfma_f32_16x16x32_bf16 v[54:57], v[192:195], v[244:247], v[54:57]
	ds_read_b128 v[220:223], v152 offset:15360
	v_mfma_f32_16x16x32_bf16 v[22:25], v[192:195], v[248:251], v[22:25]
	v_mfma_f32_16x16x32_bf16 v[114:117], v[196:199], v[224:227], v[114:117]
	v_mfma_f32_16x16x32_bf16 v[82:85], v[196:199], v[240:243], v[82:85]
	v_mfma_f32_16x16x32_bf16 v[50:53], v[196:199], v[244:247], v[50:53]
	v_mfma_f32_16x16x32_bf16 v[18:21], v[196:199], v[248:251], v[18:21]
	s_waitcnt lgkmcnt(0)
	s_waitcnt vmcnt(0)
	s_barrier
	s_add_i32 m0, s42, 0x0
	v_mfma_f32_16x16x32_bf16 v[110:113], v[200:203], v[224:227], v[110:113]
	global_load_lds_dwordx4 v144, s[40:41]
	ds_read_b128 v[168:171], v155
	v_mfma_f32_16x16x32_bf16 v[78:81], v[200:203], v[240:243], v[78:81]
	ds_read_b128 v[172:175], v155 offset:2048
	s_add_i32 m0, s42, 0x400
	v_mfma_f32_16x16x32_bf16 v[46:49], v[200:203], v[244:247], v[46:49]
	global_load_lds_dwordx4 v145, s[40:41]
	ds_read_b128 v[176:179], v155 offset:4096
	v_mfma_f32_16x16x32_bf16 v[14:17], v[200:203], v[248:251], v[14:17]
	ds_read_b128 v[180:183], v155 offset:6144
	s_add_i32 m0, s42, 0x800
	v_mfma_f32_16x16x32_bf16 v[106:109], v[204:207], v[224:227], v[106:109]
	global_load_lds_dwordx4 v146, s[40:41]
	ds_read_b128 v[184:187], v153
	v_mfma_f32_16x16x32_bf16 v[74:77], v[204:207], v[240:243], v[74:77]
	ds_read_b128 v[188:191], v153 offset:2048
	s_add_i32 m0, s42, 0xc00
	v_mfma_f32_16x16x32_bf16 v[42:45], v[204:207], v[244:247], v[42:45]
	global_load_lds_dwordx4 v147, s[40:41]
	ds_read_b128 v[192:195], v153 offset:4096
	v_mfma_f32_16x16x32_bf16 v[10:13], v[204:207], v[248:251], v[10:13]
	ds_read_b128 v[196:199], v153 offset:6144
	s_add_i32 m0, s42, 0x1000
	v_mfma_f32_16x16x32_bf16 v[102:105], v[216:219], v[224:227], v[102:105]
	global_load_lds_dwordx4 v148, s[40:41]
	v_mfma_f32_16x16x32_bf16 v[70:73], v[216:219], v[240:243], v[70:73]
	s_add_i32 m0, s42, 0x1400
	v_mfma_f32_16x16x32_bf16 v[38:41], v[216:219], v[244:247], v[38:41]
	global_load_lds_dwordx4 v149, s[40:41]
	v_mfma_f32_16x16x32_bf16 v[6:9], v[216:219], v[248:251], v[6:9]
	s_add_i32 m0, s42, 0x1800
	v_mfma_f32_16x16x32_bf16 v[94:97], v[220:223], v[224:227], v[94:97]
	global_load_lds_dwordx4 v150, s[40:41]
	v_mfma_f32_16x16x32_bf16 v[62:65], v[220:223], v[240:243], v[62:65]
	s_add_i32 m0, s42, 0x1c00
	v_mfma_f32_16x16x32_bf16 v[26:29], v[220:223], v[244:247], v[26:29]
	global_load_lds_dwordx4 v151, s[40:41]
	v_mfma_f32_16x16x32_bf16 v[2:5], v[220:223], v[248:251], v[2:5]
	s_add_u32 s40, s40, 0x80
	s_addc_u32 s41, s41, 0
	s_waitcnt lgkmcnt(0)
; DI void g_compute(const unsigned char* stage, int ra, int rb, f32x4 (&acc)[8][4]) {
;   bf16x8 b0[4], b1[4], a0[4], a1[4];
;   G_LDB(b0, 0); G_LDA(a0, 0, 0);
;   __builtin_amdgcn_sched_barrier(0);
;   G_LDA(a1, 1, 0);
;   G_MMA(0, a0, b0);
;   __builtin_amdgcn_sched_barrier(0);
;   G_LDB(b1, 1); G_LDA(a0, 0, 1);
;   G_MMA(1, a1, b0);
;   __builtin_amdgcn_sched_barrier(0);
;   G_LDA(a1, 1, 1);
;   G_MMA(0, a0, b1);
;   __builtin_amdgcn_sched_barrier(0);
;   G_MMA(1, a1, b1);
;   __builtin_amdgcn_sched_barrier(0);
; }
;   unsigned char* lds = (unsigned char*)ldsb;
;   const int tid = my_tid(), lane = tid & 63, w = __builtin_amdgcn_readfirstlane(tid >> 6), wa = w >> 2, wb = w & 3, qi = lane & 15, quad = lane >> 4;
;   const bf16_t* base = w >= 4 ? Bg : Ag; const int ld = (int)(w >= 4 ? ldb : lda);
;   const bf16_t* nbase = nAg ? (w >= 4 ? nBg : nAg) : base;
;   unsigned off[8];
; #pragma unroll
;   for (int u = 0; u < 8; ++u) {
;     const int blk = (w & 3) * 8 + u, rg = blk >> 1, kh = blk & 1;
;     int R = rg * 16 + (lane >> 2);
;     if (perm) { const int rho = R & 31; R = (R & ~31) + ((rho >> 2) & 3) * 8 + (rho >> 4) * 4 + (rho & 3); }
;     off[u] = (unsigned)(R * ld + kh * 32 + (lane & 3) * 8);
;   }
;   const int ra = (wa * 8) * 2 * 1024 + (qi * 4 + quad) * 16, rb = (wb * 4) * 2 * 1024 + (qi * 4 + quad) * 16;
;   unsigned char* buf0 = lds; unsigned char* buf1 = lds + STAGE_B;
;   const int KT = K >> 6;
;   if (!pre) {
;     g_dma(base, off, 0, buf0, w);
;     asm volatile("s_waitcnt vmcnt(0)" ::: "memory");
;     __syncthreads();
;   }
;   for (int kt = 0; kt < KT; kt += 2) {
;     g_dma(base, off, (kt + 1) * kstep, buf1, w);
;     g_compute(buf0, ra, rb, acc);
;     asm volatile("s_waitcnt vmcnt(0)" ::: "memory");
;     __syncthreads();
;     const bool last = kt + 2 >= KT;
;     g_dma(last ? nbase : base, off, last ? 0 : (kt + 2) * kstep, buf0, w);
;     g_compute(buf1, ra, rb, acc);
;     asm volatile("s_waitcnt vmcnt(0)" ::: "memory");
;     __syncthreads();
;   }
; DI void phaseE(const Params& p0, const Slot sl, int layer, unsigned char* lds, const float* xsrc) {
;     ...
;     const int tid = my_tid(), lane = tid & 63, w = tid >> 6, wa = w >> 2, wb = w & 3, qi = lane & 15, quad = lane >> 4;
; #pragma unroll
;     for (int j = 0; j < 4; ++j) {
;       const long tok = (long)mt * 256 + wb * 64 + j * 16 + qi;
;       float ss = 0.f;
; #pragma unroll
	v_mfma_f32_16x16x32_bf16 v[126:129], v[184:187], v[168:171], v[126:129]
	v_mfma_f32_16x16x32_bf16 v[98:101], v[184:187], v[172:175], v[98:101]
	ds_read_b128 v[200:203], v153 offset:8192
	v_mfma_f32_16x16x32_bf16 v[66:69], v[184:187], v[176:179], v[66:69]
	v_mfma_f32_16x16x32_bf16 v[34:37], v[184:187], v[180:183], v[34:37]
	v_mfma_f32_16x16x32_bf16 v[122:125], v[188:191], v[168:171], v[122:125]
	ds_read_b128 v[204:207], v153 offset:10240
	v_mfma_f32_16x16x32_bf16 v[90:93], v[188:191], v[172:175], v[90:93]
	v_mfma_f32_16x16x32_bf16 v[58:61], v[188:191], v[176:179], v[58:61]
	v_mfma_f32_16x16x32_bf16 v[30:33], v[188:191], v[180:183], v[30:33]
	ds_read_b128 v[216:219], v153 offset:12288
	v_mfma_f32_16x16x32_bf16 v[118:121], v[192:195], v[168:171], v[118:121]
	v_mfma_f32_16x16x32_bf16 v[86:89], v[192:195], v[172:175], v[86:89]
	v_mfma_f32_16x16x32_bf16 v[54:57], v[192:195], v[176:179], v[54:57]
	ds_read_b128 v[220:223], v153 offset:14336
	v_mfma_f32_16x16x32_bf16 v[22:25], v[192:195], v[180:183], v[22:25]
	v_mfma_f32_16x16x32_bf16 v[114:117], v[196:199], v[168:171], v[114:117]
	v_mfma_f32_16x16x32_bf16 v[82:85], v[196:199], v[172:175], v[82:85]
	v_mfma_f32_16x16x32_bf16 v[50:53], v[196:199], v[176:179], v[50:53]
	v_mfma_f32_16x16x32_bf16 v[18:21], v[196:199], v[180:183], v[18:21]
	s_waitcnt lgkmcnt(0)
	v_mfma_f32_16x16x32_bf16 v[110:113], v[200:203], v[168:171], v[110:113]
	ds_read_b128 v[224:227], v155 offset:1024
	v_mfma_f32_16x16x32_bf16 v[78:81], v[200:203], v[172:175], v[78:81]
	v_mfma_f32_16x16x32_bf16 v[46:49], v[200:203], v[176:179], v[46:49]
	ds_read_b128 v[240:243], v155 offset:3072
	v_mfma_f32_16x16x32_bf16 v[14:17], v[200:203], v[180:183], v[14:17]
	v_mfma_f32_16x16x32_bf16 v[106:109], v[204:207], v[168:171], v[106:109]
	ds_read_b128 v[244:247], v155 offset:5120
	v_mfma_f32_16x16x32_bf16 v[74:77], v[204:207], v[172:175], v[74:77]
	v_mfma_f32_16x16x32_bf16 v[42:45], v[204:207], v[176:179], v[42:45]
	ds_read_b128 v[248:251], v155 offset:7168
	v_mfma_f32_16x16x32_bf16 v[10:13], v[204:207], v[180:183], v[10:13]
	v_mfma_f32_16x16x32_bf16 v[102:105], v[216:219], v[168:171], v[102:105]
	ds_read_b128 v[184:187], v153 offset:1024
	v_mfma_f32_16x16x32_bf16 v[70:73], v[216:219], v[172:175], v[70:73]
	ds_read_b128 v[188:191], v153 offset:3072
	v_mfma_f32_16x16x32_bf16 v[38:41], v[216:219], v[176:179], v[38:41]
	ds_read_b128 v[192:195], v153 offset:5120
	v_mfma_f32_16x16x32_bf16 v[6:9], v[216:219], v[180:183], v[6:9]
	ds_read_b128 v[196:199], v153 offset:7168
	v_mfma_f32_16x16x32_bf16 v[94:97], v[220:223], v[168:171], v[94:97]
	v_mfma_f32_16x16x32_bf16 v[62:65], v[220:223], v[172:175], v[62:65]
	v_mfma_f32_16x16x32_bf16 v[26:29], v[220:223], v[176:179], v[26:29]
	v_mfma_f32_16x16x32_bf16 v[2:5], v[220:223], v[180:183], v[2:5]
	s_waitcnt lgkmcnt(0)
	v_mfma_f32_16x16x32_bf16 v[126:129], v[184:187], v[224:227], v[126:129]
	v_mfma_f32_16x16x32_bf16 v[98:101], v[184:187], v[240:243], v[98:101]
	ds_read_b128 v[200:203], v153 offset:9216
	v_mfma_f32_16x16x32_bf16 v[66:69], v[184:187], v[244:247], v[66:69]
	v_mfma_f32_16x16x32_bf16 v[34:37], v[184:187], v[248:251], v[34:37]
	v_mfma_f32_16x16x32_bf16 v[122:125], v[188:191], v[224:227], v[122:125]
	ds_read_b128 v[204:207], v153 offset:11264
	v_mfma_f32_16x16x32_bf16 v[90:93], v[188:191], v[240:243], v[90:93]
	v_mfma_f32_16x16x32_bf16 v[58:61], v[188:191], v[244:247], v[58:61]
	v_mfma_f32_16x16x32_bf16 v[30:33], v[188:191], v[248:251], v[30:33]
	ds_read_b128 v[216:219], v153 offset:13312
	v_mfma_f32_16x16x32_bf16 v[118:121], v[192:195], v[224:227], v[118:121]
	v_mfma_f32_16x16x32_bf16 v[86:89], v[192:195], v[240:243], v[86:89]
	v_mfma_f32_16x16x32_bf16 v[54:57], v[192:195], v[244:247], v[54:57]
	ds_read_b128 v[220:223], v153 offset:15360
	v_mfma_f32_16x16x32_bf16 v[22:25], v[192:195], v[248:251], v[22:25]
	v_mfma_f32_16x16x32_bf16 v[114:117], v[196:199], v[224:227], v[114:117]
	v_mfma_f32_16x16x32_bf16 v[82:85], v[196:199], v[240:243], v[82:85]
	v_mfma_f32_16x16x32_bf16 v[50:53], v[196:199], v[244:247], v[50:53]
	v_mfma_f32_16x16x32_bf16 v[18:21], v[196:199], v[248:251], v[18:21]
	s_waitcnt lgkmcnt(0)
	s_waitcnt vmcnt(0)
	s_barrier
	v_mfma_f32_16x16x32_bf16 v[110:113], v[200:203], v[224:227], v[110:113]
	v_mfma_f32_16x16x32_bf16 v[78:81], v[200:203], v[240:243], v[78:81]
	v_mfma_f32_16x16x32_bf16 v[46:49], v[200:203], v[244:247], v[46:49]
	v_mfma_f32_16x16x32_bf16 v[14:17], v[200:203], v[248:251], v[14:17]
	v_mfma_f32_16x16x32_bf16 v[106:109], v[204:207], v[224:227], v[106:109]
	v_mfma_f32_16x16x32_bf16 v[74:77], v[204:207], v[240:243], v[74:77]
	v_mfma_f32_16x16x32_bf16 v[42:45], v[204:207], v[244:247], v[42:45]
	v_mfma_f32_16x16x32_bf16 v[10:13], v[204:207], v[248:251], v[10:13]
	v_mfma_f32_16x16x32_bf16 v[102:105], v[216:219], v[224:227], v[102:105]
	v_mfma_f32_16x16x32_bf16 v[70:73], v[216:219], v[240:243], v[70:73]
	v_mfma_f32_16x16x32_bf16 v[38:41], v[216:219], v[244:247], v[38:41]
	v_mfma_f32_16x16x32_bf16 v[6:9], v[216:219], v[248:251], v[6:9]
	v_mfma_f32_16x16x32_bf16 v[94:97], v[220:223], v[224:227], v[94:97]
	v_mfma_f32_16x16x32_bf16 v[62:65], v[220:223], v[240:243], v[62:65]
	v_mfma_f32_16x16x32_bf16 v[26:29], v[220:223], v[244:247], v[26:29]
	v_mfma_f32_16x16x32_bf16 v[2:5], v[220:223], v[248:251], v[2:5]
	s_nop 7
	s_nop 3
	v_readlane_b32 s56, v253, 8
	v_readlane_b32 s57, v253, 9
	v_and_b32_e32 v248, 0xc0, v210
	v_and_b32_e32 v249, 15, v210
	v_lshl_or_b32 v248, v136, 8, v248
	v_or_b32_e32 v248, v248, v249
	v_ashrrev_i32_e32 v249, 8, v210
	v_bfe_u32 v231, v210, 4, 2
	v_lshlrev_b32_e32 v251, 8, v134
	v_lshl_or_b32 v251, v249, 7, v251
	v_lshl_or_b32 v251, v231, 2, v251
	v_lshlrev_b32_e32 v130, 12, v248
; DI unsigned pk2(float lo, float hi) { f32x2 v = {lo, hi}; bf16x2_t b = __builtin_convertvector(v, bf16x2_t); return __builtin_bit_cast(unsigned, b); }
; DI int my_tid() { int t = threadIdx.x; asm volatile("" : "+v"(t)); return t; }
; DI void phaseE(const Params& p0, const Slot sl, int layer, unsigned char* lds, const float* xsrc) {
;     ...
;     const int tid = my_tid(), lane = tid & 63, w = tid >> 6, wa = w >> 2, wb = w & 3, qi = lane & 15, quad = lane >> 4;
; #pragma unroll
;     for (int j = 0; j < 4; ++j) {
;       const long tok = (long)mt * 256 + wb * 64 + j * 16 + qi;
;       float ss = 0.f;
; #pragma unroll
;       for (int i = 0; i < 8; ++i) {
;         const long off = tok * 1024 + nt * 256 + wa * 128 + i * 16 + quad * 4;
;         const f32x4 xo = *(const f32x4*)(xsrc + off);
;         const f32x4 xn = xo + acc[i][j];
;         *(f32x4*)(p.out + off) = xn;
;         *(u32x2*)(p.xb() + off + tok * (LDX - D_MODEL)) = (u32x2){pk2(xn[0], xn[1]), pk2(xn[2], xn[3])};
;         ss += xn[0] * xn[0] + xn[1] * xn[1] + xn[2] * xn[2] + xn[3] * xn[3];
	v_lshl_add_u32 v130, v251, 2, v130
	v_add_u32_e32 v161, 0x10000, v130
	v_add_u32_e32 v163, 0x20000, v130
	v_add_u32_e32 v205, 0x30000, v130
	s_movk_i32 s10, 0x880
	v_mul_lo_u32 v200, v248, s10
	v_lshl_add_u32 v200, v251, 1, v200
	v_and_b32_e32 v250, 1, v231
	v_lshlrev_b32_e32 v250, 5, v250
	v_lshrrev_b32_e32 v242, 1, v231
	v_lshl_add_u32 v250, v242, 4, v250
	v_lshlrev_b32_e32 v242, 3, v231
	v_sub_u32_e32 v250, v250, v242
	v_add_u32_e32 v200, v200, v250
	v_add_u32_e32 v201, 0x8800, v200
	v_add_u32_e32 v158, 0x11000, v200
	v_add_u32_e32 v159, 0x19800, v200
	v_lshl_add_u32 v251, v134, 1, v249
	v_lshlrev_b32_e32 v230, 6, v248
	v_lshl_add_u32 v230, v251, 2, v230
	v_xor_b32_e32 v239, 16, v228
	v_xor_b32_e32 v243, 32, v228
	v_lshlrev_b32_e32 v239, 2, v239
	v_lshlrev_b32_e32 v243, 2, v243
	global_load_dwordx4 v[164:167], v130, s[56:57]
	global_load_dwordx4 v[168:171], v130, s[56:57] offset:64
	global_load_dwordx4 v[172:175], v130, s[56:57] offset:128
	global_load_dwordx4 v[176:179], v130, s[56:57] offset:192
	global_load_dwordx4 v[180:183], v130, s[56:57] offset:256
	global_load_dwordx4 v[184:187], v130, s[56:57] offset:320
	global_load_dwordx4 v[188:191], v130, s[56:57] offset:384
	global_load_dwordx4 v[192:195], v130, s[56:57] offset:448
	global_load_dwordx4 v[196:199], v161, s[56:57]
	global_load_dwordx4 v[216:219], v161, s[56:57] offset:64
	global_load_dwordx4 v[220:223], v161, s[56:57] offset:128
	global_load_dwordx4 v[224:227], v161, s[56:57] offset:192
	s_waitcnt vmcnt(11)
	v_pk_add_f32 v[126:127], v[126:127], v[164:165]
	v_pk_add_f32 v[128:129], v[128:129], v[166:167]
	v_mul_f32_e32 v244, v127, v127
	v_fmac_f32_e32 v244, v126, v126
	v_fmac_f32_e32 v244, v128, v128
	v_fmac_f32_e32 v244, v129, v129
	global_load_dwordx4 v[164:167], v161, s[56:57] offset:256
	s_waitcnt vmcnt(11)
	v_pk_add_f32 v[122:123], v[122:123], v[168:169]
	v_pk_add_f32 v[124:125], v[124:125], v[170:171]
	v_mul_f32_e32 v242, v123, v123
	v_fmac_f32_e32 v242, v122, v122
	v_fmac_f32_e32 v242, v124, v124
	v_fmac_f32_e32 v242, v125, v125
	v_add_f32_e32 v244, v244, v242
	global_load_dwordx4 v[168:171], v161, s[56:57] offset:320
	s_waitcnt vmcnt(11)
	v_pk_add_f32 v[118:119], v[118:119], v[172:173]
	v_pk_add_f32 v[120:121], v[120:121], v[174:175]
	v_mul_f32_e32 v242, v119, v119
	v_fmac_f32_e32 v242, v118, v118
	v_fmac_f32_e32 v242, v120, v120
	v_fmac_f32_e32 v242, v121, v121
	v_add_f32_e32 v244, v244, v242
	global_load_dwordx4 v[172:175], v161, s[56:57] offset:384
	s_waitcnt vmcnt(11)
	v_pk_add_f32 v[114:115], v[114:115], v[176:177]
	v_pk_add_f32 v[116:117], v[116:117], v[178:179]
	v_mul_f32_e32 v242, v115, v115
	v_fmac_f32_e32 v242, v114, v114
	v_fmac_f32_e32 v242, v116, v116
	v_fmac_f32_e32 v242, v117, v117
	v_add_f32_e32 v244, v244, v242
	global_load_dwordx4 v[176:179], v161, s[56:57] offset:448
	s_waitcnt vmcnt(11)
	v_pk_add_f32 v[110:111], v[110:111], v[180:181]
	v_pk_add_f32 v[112:113], v[112:113], v[182:183]
	v_mul_f32_e32 v242, v111, v111
	v_fmac_f32_e32 v242, v110, v110
	v_fmac_f32_e32 v242, v112, v112
	v_fmac_f32_e32 v242, v113, v113
	v_add_f32_e32 v244, v244, v242
	global_load_dwordx4 v[180:183], v163, s[56:57]
	s_waitcnt vmcnt(11)
	v_pk_add_f32 v[106:107], v[106:107], v[184:185]
	v_pk_add_f32 v[108:109], v[108:109], v[186:187]
	v_mul_f32_e32 v242, v107, v107
	v_fmac_f32_e32 v242, v106, v106
	v_fmac_f32_e32 v242, v108, v108
	v_fmac_f32_e32 v242, v109, v109
	v_add_f32_e32 v244, v244, v242
	global_load_dwordx4 v[184:187], v163, s[56:57] offset:64
	s_waitcnt vmcnt(11)
	v_pk_add_f32 v[102:103], v[102:103], v[188:189]
	v_pk_add_f32 v[104:105], v[104:105], v[190:191]
	v_mul_f32_e32 v242, v103, v103
	v_fmac_f32_e32 v242, v102, v102
	v_fmac_f32_e32 v242, v104, v104
	v_fmac_f32_e32 v242, v105, v105
	v_add_f32_e32 v244, v244, v242
	global_load_dwordx4 v[188:191], v163, s[56:57] offset:128
	s_waitcnt vmcnt(11)
	v_pk_add_f32 v[94:95], v[94:95], v[192:193]
	v_pk_add_f32 v[96:97], v[96:97], v[194:195]
	v_mul_f32_e32 v242, v95, v95
	v_fmac_f32_e32 v242, v94, v94
	v_fmac_f32_e32 v242, v96, v96
	v_fmac_f32_e32 v242, v97, v97
	v_add_f32_e32 v244, v244, v242
	global_load_dwordx4 v[192:195], v163, s[56:57] offset:192
	s_waitcnt vmcnt(11)
	v_pk_add_f32 v[98:99], v[98:99], v[196:197]
	v_pk_add_f32 v[100:101], v[100:101], v[198:199]
	v_mul_f32_e32 v245, v99, v99
	v_fmac_f32_e32 v245, v98, v98
	v_fmac_f32_e32 v245, v100, v100
	v_fmac_f32_e32 v245, v101, v101
	global_load_dwordx4 v[196:199], v163, s[56:57] offset:256
	s_waitcnt vmcnt(11)
	v_pk_add_f32 v[90:91], v[90:91], v[216:217]
	v_pk_add_f32 v[92:93], v[92:93], v[218:219]
	v_mul_f32_e32 v242, v91, v91
	v_fmac_f32_e32 v242, v90, v90
	v_fmac_f32_e32 v242, v92, v92
	v_fmac_f32_e32 v242, v93, v93
	v_add_f32_e32 v245, v245, v242
	global_load_dwordx4 v[216:219], v163, s[56:57] offset:320
	s_waitcnt vmcnt(11)
	v_pk_add_f32 v[86:87], v[86:87], v[220:221]
	v_pk_add_f32 v[88:89], v[88:89], v[222:223]
	v_mul_f32_e32 v242, v87, v87
	v_fmac_f32_e32 v242, v86, v86
	v_fmac_f32_e32 v242, v88, v88
	v_fmac_f32_e32 v242, v89, v89
	v_add_f32_e32 v245, v245, v242
	global_load_dwordx4 v[220:223], v163, s[56:57] offset:384
	s_waitcnt vmcnt(11)
	v_pk_add_f32 v[82:83], v[82:83], v[224:225]
	v_pk_add_f32 v[84:85], v[84:85], v[226:227]
	v_mul_f32_e32 v242, v83, v83
	v_fmac_f32_e32 v242, v82, v82
	v_fmac_f32_e32 v242, v84, v84
	v_fmac_f32_e32 v242, v85, v85
	v_add_f32_e32 v245, v245, v242
	global_load_dwordx4 v[224:227], v163, s[56:57] offset:448
	s_waitcnt vmcnt(11)
	v_pk_add_f32 v[78:79], v[78:79], v[164:165]
	v_pk_add_f32 v[80:81], v[80:81], v[166:167]
	v_mul_f32_e32 v242, v79, v79
	v_fmac_f32_e32 v242, v78, v78
	v_fmac_f32_e32 v242, v80, v80
	v_fmac_f32_e32 v242, v81, v81
	v_add_f32_e32 v245, v245, v242
	global_load_dwordx4 v[164:167], v205, s[56:57]
	s_waitcnt vmcnt(11)
; DI unsigned pk2(float lo, float hi) { f32x2 v = {lo, hi}; bf16x2_t b = __builtin_convertvector(v, bf16x2_t); return __builtin_bit_cast(unsigned, b); }
; DI void phaseE(const Params& p0, const Slot sl, int layer, unsigned char* lds, const float* xsrc) {
;     ...
;     for (int j = 0; j < 4; ++j) {
;       const long tok = (long)mt * 256 + wb * 64 + j * 16 + qi;
;       float ss = 0.f;
; #pragma unroll
;       for (int i = 0; i < 8; ++i) {
;         const long off = tok * 1024 + nt * 256 + wa * 128 + i * 16 + quad * 4;
;         const f32x4 xo = *(const f32x4*)(xsrc + off);
;         const f32x4 xn = xo + acc[i][j];
;         *(f32x4*)(p.out + off) = xn;
;         *(u32x2*)(p.xb() + off + tok * (LDX - D_MODEL)) = (u32x2){pk2(xn[0], xn[1]), pk2(xn[2], xn[3])};
;         ss += xn[0] * xn[0] + xn[1] * xn[1] + xn[2] * xn[2] + xn[3] * xn[3];
;       }
;       ss += __shfl_xor(ss, 16); ss += __shfl_xor(ss, 32);
;       if (quad == 0) p.part()[tok * 16 + nt * 2 + wa] = ss;
;     }
	v_pk_add_f32 v[74:75], v[74:75], v[168:169]
	v_pk_add_f32 v[76:77], v[76:77], v[170:171]
	v_mul_f32_e32 v242, v75, v75
	v_fmac_f32_e32 v242, v74, v74
	v_fmac_f32_e32 v242, v76, v76
	v_fmac_f32_e32 v242, v77, v77
	v_add_f32_e32 v245, v245, v242
	global_load_dwordx4 v[168:171], v205, s[56:57] offset:64
	s_waitcnt vmcnt(11)
	v_pk_add_f32 v[70:71], v[70:71], v[172:173]
	v_pk_add_f32 v[72:73], v[72:73], v[174:175]
	v_mul_f32_e32 v242, v71, v71
	v_fmac_f32_e32 v242, v70, v70
	v_fmac_f32_e32 v242, v72, v72
	v_fmac_f32_e32 v242, v73, v73
	v_add_f32_e32 v245, v245, v242
	global_load_dwordx4 v[172:175], v205, s[56:57] offset:128
	s_waitcnt vmcnt(11)
	v_pk_add_f32 v[62:63], v[62:63], v[176:177]
	v_pk_add_f32 v[64:65], v[64:65], v[178:179]
	v_mul_f32_e32 v242, v63, v63
	v_fmac_f32_e32 v242, v62, v62
	v_fmac_f32_e32 v242, v64, v64
	v_fmac_f32_e32 v242, v65, v65
	v_add_f32_e32 v245, v245, v242
	global_load_dwordx4 v[176:179], v205, s[56:57] offset:192
	s_waitcnt vmcnt(11)
	v_pk_add_f32 v[66:67], v[66:67], v[180:181]
	v_pk_add_f32 v[68:69], v[68:69], v[182:183]
	v_mul_f32_e32 v246, v67, v67
	v_fmac_f32_e32 v246, v66, v66
	v_fmac_f32_e32 v246, v68, v68
	v_fmac_f32_e32 v246, v69, v69
	global_load_dwordx4 v[180:183], v205, s[56:57] offset:256
	s_waitcnt vmcnt(11)
	v_pk_add_f32 v[58:59], v[58:59], v[184:185]
	v_pk_add_f32 v[60:61], v[60:61], v[186:187]
	v_mul_f32_e32 v242, v59, v59
	v_fmac_f32_e32 v242, v58, v58
	v_fmac_f32_e32 v242, v60, v60
	v_fmac_f32_e32 v242, v61, v61
	v_add_f32_e32 v246, v246, v242
	global_load_dwordx4 v[184:187], v205, s[56:57] offset:320
	s_waitcnt vmcnt(11)
	v_pk_add_f32 v[54:55], v[54:55], v[188:189]
	v_pk_add_f32 v[56:57], v[56:57], v[190:191]
	v_mul_f32_e32 v242, v55, v55
	v_fmac_f32_e32 v242, v54, v54
	v_fmac_f32_e32 v242, v56, v56
	v_fmac_f32_e32 v242, v57, v57
	v_add_f32_e32 v246, v246, v242
	global_load_dwordx4 v[188:191], v205, s[56:57] offset:384
	s_waitcnt vmcnt(11)
	v_pk_add_f32 v[50:51], v[50:51], v[192:193]
	v_pk_add_f32 v[52:53], v[52:53], v[194:195]
	v_mul_f32_e32 v242, v51, v51
	v_fmac_f32_e32 v242, v50, v50
	v_fmac_f32_e32 v242, v52, v52
	v_fmac_f32_e32 v242, v53, v53
	v_add_f32_e32 v246, v246, v242
	global_load_dwordx4 v[192:195], v205, s[56:57] offset:448
	v_cvt_pk_bf16_f32 v248, v126, v127
	v_cvt_pk_bf16_f32 v249, v128, v129
	v_cvt_pk_bf16_f32 v250, v122, v123
	v_cvt_pk_bf16_f32 v251, v124, v125
	global_store_dwordx4 v130, v[126:129], s[90:91]
	global_store_dwordx4 v130, v[122:125], s[90:91] offset:64
	v_permlane16_swap_b32_e32 v248, v250
	v_permlane16_swap_b32_e32 v249, v251
	global_store_dwordx4 v200, v[248:251], s[14:15]
	v_cvt_pk_bf16_f32 v206, v118, v119
	v_cvt_pk_bf16_f32 v207, v120, v121
	v_cvt_pk_bf16_f32 v208, v114, v115
	v_cvt_pk_bf16_f32 v209, v116, v117
	global_store_dwordx4 v130, v[118:121], s[90:91] offset:128
	global_store_dwordx4 v130, v[114:117], s[90:91] offset:192
	v_permlane16_swap_b32_e32 v206, v208
	v_permlane16_swap_b32_e32 v207, v209
	global_store_dwordx4 v200, v[206:209], s[14:15] offset:64
	ds_bpermute_b32 v242, v239, v244
	s_waitcnt lgkmcnt(0)
	v_add_f32_e32 v244, v244, v242
	ds_bpermute_b32 v242, v243, v244
	s_waitcnt lgkmcnt(0)
	v_add_f32_e32 v244, v244, v242
	v_cmp_eq_u32_e32 vcc, 0, v231
	s_nop 0
	s_and_saveexec_b64 s[10:11], vcc
	global_store_dword v230, v244, s[16:17]
	s_mov_b64 exec, s[10:11]
	s_waitcnt vmcnt(18)
	v_pk_add_f32 v[46:47], v[46:47], v[196:197]
	v_pk_add_f32 v[48:49], v[48:49], v[198:199]
	v_mul_f32_e32 v242, v47, v47
	v_fmac_f32_e32 v242, v46, v46
	v_fmac_f32_e32 v242, v48, v48
	v_fmac_f32_e32 v242, v49, v49
	v_add_f32_e32 v246, v246, v242
	s_waitcnt vmcnt(17)
	v_pk_add_f32 v[42:43], v[42:43], v[216:217]
	v_pk_add_f32 v[44:45], v[44:45], v[218:219]
	v_mul_f32_e32 v242, v43, v43
	v_fmac_f32_e32 v242, v42, v42
	v_fmac_f32_e32 v242, v44, v44
	v_fmac_f32_e32 v242, v45, v45
	v_add_f32_e32 v246, v246, v242
	v_cvt_pk_bf16_f32 v248, v110, v111
	v_cvt_pk_bf16_f32 v249, v112, v113
	v_cvt_pk_bf16_f32 v250, v106, v107
	v_cvt_pk_bf16_f32 v251, v108, v109
	global_store_dwordx4 v130, v[110:113], s[90:91] offset:256
	global_store_dwordx4 v130, v[106:109], s[90:91] offset:320
	v_permlane16_swap_b32_e32 v248, v250
	v_permlane16_swap_b32_e32 v249, v251
	global_store_dwordx4 v200, v[248:251], s[14:15] offset:128
	v_cvt_pk_bf16_f32 v206, v102, v103
	v_cvt_pk_bf16_f32 v207, v104, v105
	v_cvt_pk_bf16_f32 v208, v94, v95
	v_cvt_pk_bf16_f32 v209, v96, v97
	global_store_dwordx4 v130, v[102:105], s[90:91] offset:384
	global_store_dwordx4 v130, v[94:97], s[90:91] offset:448
	v_permlane16_swap_b32_e32 v206, v208
	v_permlane16_swap_b32_e32 v207, v209
	global_store_dwordx4 v200, v[206:209], s[14:15] offset:192
	ds_bpermute_b32 v242, v239, v245
	s_waitcnt lgkmcnt(0)
	v_add_f32_e32 v245, v245, v242
	ds_bpermute_b32 v242, v243, v245
	s_waitcnt lgkmcnt(0)
	v_add_f32_e32 v245, v245, v242
	v_cmp_eq_u32_e32 vcc, 0, v231
	s_nop 0
	s_and_saveexec_b64 s[10:11], vcc
	global_store_dword v230, v245, s[16:17] offset:1024
	s_mov_b64 exec, s[10:11]
	s_waitcnt vmcnt(23)
	v_pk_add_f32 v[38:39], v[38:39], v[220:221]
	v_pk_add_f32 v[40:41], v[40:41], v[222:223]
	v_mul_f32_e32 v242, v39, v39
	v_fmac_f32_e32 v242, v38, v38
	v_fmac_f32_e32 v242, v40, v40
	v_fmac_f32_e32 v242, v41, v41
	v_add_f32_e32 v246, v246, v242
	s_waitcnt vmcnt(22)
; DI unsigned pk2(float lo, float hi) { f32x2 v = {lo, hi}; bf16x2_t b = __builtin_convertvector(v, bf16x2_t); return __builtin_bit_cast(unsigned, b); }
; DI void phaseE(const Params& p0, const Slot sl, int layer, unsigned char* lds, const float* xsrc) {
;     ...
;     for (int j = 0; j < 4; ++j) {
;       const long tok = (long)mt * 256 + wb * 64 + j * 16 + qi;
;       float ss = 0.f;
; #pragma unroll
;       for (int i = 0; i < 8; ++i) {
;         const long off = tok * 1024 + nt * 256 + wa * 128 + i * 16 + quad * 4;
;         const f32x4 xo = *(const f32x4*)(xsrc + off);
;         const f32x4 xn = xo + acc[i][j];
;         *(f32x4*)(p.out + off) = xn;
;         *(u32x2*)(p.xb() + off + tok * (LDX - D_MODEL)) = (u32x2){pk2(xn[0], xn[1]), pk2(xn[2], xn[3])};
;         ss += xn[0] * xn[0] + xn[1] * xn[1] + xn[2] * xn[2] + xn[3] * xn[3];
;       }
;       ss += __shfl_xor(ss, 16); ss += __shfl_xor(ss, 32);
;       if (quad == 0) p.part()[tok * 16 + nt * 2 + wa] = ss;
;     }
	v_pk_add_f32 v[26:27], v[26:27], v[224:225]
	v_pk_add_f32 v[28:29], v[28:29], v[226:227]
	v_mul_f32_e32 v242, v27, v27
	v_fmac_f32_e32 v242, v26, v26
	v_fmac_f32_e32 v242, v28, v28
	v_fmac_f32_e32 v242, v29, v29
	v_add_f32_e32 v246, v246, v242
	v_cvt_pk_bf16_f32 v248, v98, v99
	v_cvt_pk_bf16_f32 v249, v100, v101
	v_cvt_pk_bf16_f32 v250, v90, v91
	v_cvt_pk_bf16_f32 v251, v92, v93
	global_store_dwordx4 v161, v[98:101], s[90:91]
	global_store_dwordx4 v161, v[90:93], s[90:91] offset:64
	v_permlane16_swap_b32_e32 v248, v250
	v_permlane16_swap_b32_e32 v249, v251
	global_store_dwordx4 v201, v[248:251], s[14:15]
	v_cvt_pk_bf16_f32 v206, v86, v87
	v_cvt_pk_bf16_f32 v207, v88, v89
	v_cvt_pk_bf16_f32 v208, v82, v83
	v_cvt_pk_bf16_f32 v209, v84, v85
	global_store_dwordx4 v161, v[86:89], s[90:91] offset:128
	global_store_dwordx4 v161, v[82:85], s[90:91] offset:192
	v_permlane16_swap_b32_e32 v206, v208
	v_permlane16_swap_b32_e32 v207, v209
	global_store_dwordx4 v201, v[206:209], s[14:15] offset:64
	ds_bpermute_b32 v242, v239, v246
	s_waitcnt lgkmcnt(0)
	v_add_f32_e32 v246, v246, v242
	ds_bpermute_b32 v242, v243, v246
	s_waitcnt lgkmcnt(0)
	v_add_f32_e32 v246, v246, v242
	v_cmp_eq_u32_e32 vcc, 0, v231
	s_nop 0
	s_and_saveexec_b64 s[10:11], vcc
	global_store_dword v230, v246, s[16:17] offset:2048
	s_mov_b64 exec, s[10:11]
	s_waitcnt vmcnt(28)
	v_pk_add_f32 v[34:35], v[34:35], v[164:165]
	v_pk_add_f32 v[36:37], v[36:37], v[166:167]
	v_mul_f32_e32 v247, v35, v35
	v_fmac_f32_e32 v247, v34, v34
	v_fmac_f32_e32 v247, v36, v36
	v_fmac_f32_e32 v247, v37, v37
	s_waitcnt vmcnt(27)
	v_pk_add_f32 v[30:31], v[30:31], v[168:169]
	v_pk_add_f32 v[32:33], v[32:33], v[170:171]
	v_mul_f32_e32 v242, v31, v31
	v_fmac_f32_e32 v242, v30, v30
	v_fmac_f32_e32 v242, v32, v32
	v_fmac_f32_e32 v242, v33, v33
	v_add_f32_e32 v247, v247, v242
	v_cvt_pk_bf16_f32 v248, v78, v79
	v_cvt_pk_bf16_f32 v249, v80, v81
	v_cvt_pk_bf16_f32 v250, v74, v75
	v_cvt_pk_bf16_f32 v251, v76, v77
	global_store_dwordx4 v161, v[78:81], s[90:91] offset:256
	global_store_dwordx4 v161, v[74:77], s[90:91] offset:320
	v_permlane16_swap_b32_e32 v248, v250
	v_permlane16_swap_b32_e32 v249, v251
	global_store_dwordx4 v201, v[248:251], s[14:15] offset:128
	v_cvt_pk_bf16_f32 v206, v70, v71
	v_cvt_pk_bf16_f32 v207, v72, v73
	v_cvt_pk_bf16_f32 v208, v62, v63
	v_cvt_pk_bf16_f32 v209, v64, v65
	global_store_dwordx4 v161, v[70:73], s[90:91] offset:384
	global_store_dwordx4 v161, v[62:65], s[90:91] offset:448
	v_permlane16_swap_b32_e32 v206, v208
	v_permlane16_swap_b32_e32 v207, v209
	global_store_dwordx4 v201, v[206:209], s[14:15] offset:192
	s_waitcnt vmcnt(32)
	v_pk_add_f32 v[22:23], v[22:23], v[172:173]
	v_pk_add_f32 v[24:25], v[24:25], v[174:175]
	v_mul_f32_e32 v242, v23, v23
	v_fmac_f32_e32 v242, v22, v22
	v_fmac_f32_e32 v242, v24, v24
	v_fmac_f32_e32 v242, v25, v25
	v_add_f32_e32 v247, v247, v242
	s_waitcnt vmcnt(31)
	v_pk_add_f32 v[18:19], v[18:19], v[176:177]
	v_pk_add_f32 v[20:21], v[20:21], v[178:179]
	v_mul_f32_e32 v242, v19, v19
	v_fmac_f32_e32 v242, v18, v18
	v_fmac_f32_e32 v242, v20, v20
	v_fmac_f32_e32 v242, v21, v21
	v_add_f32_e32 v247, v247, v242
	v_cvt_pk_bf16_f32 v248, v66, v67
	v_cvt_pk_bf16_f32 v249, v68, v69
	v_cvt_pk_bf16_f32 v250, v58, v59
	v_cvt_pk_bf16_f32 v251, v60, v61
	global_store_dwordx4 v163, v[66:69], s[90:91]
	global_store_dwordx4 v163, v[58:61], s[90:91] offset:64
	v_permlane16_swap_b32_e32 v248, v250
	v_permlane16_swap_b32_e32 v249, v251
	global_store_dwordx4 v158, v[248:251], s[14:15]
	v_cvt_pk_bf16_f32 v206, v54, v55
	v_cvt_pk_bf16_f32 v207, v56, v57
	v_cvt_pk_bf16_f32 v208, v50, v51
	v_cvt_pk_bf16_f32 v209, v52, v53
	global_store_dwordx4 v163, v[54:57], s[90:91] offset:128
	global_store_dwordx4 v163, v[50:53], s[90:91] offset:192
	v_permlane16_swap_b32_e32 v206, v208
	v_permlane16_swap_b32_e32 v207, v209
	global_store_dwordx4 v158, v[206:209], s[14:15] offset:64
	s_waitcnt vmcnt(36)
; DI unsigned pk2(float lo, float hi) { f32x2 v = {lo, hi}; bf16x2_t b = __builtin_convertvector(v, bf16x2_t); return __builtin_bit_cast(unsigned, b); }
; DI void phaseE(const Params& p0, const Slot sl, int layer, unsigned char* lds, const float* xsrc) {
;     ...
;     for (int j = 0; j < 4; ++j) {
;       const long tok = (long)mt * 256 + wb * 64 + j * 16 + qi;
;       float ss = 0.f;
; #pragma unroll
;       for (int i = 0; i < 8; ++i) {
;         const long off = tok * 1024 + nt * 256 + wa * 128 + i * 16 + quad * 4;
;         const f32x4 xo = *(const f32x4*)(xsrc + off);
;         const f32x4 xn = xo + acc[i][j];
;         *(f32x4*)(p.out + off) = xn;
;         *(u32x2*)(p.xb() + off + tok * (LDX - D_MODEL)) = (u32x2){pk2(xn[0], xn[1]), pk2(xn[2], xn[3])};
;         ss += xn[0] * xn[0] + xn[1] * xn[1] + xn[2] * xn[2] + xn[3] * xn[3];
;       }
;       ss += __shfl_xor(ss, 16); ss += __shfl_xor(ss, 32);
;       if (quad == 0) p.part()[tok * 16 + nt * 2 + wa] = ss;
;     }
	v_pk_add_f32 v[14:15], v[14:15], v[180:181]
	v_pk_add_f32 v[16:17], v[16:17], v[182:183]
	v_mul_f32_e32 v242, v15, v15
	v_fmac_f32_e32 v242, v14, v14
	v_fmac_f32_e32 v242, v16, v16
	v_fmac_f32_e32 v242, v17, v17
	v_add_f32_e32 v247, v247, v242
	s_waitcnt vmcnt(35)
	v_pk_add_f32 v[10:11], v[10:11], v[184:185]
	v_pk_add_f32 v[12:13], v[12:13], v[186:187]
	v_mul_f32_e32 v242, v11, v11
	v_fmac_f32_e32 v242, v10, v10
	v_fmac_f32_e32 v242, v12, v12
	v_fmac_f32_e32 v242, v13, v13
	v_add_f32_e32 v247, v247, v242
	v_cvt_pk_bf16_f32 v248, v46, v47
	v_cvt_pk_bf16_f32 v249, v48, v49
	v_cvt_pk_bf16_f32 v250, v42, v43
	v_cvt_pk_bf16_f32 v251, v44, v45
	global_store_dwordx4 v163, v[46:49], s[90:91] offset:256
	global_store_dwordx4 v163, v[42:45], s[90:91] offset:320
	v_permlane16_swap_b32_e32 v248, v250
	v_permlane16_swap_b32_e32 v249, v251
	global_store_dwordx4 v158, v[248:251], s[14:15] offset:128
	v_cvt_pk_bf16_f32 v206, v38, v39
	v_cvt_pk_bf16_f32 v207, v40, v41
	v_cvt_pk_bf16_f32 v208, v26, v27
	v_cvt_pk_bf16_f32 v209, v28, v29
	global_store_dwordx4 v163, v[38:41], s[90:91] offset:384
	global_store_dwordx4 v163, v[26:29], s[90:91] offset:448
	v_permlane16_swap_b32_e32 v206, v208
	v_permlane16_swap_b32_e32 v207, v209
	global_store_dwordx4 v158, v[206:209], s[14:15] offset:192
	s_waitcnt vmcnt(40)
	v_pk_add_f32 v[6:7], v[6:7], v[188:189]
	v_pk_add_f32 v[8:9], v[8:9], v[190:191]
	v_mul_f32_e32 v242, v7, v7
	v_fmac_f32_e32 v242, v6, v6
	v_fmac_f32_e32 v242, v8, v8
	v_fmac_f32_e32 v242, v9, v9
	v_add_f32_e32 v247, v247, v242
	s_waitcnt vmcnt(39)
	v_pk_add_f32 v[2:3], v[2:3], v[192:193]
	v_pk_add_f32 v[4:5], v[4:5], v[194:195]
	v_mul_f32_e32 v242, v3, v3
	v_fmac_f32_e32 v242, v2, v2
	v_fmac_f32_e32 v242, v4, v4
	v_fmac_f32_e32 v242, v5, v5
	v_add_f32_e32 v247, v247, v242
	v_cvt_pk_bf16_f32 v248, v34, v35
	v_cvt_pk_bf16_f32 v249, v36, v37
	v_cvt_pk_bf16_f32 v250, v30, v31
	v_cvt_pk_bf16_f32 v251, v32, v33
	global_store_dwordx4 v205, v[34:37], s[90:91]
	global_store_dwordx4 v205, v[30:33], s[90:91] offset:64
	v_permlane16_swap_b32_e32 v248, v250
	v_permlane16_swap_b32_e32 v249, v251
	global_store_dwordx4 v159, v[248:251], s[14:15]
	v_cvt_pk_bf16_f32 v206, v22, v23
	v_cvt_pk_bf16_f32 v207, v24, v25
	v_cvt_pk_bf16_f32 v208, v18, v19
	v_cvt_pk_bf16_f32 v209, v20, v21
	global_store_dwordx4 v205, v[22:25], s[90:91] offset:128
	global_store_dwordx4 v205, v[18:21], s[90:91] offset:192
	v_permlane16_swap_b32_e32 v206, v208
	v_permlane16_swap_b32_e32 v207, v209
	global_store_dwordx4 v159, v[206:209], s[14:15] offset:64
	ds_bpermute_b32 v242, v239, v247
	s_waitcnt lgkmcnt(0)
	v_add_f32_e32 v247, v247, v242
	ds_bpermute_b32 v242, v243, v247
	s_waitcnt lgkmcnt(0)
	v_add_f32_e32 v247, v247, v242
	v_cmp_eq_u32_e32 vcc, 0, v231
	s_nop 0
	s_and_saveexec_b64 s[10:11], vcc
	global_store_dword v230, v247, s[16:17] offset:3072
	s_mov_b64 exec, s[10:11]
	v_cvt_pk_bf16_f32 v248, v14, v15
	v_cvt_pk_bf16_f32 v249, v16, v17
	v_cvt_pk_bf16_f32 v250, v10, v11
	v_cvt_pk_bf16_f32 v251, v12, v13
	global_store_dwordx4 v205, v[14:17], s[90:91] offset:256
	global_store_dwordx4 v205, v[10:13], s[90:91] offset:320
	v_permlane16_swap_b32_e32 v248, v250
	v_permlane16_swap_b32_e32 v249, v251
	global_store_dwordx4 v159, v[248:251], s[14:15] offset:128
	v_cvt_pk_bf16_f32 v206, v6, v7
	v_cvt_pk_bf16_f32 v207, v8, v9
	v_cvt_pk_bf16_f32 v208, v2, v3
	v_cvt_pk_bf16_f32 v209, v4, v5
	global_store_dwordx4 v205, v[6:9], s[90:91] offset:384
	global_store_dwordx4 v205, v[2:5], s[90:91] offset:448
	v_permlane16_swap_b32_e32 v206, v208
	v_permlane16_swap_b32_e32 v207, v209
	global_store_dwordx4 v159, v[206:209], s[14:15] offset:192
	s_mov_b64 s[8:9], exec
	s_branch .LBB0_983
